# k16: k15 + per-phase s_setprio flips removed from the GEMM MMA phases
# speedup vs baseline: 1.0113x; 1.0025x over previous
; #define PG8_STAGE(bufoff, gbase, voff) do { _Pragma("unroll") for (int _i = 0; _i < 2; ++_i) \
;         __builtin_amdgcn_global_load_lds((const unsigned*)((const char*)(gbase) + (voff)[_i]), (LAS unsigned*)(lds + (bufoff) + ldsw + _i * 8192), 16, 0, 0); } while (0)
; #define PG8_LDA(dst, b, h) do { _Pragma("unroll") for (int m = 0; m < 4; ++m) _Pragma("unroll") for (int k = 0; k < 2; ++k) dst[m][k] = *(const LAS bf16x8*)(lds + PG8_SA(b, h) + aoff + m * 2048 + k * 1024); } while (0)
; #define PG8_LDB(dst, b, h) do { _Pragma("unroll") for (int n = 0; n < 2; ++n) _Pragma("unroll") for (int k = 0; k < 2; ++k) dst[n][k] = *(const LAS bf16x8*)(lds + PG8_SB(b, h) + boff + n * 2048 + k * 1024); } while (0)
; #define PG8_MMA(ai, bj, At, Bt) do { __builtin_amdgcn_s_setprio(1); _Pragma("unroll") for (int m = 0; m < 4; ++m) _Pragma("unroll") for (int n = 0; n < 2; ++n) _Pragma("unroll") for (int k = 0; k < 2; ++k) \
;         acc[ai][bj][m][n] = __builtin_amdgcn_mfma_f32_16x16x32_bf16(Bt[n][k], At[m][k], acc[ai][bj][m][n], 0, 0, 0); __builtin_amdgcn_s_setprio(0); } while (0)
; template <class Epi>
; __device__ __forceinline__ void gemm_phase(LAS unsigned char* lds, const Gemm g, const Epi& E) {
;     ...
;     for (;;) {
;         const bool has_next = S.next(ui + 1, nxt);
;         const char* nA = has_next ? (const char*)g.A + (size_t)g.mapA.src(nxt.pm) * tstepA + (size_t)nxt.pn * g.a_pn_step : cA;
;         const char* nB = has_next ? (const char*)g.Bt + (size_t)g.mapB.src(nxt.pn) * tstepB : cB;
;         for (int t = 0; t < nt; t += 2) {
;             const bool last = (t == nt - 2);
;             const char* a1 = cA + (size_t)(t + 1) * kstep;
;             const char* a2 = last ? nA : cA + (size_t)(t + 2) * kstep; const char* b2 = last ? nB : cB + (size_t)(t + 2) * kstep;
;             const char* a3 = a2 + kstep; const char* b3 = b2 + kstep;
;             PG8_LDB(B0, 0, 0); PG8_SCHED; PG8_LDA(At, 0, 0); PG8_STAGE(PG8_SA(1, 1), a1 + hstepA, voffA);
;             PG8_WAIT_L(8); PG8_BAR; PG8_WAIT_L(0); PG8_MMA(0, 0, At, B0); PG8_BAR; PG8_SCHED;
;             PG8_LDB(B1, 0, 1); PG8_STAGE(PG8_SB(0, 0), b2, voffB);
;             PG8_BAR; PG8_WAIT_L(0); PG8_MMA(0, 1, At, B1); PG8_BAR;
;             PG8_LDA(At, 0, 1); PG8_STAGE(PG8_SA(0, 0), a2, voffA);
;             PG8_BAR; PG8_WAIT_L(0); PG8_MMA(1, 0, At, B0); PG8_BAR; PG8_SCHED;
.LBB0_296:
	s_add_u32 s9, s16, s5
	s_addc_u32 s18, s17, 0
	s_add_u32 s36, s9, 0x100
	s_addc_u32 s60, s18, 0
	s_and_b64 s[0:1], s[58:59], exec
	s_cselect_b32 s67, s11, s60
	s_cselect_b32 s66, s10, s36
	s_add_u32 s0, s14, s5
	s_addc_u32 s1, s15, 0
	s_add_u32 s5, s0, 0x100
	s_addc_u32 s36, s1, 0
	s_add_i32 s73, 0, 0x10000
	s_and_b64 s[0:1], s[58:59], exec
	s_cselect_b32 s75, s13, s36
	s_cselect_b32 s74, s12, s5
	s_add_u32 s78, s9, 0x40080
	s_addc_u32 s79, s18, 0
	s_add_i32 s72, s73, s30
	s_add_i32 m0, s26, 0xc000
	s_add_i32 s50, s26, 0xe000
	s_add_i32 s27, 0, 0x14000
	s_add_i32 s24, s72, 0x2000
	s_add_u32 s64, s74, 0x10000
	v_add_u32_e32 v142, s73, v159
	s_addc_u32 s65, s75, 0
	s_add_i32 s18, s27, s30
	ds_read_b128 v[130:133], v142
	ds_read_b128 v[134:137], v142 offset:1024
	ds_read_b128 v[138:141], v142 offset:2048
	ds_read_b128 v[142:145], v142 offset:3072
	s_add_i32 s36, s18, 0x2000
	s_add_i32 vcc_hi, 0, 0x18000
	s_add_u32 s60, s66, 0x40000
	s_addc_u32 s61, s67, 0
	s_add_i32 vcc_lo, vcc_hi, s30
	s_add_i32 s9, 0, 0x1c000
	s_add_i32 s5, vcc_lo, 0x2000
	s_add_u32 s58, s74, 0x10080
	s_addc_u32 s59, s75, 0
	s_add_i32 s0, s9, s30
	s_add_i32 s1, s0, 0x2000
	v_lshl_add_u64 v[192:193], s[78:79], 0, v[152:153]
	ds_read_b128 v[154:157], v160
	ds_read_b128 v[162:165], v160 offset:1024
	ds_read_b128 v[166:169], v160 offset:2048
	ds_read_b128 v[170:173], v160 offset:3072
	ds_read_b128 v[174:177], v160 offset:4096
	ds_read_b128 v[180:183], v160 offset:5120
	ds_read_b128 v[184:187], v160 offset:6144
	ds_read_b128 v[188:191], v160 offset:7168
	global_load_lds_dwordx4 v[192:193], off
	v_lshl_add_u64 v[192:193], s[78:79], 0, v[148:149]
	s_mov_b32 m0, s50
	s_nop 0
	global_load_lds_dwordx4 v[192:193], off
	s_waitcnt lgkmcnt(8)
	s_barrier
	s_waitcnt lgkmcnt(0)
	v_mfma_f32_16x16x32_bf16 v[126:129], v[130:133], v[154:157], v[126:129]
	v_mfma_f32_16x16x32_bf16 v[122:125], v[138:141], v[154:157], v[122:125]
	v_mfma_f32_16x16x32_bf16 v[114:117], v[130:133], v[166:169], v[114:117]
	v_mfma_f32_16x16x32_bf16 v[110:113], v[138:141], v[166:169], v[110:113]
	v_mfma_f32_16x16x32_bf16 v[102:105], v[130:133], v[174:177], v[102:105]
	v_mfma_f32_16x16x32_bf16 v[94:97], v[138:141], v[174:177], v[94:97]
	v_mfma_f32_16x16x32_bf16 v[86:89], v[130:133], v[184:187], v[86:89]
	v_mfma_f32_16x16x32_bf16 v[78:81], v[138:141], v[184:187], v[78:81]
	v_mfma_f32_16x16x32_bf16 v[126:129], v[134:137], v[162:165], v[126:129]
	v_mfma_f32_16x16x32_bf16 v[122:125], v[142:145], v[162:165], v[122:125]
	v_mfma_f32_16x16x32_bf16 v[114:117], v[134:137], v[170:173], v[114:117]
	v_mfma_f32_16x16x32_bf16 v[110:113], v[142:145], v[170:173], v[110:113]
	v_mfma_f32_16x16x32_bf16 v[102:105], v[134:137], v[180:183], v[102:105]
	v_mfma_f32_16x16x32_bf16 v[94:97], v[142:145], v[180:183], v[94:97]
	v_mfma_f32_16x16x32_bf16 v[86:89], v[134:137], v[188:191], v[86:89]
	v_mfma_f32_16x16x32_bf16 v[78:81], v[142:145], v[188:191], v[78:81]
	s_barrier
	s_mov_b32 m0, s72
	v_add_u32_e32 v161, s27, v159
	v_lshl_add_u64 v[208:209], s[74:75], 0, v[150:151]
	ds_read_b128 v[192:195], v161
	ds_read_b128 v[196:199], v161 offset:1024
	ds_read_b128 v[200:203], v161 offset:2048
	ds_read_b128 v[204:207], v161 offset:3072
	global_load_lds_dwordx4 v[208:209], off
	v_lshl_add_u64 v[226:227], s[74:75], 0, v[146:147]
	s_mov_b32 m0, s24
	s_nop 0
	global_load_lds_dwordx4 v[226:227], off
	s_barrier
	s_waitcnt lgkmcnt(0)
	v_mfma_f32_16x16x32_bf16 v[118:121], v[192:195], v[154:157], v[118:121]
	v_mfma_f32_16x16x32_bf16 v[106:109], v[200:203], v[154:157], v[106:109]
	v_mfma_f32_16x16x32_bf16 v[98:101], v[192:195], v[166:169], v[98:101]
	v_mfma_f32_16x16x32_bf16 v[90:93], v[200:203], v[166:169], v[90:93]
	v_mfma_f32_16x16x32_bf16 v[82:85], v[192:195], v[174:177], v[82:85]
	v_mfma_f32_16x16x32_bf16 v[74:77], v[200:203], v[174:177], v[74:77]
	v_mfma_f32_16x16x32_bf16 v[70:73], v[192:195], v[184:187], v[70:73]
	v_mfma_f32_16x16x32_bf16 v[66:69], v[200:203], v[184:187], v[66:69]
	v_mfma_f32_16x16x32_bf16 v[118:121], v[196:199], v[162:165], v[118:121]
	v_mfma_f32_16x16x32_bf16 v[106:109], v[204:207], v[162:165], v[106:109]
	v_mfma_f32_16x16x32_bf16 v[98:101], v[196:199], v[170:173], v[98:101]
	v_mfma_f32_16x16x32_bf16 v[90:93], v[204:207], v[170:173], v[90:93]
	v_mfma_f32_16x16x32_bf16 v[82:85], v[196:199], v[180:183], v[82:85]
	v_mfma_f32_16x16x32_bf16 v[74:77], v[204:207], v[180:183], v[74:77]
	v_mfma_f32_16x16x32_bf16 v[70:73], v[196:199], v[188:191], v[70:73]
	v_mfma_f32_16x16x32_bf16 v[66:69], v[204:207], v[188:191], v[66:69]
	s_mov_b32 m0, s26
	v_lshl_add_u64 v[228:229], s[66:67], 0, v[152:153]
	s_barrier
	ds_read_b128 v[154:157], v160 offset:16384
	ds_read_b128 v[162:165], v160 offset:17408
	ds_read_b128 v[166:169], v160 offset:18432
	ds_read_b128 v[170:173], v160 offset:19456
	ds_read_b128 v[174:177], v160 offset:20480
	ds_read_b128 v[180:183], v160 offset:21504
	ds_read_b128 v[184:187], v160 offset:22528
	ds_read_b128 v[188:191], v160 offset:23552
	global_load_lds_dwordx4 v[228:229], off
	v_lshl_add_u64 v[230:231], s[66:67], 0, v[148:149]
	s_mov_b32 m0, s52
	s_nop 0
	global_load_lds_dwordx4 v[230:231], off
	s_barrier
; #define PG8_STAGE(bufoff, gbase, voff) do { _Pragma("unroll") for (int _i = 0; _i < 2; ++_i) \
;         __builtin_amdgcn_global_load_lds((const unsigned*)((const char*)(gbase) + (voff)[_i]), (LAS unsigned*)(lds + (bufoff) + ldsw + _i * 8192), 16, 0, 0); } while (0)
; #define PG8_LDA(dst, b, h) do { _Pragma("unroll") for (int m = 0; m < 4; ++m) _Pragma("unroll") for (int k = 0; k < 2; ++k) dst[m][k] = *(const LAS bf16x8*)(lds + PG8_SA(b, h) + aoff + m * 2048 + k * 1024); } while (0)
; #define PG8_LDB(dst, b, h) do { _Pragma("unroll") for (int n = 0; n < 2; ++n) _Pragma("unroll") for (int k = 0; k < 2; ++k) dst[n][k] = *(const LAS bf16x8*)(lds + PG8_SB(b, h) + boff + n * 2048 + k * 1024); } while (0)
; #define PG8_MMA(ai, bj, At, Bt) do { __builtin_amdgcn_s_setprio(1); _Pragma("unroll") for (int m = 0; m < 4; ++m) _Pragma("unroll") for (int n = 0; n < 2; ++n) _Pragma("unroll") for (int k = 0; k < 2; ++k) \
;         acc[ai][bj][m][n] = __builtin_amdgcn_mfma_f32_16x16x32_bf16(Bt[n][k], At[m][k], acc[ai][bj][m][n], 0, 0, 0); __builtin_amdgcn_s_setprio(0); } while (0)
; #define PG8_WAIT_V(n) asm volatile("s_waitcnt vmcnt(" #n ")" ::: "memory")
; #define PG8_WAIT_L(n) asm volatile("s_waitcnt lgkmcnt(" #n ")" ::: "memory")
; #define PG8_BAR __builtin_amdgcn_s_barrier()
; #define PG8_SCHED __builtin_amdgcn_sched_barrier(0)
; template <class Epi>
; __device__ __forceinline__ void gemm_phase(LAS unsigned char* lds, const Gemm g, const Epi& E) {
;     ...
;             PG8_BAR; PG8_WAIT_L(0); PG8_MMA(1, 0, At, B0); PG8_BAR; PG8_SCHED;
;             PG8_STAGE(PG8_SB(0, 1), b2 + hstepB, voffB);
;             PG8_WAIT_V(6); PG8_BAR; PG8_MMA(1, 1, At, B1); PG8_BAR;
;             PG8_LDB(B0, 1, 0); PG8_SCHED; PG8_LDA(At, 1, 0); PG8_STAGE(PG8_SA(0, 1), a2 + hstepA, voffA);
;             PG8_WAIT_L(8); PG8_BAR; PG8_WAIT_L(0); PG8_MMA(0, 0, At, B0); PG8_BAR; PG8_SCHED;
;             PG8_LDB(B1, 1, 1); PG8_STAGE(PG8_SB(1, 0), b3, voffB);
;             PG8_BAR; PG8_WAIT_L(0); PG8_MMA(0, 1, At, B1); PG8_BAR;
	s_waitcnt lgkmcnt(0)
	v_mfma_f32_16x16x32_bf16 v[62:65], v[130:133], v[154:157], v[62:65]
	v_mfma_f32_16x16x32_bf16 v[58:61], v[138:141], v[154:157], v[58:61]
	v_mfma_f32_16x16x32_bf16 v[54:57], v[130:133], v[166:169], v[54:57]
	v_mfma_f32_16x16x32_bf16 v[46:49], v[138:141], v[166:169], v[46:49]
	v_mfma_f32_16x16x32_bf16 v[38:41], v[130:133], v[174:177], v[38:41]
	v_mfma_f32_16x16x32_bf16 v[30:33], v[138:141], v[174:177], v[30:33]
	v_mfma_f32_16x16x32_bf16 v[22:25], v[130:133], v[184:187], v[22:25]
	v_mfma_f32_16x16x32_bf16 v[14:17], v[138:141], v[184:187], v[14:17]
	v_mfma_f32_16x16x32_bf16 v[62:65], v[134:137], v[162:165], v[62:65]
	v_mfma_f32_16x16x32_bf16 v[58:61], v[142:145], v[162:165], v[58:61]
	v_mfma_f32_16x16x32_bf16 v[54:57], v[134:137], v[170:173], v[54:57]
	v_mfma_f32_16x16x32_bf16 v[46:49], v[142:145], v[170:173], v[46:49]
	v_mfma_f32_16x16x32_bf16 v[38:41], v[134:137], v[180:183], v[38:41]
	v_mfma_f32_16x16x32_bf16 v[30:33], v[142:145], v[180:183], v[30:33]
	v_mfma_f32_16x16x32_bf16 v[22:25], v[134:137], v[188:191], v[22:25]
	v_mfma_f32_16x16x32_bf16 v[14:17], v[142:145], v[188:191], v[14:17]
	s_barrier
	s_mov_b32 m0, s18
	v_lshl_add_u64 v[130:131], s[64:65], 0, v[150:151]
	global_load_lds_dwordx4 v[130:131], off
	v_lshl_add_u64 v[130:131], s[64:65], 0, v[146:147]
	s_mov_b32 m0, s36
	s_nop 0
	global_load_lds_dwordx4 v[130:131], off
	s_waitcnt vmcnt(6)
	s_barrier
	v_mfma_f32_16x16x32_bf16 v[50:53], v[192:195], v[154:157], v[50:53]
	v_mfma_f32_16x16x32_bf16 v[42:45], v[200:203], v[154:157], v[42:45]
	v_mfma_f32_16x16x32_bf16 v[34:37], v[192:195], v[166:169], v[34:37]
	v_mfma_f32_16x16x32_bf16 v[26:29], v[200:203], v[166:169], v[26:29]
	v_mfma_f32_16x16x32_bf16 v[18:21], v[192:195], v[174:177], v[18:21]
	v_mfma_f32_16x16x32_bf16 v[10:13], v[200:203], v[174:177], v[10:13]
	v_mfma_f32_16x16x32_bf16 v[6:9], v[192:195], v[184:187], v[6:9]
	v_mfma_f32_16x16x32_bf16 v[2:5], v[200:203], v[184:187], v[2:5]
	v_mfma_f32_16x16x32_bf16 v[50:53], v[196:199], v[162:165], v[50:53]
	v_mfma_f32_16x16x32_bf16 v[42:45], v[204:207], v[162:165], v[42:45]
	v_mfma_f32_16x16x32_bf16 v[34:37], v[196:199], v[170:173], v[34:37]
	v_mfma_f32_16x16x32_bf16 v[26:29], v[204:207], v[170:173], v[26:29]
	v_mfma_f32_16x16x32_bf16 v[18:21], v[196:199], v[180:183], v[18:21]
	v_mfma_f32_16x16x32_bf16 v[10:13], v[204:207], v[180:183], v[10:13]
	v_mfma_f32_16x16x32_bf16 v[6:9], v[196:199], v[188:191], v[6:9]
	v_mfma_f32_16x16x32_bf16 v[2:5], v[204:207], v[188:191], v[2:5]
	v_add_u32_e32 v142, vcc_hi, v159
	s_barrier
	ds_read_b128 v[130:133], v142
	ds_read_b128 v[134:137], v142 offset:1024
	ds_read_b128 v[138:141], v142 offset:2048
	ds_read_b128 v[142:145], v142 offset:3072
	s_mov_b32 m0, s53
	v_lshl_add_u64 v[192:193], s[60:61], 0, v[152:153]
	ds_read_b128 v[154:157], v160 offset:32768
	ds_read_b128 v[162:165], v160 offset:33792
	ds_read_b128 v[166:169], v160 offset:34816
	ds_read_b128 v[170:173], v160 offset:35840
	ds_read_b128 v[174:177], v160 offset:36864
	ds_read_b128 v[180:183], v160 offset:37888
	ds_read_b128 v[184:187], v160 offset:38912
	ds_read_b128 v[188:191], v160 offset:39936
	global_load_lds_dwordx4 v[192:193], off
	v_lshl_add_u64 v[192:193], s[60:61], 0, v[148:149]
	s_mov_b32 m0, s68
	s_nop 0
	global_load_lds_dwordx4 v[192:193], off
	s_waitcnt lgkmcnt(8)
	s_barrier
	s_waitcnt lgkmcnt(0)
	v_mfma_f32_16x16x32_bf16 v[126:129], v[130:133], v[154:157], v[126:129]
	v_mfma_f32_16x16x32_bf16 v[122:125], v[138:141], v[154:157], v[122:125]
	v_mfma_f32_16x16x32_bf16 v[114:117], v[130:133], v[166:169], v[114:117]
	v_mfma_f32_16x16x32_bf16 v[110:113], v[138:141], v[166:169], v[110:113]
	v_mfma_f32_16x16x32_bf16 v[102:105], v[130:133], v[174:177], v[102:105]
	v_mfma_f32_16x16x32_bf16 v[94:97], v[138:141], v[174:177], v[94:97]
	v_mfma_f32_16x16x32_bf16 v[86:89], v[130:133], v[184:187], v[86:89]
	v_mfma_f32_16x16x32_bf16 v[78:81], v[138:141], v[184:187], v[78:81]
	v_mfma_f32_16x16x32_bf16 v[126:129], v[134:137], v[162:165], v[126:129]
	v_mfma_f32_16x16x32_bf16 v[122:125], v[142:145], v[162:165], v[122:125]
	v_mfma_f32_16x16x32_bf16 v[114:117], v[134:137], v[170:173], v[114:117]
	v_mfma_f32_16x16x32_bf16 v[110:113], v[142:145], v[170:173], v[110:113]
	v_mfma_f32_16x16x32_bf16 v[102:105], v[134:137], v[180:183], v[102:105]
	v_mfma_f32_16x16x32_bf16 v[94:97], v[142:145], v[180:183], v[94:97]
	v_mfma_f32_16x16x32_bf16 v[86:89], v[134:137], v[188:191], v[86:89]
	v_mfma_f32_16x16x32_bf16 v[78:81], v[142:145], v[188:191], v[78:81]
	s_barrier
	s_mov_b32 m0, vcc_lo
	v_add_u32_e32 v161, s9, v159
	v_lshl_add_u64 v[208:209], v[208:209], 0, s[86:87]
	ds_read_b128 v[192:195], v161
	ds_read_b128 v[196:199], v161 offset:1024
	ds_read_b128 v[200:203], v161 offset:2048
	ds_read_b128 v[204:207], v161 offset:3072
	global_load_lds_dwordx4 v[208:209], off
	v_lshl_add_u64 v[208:209], v[226:227], 0, s[86:87]
	s_mov_b32 m0, s5
	s_nop 0
	global_load_lds_dwordx4 v[208:209], off
	s_barrier
; #define PG8_STAGE(bufoff, gbase, voff) do { _Pragma("unroll") for (int _i = 0; _i < 2; ++_i) \
;         __builtin_amdgcn_global_load_lds((const unsigned*)((const char*)(gbase) + (voff)[_i]), (LAS unsigned*)(lds + (bufoff) + ldsw + _i * 8192), 16, 0, 0); } while (0)
; #define PG8_LDA(dst, b, h) do { _Pragma("unroll") for (int m = 0; m < 4; ++m) _Pragma("unroll") for (int k = 0; k < 2; ++k) dst[m][k] = *(const LAS bf16x8*)(lds + PG8_SA(b, h) + aoff + m * 2048 + k * 1024); } while (0)
; #define PG8_MMA(ai, bj, At, Bt) do { __builtin_amdgcn_s_setprio(1); _Pragma("unroll") for (int m = 0; m < 4; ++m) _Pragma("unroll") for (int n = 0; n < 2; ++n) _Pragma("unroll") for (int k = 0; k < 2; ++k) \
;         acc[ai][bj][m][n] = __builtin_amdgcn_mfma_f32_16x16x32_bf16(Bt[n][k], At[m][k], acc[ai][bj][m][n], 0, 0, 0); __builtin_amdgcn_s_setprio(0); } while (0)
; #define PG8_WAIT_V(n) asm volatile("s_waitcnt vmcnt(" #n ")" ::: "memory")
; #define PG8_WAIT_L(n) asm volatile("s_waitcnt lgkmcnt(" #n ")" ::: "memory")
; #define PG8_BAR __builtin_amdgcn_s_barrier()
; #define PG8_SCHED __builtin_amdgcn_sched_barrier(0)
; template <class Epi>
; __device__ __forceinline__ void gemm_phase(LAS unsigned char* lds, const Gemm g, const Epi& E) {
;     ...
;             PG8_BAR; PG8_WAIT_L(0); PG8_MMA(0, 1, At, B1); PG8_BAR;
;             PG8_LDA(At, 1, 1); PG8_STAGE(PG8_SA(1, 0), a3, voffA);
;             PG8_BAR; PG8_WAIT_L(0); PG8_MMA(1, 0, At, B0); PG8_BAR; PG8_SCHED;
;             PG8_STAGE(PG8_SB(1, 1), b3 + hstepB, voffB);
;             PG8_WAIT_V(6); PG8_BAR; PG8_MMA(1, 1, At, B1); PG8_BAR;
;         }
;     __device__ __forceinline__ void operator()(const AccT& acc, const Unit& u, int wr, int wc, int fr, int fq) const {
;     ...
;         const int gpm = mapA.src(u.pm);
;         const int mb = gpm < 32 ? 32 : (gpm - 32) >> 3;
;         const int row0 = gpm * 256 + wr * 64 + fr, col0 = u.pn * 256 + wc * 32 + 4 * fq;
;         const float* gp = modl + ((size_t)mb * 6 + gi) * 1024;
;         f32x4 gv[2][2];
; #pragma unroll
;         for (int bj = 0; bj < 2; ++bj)
; #pragma unroll
;             for (int n = 0; n < 2; ++n) { gv[bj][n] = *(const f32x4*)(gp + col0 + bj * 128 + n * 16); if (scale) gv[bj][n] = gv[bj][n] * *(const f32x4*)(scale + col0 + bj * 128 + n * 16); }
	s_waitcnt lgkmcnt(0)
	v_mfma_f32_16x16x32_bf16 v[118:121], v[192:195], v[154:157], v[118:121]
	v_mfma_f32_16x16x32_bf16 v[106:109], v[200:203], v[154:157], v[106:109]
	v_mfma_f32_16x16x32_bf16 v[98:101], v[192:195], v[166:169], v[98:101]
	v_mfma_f32_16x16x32_bf16 v[90:93], v[200:203], v[166:169], v[90:93]
	v_mfma_f32_16x16x32_bf16 v[82:85], v[192:195], v[174:177], v[82:85]
	v_mfma_f32_16x16x32_bf16 v[74:77], v[200:203], v[174:177], v[74:77]
	v_mfma_f32_16x16x32_bf16 v[70:73], v[192:195], v[184:187], v[70:73]
	v_mfma_f32_16x16x32_bf16 v[66:69], v[200:203], v[184:187], v[66:69]
	v_mfma_f32_16x16x32_bf16 v[118:121], v[196:199], v[162:165], v[118:121]
	v_mfma_f32_16x16x32_bf16 v[106:109], v[204:207], v[162:165], v[106:109]
	v_mfma_f32_16x16x32_bf16 v[98:101], v[196:199], v[170:173], v[98:101]
	v_mfma_f32_16x16x32_bf16 v[90:93], v[204:207], v[170:173], v[90:93]
	v_mfma_f32_16x16x32_bf16 v[82:85], v[196:199], v[180:183], v[82:85]
	v_mfma_f32_16x16x32_bf16 v[74:77], v[204:207], v[180:183], v[74:77]
	v_mfma_f32_16x16x32_bf16 v[70:73], v[196:199], v[188:191], v[70:73]
	v_mfma_f32_16x16x32_bf16 v[66:69], v[204:207], v[188:191], v[66:69]
	s_mov_b32 m0, s71
	v_lshl_add_u64 v[208:209], v[228:229], 0, s[86:87]
	s_barrier
	ds_read_b128 v[154:157], v160 offset:49152
	ds_read_b128 v[162:165], v160 offset:50176
	ds_read_b128 v[166:169], v160 offset:51200
	ds_read_b128 v[170:173], v160 offset:52224
	ds_read_b128 v[174:177], v160 offset:53248
	ds_read_b128 v[180:183], v160 offset:54272
	ds_read_b128 v[184:187], v160 offset:55296
	ds_read_b128 v[188:191], v160 offset:56320
	global_load_lds_dwordx4 v[208:209], off
	v_lshl_add_u64 v[208:209], v[230:231], 0, s[86:87]
	s_mov_b32 m0, s80
	s_nop 0
	global_load_lds_dwordx4 v[208:209], off
	s_barrier
	s_waitcnt lgkmcnt(0)
	v_mfma_f32_16x16x32_bf16 v[62:65], v[130:133], v[154:157], v[62:65]
	v_mfma_f32_16x16x32_bf16 v[58:61], v[138:141], v[154:157], v[58:61]
	v_mfma_f32_16x16x32_bf16 v[54:57], v[130:133], v[166:169], v[54:57]
	v_mfma_f32_16x16x32_bf16 v[46:49], v[138:141], v[166:169], v[46:49]
	v_mfma_f32_16x16x32_bf16 v[38:41], v[130:133], v[174:177], v[38:41]
	v_mfma_f32_16x16x32_bf16 v[30:33], v[138:141], v[174:177], v[30:33]
	v_mfma_f32_16x16x32_bf16 v[22:25], v[130:133], v[184:187], v[22:25]
	v_mfma_f32_16x16x32_bf16 v[14:17], v[138:141], v[184:187], v[14:17]
	v_mfma_f32_16x16x32_bf16 v[62:65], v[134:137], v[162:165], v[62:65]
	v_mfma_f32_16x16x32_bf16 v[58:61], v[142:145], v[162:165], v[58:61]
	v_mfma_f32_16x16x32_bf16 v[54:57], v[134:137], v[170:173], v[54:57]
	v_mfma_f32_16x16x32_bf16 v[46:49], v[142:145], v[170:173], v[46:49]
	v_mfma_f32_16x16x32_bf16 v[38:41], v[134:137], v[180:183], v[38:41]
	v_mfma_f32_16x16x32_bf16 v[30:33], v[142:145], v[180:183], v[30:33]
	v_mfma_f32_16x16x32_bf16 v[22:25], v[134:137], v[188:191], v[22:25]
	v_mfma_f32_16x16x32_bf16 v[14:17], v[142:145], v[188:191], v[14:17]
	s_barrier
	s_mov_b32 m0, s0
	v_lshl_add_u64 v[130:131], s[58:59], 0, v[150:151]
	global_load_lds_dwordx4 v[130:131], off
	v_lshl_add_u64 v[130:131], s[58:59], 0, v[146:147]
	s_mov_b32 m0, s1
	s_nop 0
	global_load_lds_dwordx4 v[130:131], off
	s_waitcnt vmcnt(6)
	s_barrier
	v_mfma_f32_16x16x32_bf16 v[50:53], v[192:195], v[154:157], v[50:53]
	v_mfma_f32_16x16x32_bf16 v[42:45], v[200:203], v[154:157], v[42:45]
	v_mfma_f32_16x16x32_bf16 v[34:37], v[192:195], v[166:169], v[34:37]
	v_mfma_f32_16x16x32_bf16 v[26:29], v[200:203], v[166:169], v[26:29]
	v_mfma_f32_16x16x32_bf16 v[18:21], v[192:195], v[174:177], v[18:21]
	v_mfma_f32_16x16x32_bf16 v[10:13], v[200:203], v[174:177], v[10:13]
	v_mfma_f32_16x16x32_bf16 v[6:9], v[192:195], v[184:187], v[6:9]
	v_mfma_f32_16x16x32_bf16 v[2:5], v[200:203], v[184:187], v[2:5]
	v_mfma_f32_16x16x32_bf16 v[50:53], v[196:199], v[162:165], v[50:53]
	v_mfma_f32_16x16x32_bf16 v[42:45], v[204:207], v[162:165], v[42:45]
	v_mfma_f32_16x16x32_bf16 v[34:37], v[196:199], v[170:173], v[34:37]
	v_mfma_f32_16x16x32_bf16 v[26:29], v[204:207], v[170:173], v[26:29]
	v_mfma_f32_16x16x32_bf16 v[18:21], v[196:199], v[180:183], v[18:21]
	v_mfma_f32_16x16x32_bf16 v[10:13], v[204:207], v[180:183], v[10:13]
	v_mfma_f32_16x16x32_bf16 v[6:9], v[196:199], v[188:191], v[6:9]
	v_mfma_f32_16x16x32_bf16 v[2:5], v[204:207], v[188:191], v[2:5]
	s_movk_i32 s5, 0x100
	s_andn2_b64 vcc, exec, s[28:29]
	s_mov_b64 s[58:59], -1
	s_mov_b64 s[28:29], 0
	s_barrier
	s_cbranch_vccz .LBB0_296
	s_cmp_ge_i32 s93, s31
	s_cselect_b32 s0, s44, 0
	s_add_i32 s0, s93, s0
	s_sub_i32 s1, s0, 32
	s_lshl_b32 s4, s4, 8
	s_ashr_i32 s1, s1, 3
	s_or_b32 s4, s4, s70
	v_mov_b32_e32 v130, v1
	v_mov_b32_e32 v161, v158
	s_mul_i32 s1, s1, 6
	s_cmp_gt_i32 s0, 31
	v_readlane_b32 s14, v255, 14
	v_lshl_add_u32 v154, v130, 2, s4
	s_cselect_b32 s4, s1, 0xc0
	s_ashr_i32 s5, s4, 31
	s_lshl_b64 s[4:5], s[4:5], 12
	v_readlane_b32 s15, v255, 15
	s_add_u32 s4, s14, s4
	v_ashrrev_i32_e32 v155, 31, v154
	s_addc_u32 s5, s15, s5
	v_lshlrev_b64 v[136:137], 2, v[154:155]
	v_lshl_add_u64 v[134:135], s[4:5], 0, v[136:137]
	v_add_co_u32_e32 v130, vcc, 0x2000, v134
	v_readlane_b32 s14, v254, 30
	s_nop 0
	v_addc_co_u32_e32 v131, vcc, 0, v135, vcc
	global_load_dwordx4 v[130:133], v[130:131], off
	v_readlane_b32 s15, v254, 31
	s_andn2_b64 vcc, exec, s[14:15]
	v_lshl_add_u64 v[156:157], s[6:7], 0, v[136:137]
	v_cndmask_b32_e64 v138, 0, 1, s[14:15]
	v_cmp_ne_u32_e64 s[4:5], 1, v138
	s_cbranch_vccnz .LBB0_299
	global_load_dwordx4 v[136:139], v[156:157], off
	s_waitcnt vmcnt(0)
	v_pk_mul_f32 v[132:133], v[132:133], v[138:139]
	v_pk_mul_f32 v[130:131], v[130:131], v[136:137]

; #define PG8_STAGE(bufoff, gbase, voff) do { _Pragma("unroll") for (int _i = 0; _i < 2; ++_i) \
;         __builtin_amdgcn_global_load_lds((const unsigned*)((const char*)(gbase) + (voff)[_i]), (LAS unsigned*)(lds + (bufoff) + ldsw + _i * 8192), 16, 0, 0); } while (0)
; #define PG8_LDA(dst, b, h) do { _Pragma("unroll") for (int m = 0; m < 4; ++m) _Pragma("unroll") for (int k = 0; k < 2; ++k) dst[m][k] = *(const LAS bf16x8*)(lds + PG8_SA(b, h) + aoff + m * 2048 + k * 1024); } while (0)
; #define PG8_LDB(dst, b, h) do { _Pragma("unroll") for (int n = 0; n < 2; ++n) _Pragma("unroll") for (int k = 0; k < 2; ++k) dst[n][k] = *(const LAS bf16x8*)(lds + PG8_SB(b, h) + boff + n * 2048 + k * 1024); } while (0)
; #define PG8_MMA(ai, bj, At, Bt) do { __builtin_amdgcn_s_setprio(1); _Pragma("unroll") for (int m = 0; m < 4; ++m) _Pragma("unroll") for (int n = 0; n < 2; ++n) _Pragma("unroll") for (int k = 0; k < 2; ++k) \
;         acc[ai][bj][m][n] = __builtin_amdgcn_mfma_f32_16x16x32_bf16(Bt[n][k], At[m][k], acc[ai][bj][m][n], 0, 0, 0); __builtin_amdgcn_s_setprio(0); } while (0)
; #define PG8_WAIT_L(n) asm volatile("s_waitcnt lgkmcnt(" #n ")" ::: "memory")
; #define PG8_BAR __builtin_amdgcn_s_barrier()
; #define PG8_SCHED __builtin_amdgcn_sched_barrier(0)
; template <class Epi>
; __device__ __forceinline__ void gemm_phase(LAS unsigned char* lds, const Gemm g, const Epi& E) {
;     ...
;         for (int t = 0; t < nt; t += 2) {
;             const bool last = (t == nt - 2);
;             const char* a1 = cA + (size_t)(t + 1) * kstep;
;             const char* a2 = last ? nA : cA + (size_t)(t + 2) * kstep; const char* b2 = last ? nB : cB + (size_t)(t + 2) * kstep;
;             const char* a3 = a2 + kstep; const char* b3 = b2 + kstep;
;             PG8_LDB(B0, 0, 0); PG8_SCHED; PG8_LDA(At, 0, 0); PG8_STAGE(PG8_SA(1, 1), a1 + hstepA, voffA);
;             PG8_WAIT_L(8); PG8_BAR; PG8_WAIT_L(0); PG8_MMA(0, 0, At, B0); PG8_BAR; PG8_SCHED;
;             PG8_LDB(B1, 0, 1); PG8_STAGE(PG8_SB(0, 0), b2, voffB);
;             PG8_BAR; PG8_WAIT_L(0); PG8_MMA(0, 1, At, B1); PG8_BAR;
;             PG8_LDA(At, 0, 1); PG8_STAGE(PG8_SA(0, 0), a2, voffA);
;             PG8_BAR; PG8_WAIT_L(0); PG8_MMA(1, 0, At, B0); PG8_BAR; PG8_SCHED;
.LBB0_331:
	s_add_u32 s60, s4, 0xfffc0080
	s_addc_u32 s61, s5, -1
	s_add_i32 s72, 0, 0x10000
	s_waitcnt vmcnt(0)
	v_add_u32_e32 v94, s72, v201
	ds_read_b128 v[74:77], v94
	ds_read_b128 v[82:85], v94 offset:1024
	ds_read_b128 v[86:89], v94 offset:2048
	ds_read_b128 v[94:97], v94 offset:3072
	s_cmp_eq_u32 s53, 12
	s_cselect_b32 s65, s29, s61
	s_cselect_b32 s64, s28, s60
	s_cselect_b32 s61, s59, s52
	s_cselect_b32 s60, s58, s15
	v_lshl_add_u64 v[192:193], s[4:5], 0, v[188:189]
	s_add_i32 m0, s24, 0xc000
	ds_read_b128 v[106:109], v202
	ds_read_b128 v[110:113], v202 offset:1024
	ds_read_b128 v[130:133], v202 offset:2048
	ds_read_b128 v[134:137], v202 offset:3072
	ds_read_b128 v[154:157], v202 offset:4096
	ds_read_b128 v[158:161], v202 offset:5120
	ds_read_b128 v[170:173], v202 offset:6144
	ds_read_b128 v[174:177], v202 offset:7168
	global_load_lds_dwordx4 v[192:193], off
	v_lshl_add_u64 v[192:193], s[4:5], 0, v[190:191]
	s_add_i32 m0, s24, 0xe000
	s_nop 0
	global_load_lds_dwordx4 v[192:193], off
	s_waitcnt lgkmcnt(8)
	s_barrier
	s_waitcnt lgkmcnt(0)
	v_mfma_f32_16x16x32_bf16 v[166:169], v[74:77], v[106:109], v[166:169]
	v_mfma_f32_16x16x32_bf16 v[162:165], v[86:89], v[106:109], v[162:165]
	v_mfma_f32_16x16x32_bf16 v[142:145], v[74:77], v[130:133], v[142:145]
	v_mfma_f32_16x16x32_bf16 v[138:141], v[86:89], v[130:133], v[138:141]
	v_mfma_f32_16x16x32_bf16 v[118:121], v[74:77], v[154:157], v[118:121]
	v_mfma_f32_16x16x32_bf16 v[114:117], v[86:89], v[154:157], v[114:117]
	v_mfma_f32_16x16x32_bf16 v[90:93], v[74:77], v[170:173], v[90:93]
	v_mfma_f32_16x16x32_bf16 v[78:81], v[86:89], v[170:173], v[78:81]
	v_mfma_f32_16x16x32_bf16 v[166:169], v[82:85], v[110:113], v[166:169]
	v_mfma_f32_16x16x32_bf16 v[162:165], v[94:97], v[110:113], v[162:165]
	v_mfma_f32_16x16x32_bf16 v[142:145], v[82:85], v[134:137], v[142:145]
	v_mfma_f32_16x16x32_bf16 v[138:141], v[94:97], v[134:137], v[138:141]
	v_mfma_f32_16x16x32_bf16 v[118:121], v[82:85], v[158:161], v[118:121]
	v_mfma_f32_16x16x32_bf16 v[114:117], v[94:97], v[158:161], v[114:117]
	v_mfma_f32_16x16x32_bf16 v[90:93], v[82:85], v[174:177], v[90:93]
	v_mfma_f32_16x16x32_bf16 v[78:81], v[94:97], v[174:177], v[78:81]
	s_barrier
	s_add_i32 s74, 0, 0x14000
	s_add_i32 s72, s72, s1
	v_add_u32_e32 v203, s74, v201
	v_lshl_add_u64 v[208:209], s[60:61], 0, v[184:185]
	s_mov_b32 m0, s72
	ds_read_b128 v[192:195], v203
	ds_read_b128 v[196:199], v203 offset:1024
	ds_read_b128 v[204:207], v203 offset:2048
	ds_read_b128 v[226:229], v203 offset:3072
	global_load_lds_dwordx4 v[208:209], off
	v_lshl_add_u64 v[234:235], s[60:61], 0, v[180:181]
	s_add_i32 m0, s72, 0x2000
	s_nop 0
	global_load_lds_dwordx4 v[234:235], off
	s_barrier
	s_waitcnt lgkmcnt(0)
	v_mfma_f32_16x16x32_bf16 v[150:153], v[192:195], v[106:109], v[150:153]
	v_mfma_f32_16x16x32_bf16 v[106:109], v[204:207], v[106:109], v[146:149]
	v_mfma_f32_16x16x32_bf16 v[122:125], v[204:207], v[130:133], v[122:125]
	v_mfma_f32_16x16x32_bf16 v[102:105], v[192:195], v[154:157], v[102:105]
	v_mfma_f32_16x16x32_bf16 v[98:101], v[204:207], v[154:157], v[98:101]
	v_mfma_f32_16x16x32_bf16 v[70:73], v[192:195], v[170:173], v[70:73]
	v_mfma_f32_16x16x32_bf16 v[66:69], v[204:207], v[170:173], v[66:69]
	v_mfma_f32_16x16x32_bf16 v[150:153], v[196:199], v[110:113], v[150:153]
	v_mfma_f32_16x16x32_bf16 v[106:109], v[226:229], v[110:113], v[106:109]
	v_mfma_f32_16x16x32_bf16 v[110:113], v[192:195], v[130:133], v[126:129]
	v_mfma_f32_16x16x32_bf16 v[122:125], v[226:229], v[134:137], v[122:125]
	v_mfma_f32_16x16x32_bf16 v[102:105], v[196:199], v[158:161], v[102:105]
	v_mfma_f32_16x16x32_bf16 v[98:101], v[226:229], v[158:161], v[98:101]
	v_mfma_f32_16x16x32_bf16 v[70:73], v[196:199], v[174:177], v[70:73]
	v_mfma_f32_16x16x32_bf16 v[66:69], v[226:229], v[174:177], v[66:69]
	v_mfma_f32_16x16x32_bf16 v[110:113], v[196:199], v[134:137], v[110:113]
	s_mov_b32 m0, s24
	v_lshl_add_u64 v[236:237], s[64:65], 0, v[186:187]
	s_barrier
	ds_read_b128 v[126:129], v202 offset:16384
	ds_read_b128 v[130:133], v202 offset:17408
	ds_read_b128 v[134:137], v202 offset:18432
	ds_read_b128 v[146:149], v202 offset:19456
	ds_read_b128 v[154:157], v202 offset:20480
	ds_read_b128 v[158:161], v202 offset:21504
	ds_read_b128 v[170:173], v202 offset:22528
	ds_read_b128 v[174:177], v202 offset:23552
	global_load_lds_dwordx4 v[236:237], off
	v_lshl_add_u64 v[238:239], s[64:65], 0, v[182:183]
	s_mov_b32 m0, s25
	s_nop 0
	global_load_lds_dwordx4 v[238:239], off
	s_barrier
	s_waitcnt lgkmcnt(0)
	v_mfma_f32_16x16x32_bf16 v[62:65], v[74:77], v[126:129], v[62:65]
	v_mfma_f32_16x16x32_bf16 v[58:61], v[86:89], v[126:129], v[58:61]
	v_mfma_f32_16x16x32_bf16 v[46:49], v[74:77], v[134:137], v[46:49]
	v_mfma_f32_16x16x32_bf16 v[42:45], v[86:89], v[134:137], v[42:45]
	v_mfma_f32_16x16x32_bf16 v[30:33], v[74:77], v[154:157], v[30:33]
	v_mfma_f32_16x16x32_bf16 v[26:29], v[86:89], v[154:157], v[26:29]
	v_mfma_f32_16x16x32_bf16 v[14:17], v[74:77], v[170:173], v[14:17]
	v_mfma_f32_16x16x32_bf16 v[10:13], v[86:89], v[170:173], v[10:13]
	v_mfma_f32_16x16x32_bf16 v[62:65], v[82:85], v[130:133], v[62:65]
	v_mfma_f32_16x16x32_bf16 v[58:61], v[94:97], v[130:133], v[58:61]
	v_mfma_f32_16x16x32_bf16 v[46:49], v[82:85], v[146:149], v[46:49]
	v_mfma_f32_16x16x32_bf16 v[42:45], v[94:97], v[146:149], v[42:45]
	v_mfma_f32_16x16x32_bf16 v[30:33], v[82:85], v[158:161], v[30:33]
	v_mfma_f32_16x16x32_bf16 v[26:29], v[94:97], v[158:161], v[26:29]
	v_mfma_f32_16x16x32_bf16 v[14:17], v[82:85], v[174:177], v[14:17]
	v_mfma_f32_16x16x32_bf16 v[10:13], v[94:97], v[174:177], v[10:13]
	s_barrier
; #define PG8_STAGE(bufoff, gbase, voff) do { _Pragma("unroll") for (int _i = 0; _i < 2; ++_i) \
;         __builtin_amdgcn_global_load_lds((const unsigned*)((const char*)(gbase) + (voff)[_i]), (LAS unsigned*)(lds + (bufoff) + ldsw + _i * 8192), 16, 0, 0); } while (0)
; #define PG8_LDA(dst, b, h) do { _Pragma("unroll") for (int m = 0; m < 4; ++m) _Pragma("unroll") for (int k = 0; k < 2; ++k) dst[m][k] = *(const LAS bf16x8*)(lds + PG8_SA(b, h) + aoff + m * 2048 + k * 1024); } while (0)
; #define PG8_LDB(dst, b, h) do { _Pragma("unroll") for (int n = 0; n < 2; ++n) _Pragma("unroll") for (int k = 0; k < 2; ++k) dst[n][k] = *(const LAS bf16x8*)(lds + PG8_SB(b, h) + boff + n * 2048 + k * 1024); } while (0)
; #define PG8_MMA(ai, bj, At, Bt) do { __builtin_amdgcn_s_setprio(1); _Pragma("unroll") for (int m = 0; m < 4; ++m) _Pragma("unroll") for (int n = 0; n < 2; ++n) _Pragma("unroll") for (int k = 0; k < 2; ++k) \
;         acc[ai][bj][m][n] = __builtin_amdgcn_mfma_f32_16x16x32_bf16(Bt[n][k], At[m][k], acc[ai][bj][m][n], 0, 0, 0); __builtin_amdgcn_s_setprio(0); } while (0)
; #define PG8_WAIT_V(n) asm volatile("s_waitcnt vmcnt(" #n ")" ::: "memory")
; #define PG8_WAIT_L(n) asm volatile("s_waitcnt lgkmcnt(" #n ")" ::: "memory")
; #define PG8_BAR __builtin_amdgcn_s_barrier()
; #define PG8_SCHED __builtin_amdgcn_sched_barrier(0)
; template <class Epi>
; __device__ __forceinline__ void gemm_phase(LAS unsigned char* lds, const Gemm g, const Epi& E) {
;     ...
;             PG8_STAGE(PG8_SB(0, 1), b2 + hstepB, voffB);
;             PG8_WAIT_V(6); PG8_BAR; PG8_MMA(1, 1, At, B1); PG8_BAR;
;             PG8_LDB(B0, 1, 0); PG8_SCHED; PG8_LDA(At, 1, 0); PG8_STAGE(PG8_SA(0, 1), a2 + hstepA, voffA);
;             PG8_WAIT_L(8); PG8_BAR; PG8_WAIT_L(0); PG8_MMA(0, 0, At, B0); PG8_BAR; PG8_SCHED;
;             PG8_LDB(B1, 1, 1); PG8_STAGE(PG8_SB(1, 0), b3, voffB);
;             PG8_BAR; PG8_WAIT_L(0); PG8_MMA(0, 1, At, B1); PG8_BAR;
	s_add_u32 s72, s60, 0x40000
	s_addc_u32 s73, s61, 0
	s_add_i32 s74, s74, s1
	v_lshl_add_u64 v[74:75], s[72:73], 0, v[184:185]
	s_mov_b32 m0, s74
	s_nop 0
	global_load_lds_dwordx4 v[74:75], off
	v_lshl_add_u64 v[74:75], s[72:73], 0, v[180:181]
	s_add_i32 m0, s74, 0x2000
	s_nop 0
	global_load_lds_dwordx4 v[74:75], off
	s_waitcnt vmcnt(6)
	s_barrier
	v_mfma_f32_16x16x32_bf16 v[54:57], v[192:195], v[126:129], v[54:57]
	v_mfma_f32_16x16x32_bf16 v[50:53], v[204:207], v[126:129], v[50:53]
	v_mfma_f32_16x16x32_bf16 v[38:41], v[192:195], v[134:137], v[38:41]
	v_mfma_f32_16x16x32_bf16 v[34:37], v[204:207], v[134:137], v[34:37]
	v_mfma_f32_16x16x32_bf16 v[22:25], v[192:195], v[154:157], v[22:25]
	v_mfma_f32_16x16x32_bf16 v[18:21], v[204:207], v[154:157], v[18:21]
	v_mfma_f32_16x16x32_bf16 v[6:9], v[192:195], v[170:173], v[6:9]
	v_mfma_f32_16x16x32_bf16 v[2:5], v[204:207], v[170:173], v[2:5]
	v_mfma_f32_16x16x32_bf16 v[54:57], v[196:199], v[130:133], v[54:57]
	v_mfma_f32_16x16x32_bf16 v[50:53], v[226:229], v[130:133], v[50:53]
	v_mfma_f32_16x16x32_bf16 v[38:41], v[196:199], v[146:149], v[38:41]
	v_mfma_f32_16x16x32_bf16 v[34:37], v[226:229], v[146:149], v[34:37]
	v_mfma_f32_16x16x32_bf16 v[22:25], v[196:199], v[158:161], v[22:25]
	v_mfma_f32_16x16x32_bf16 v[18:21], v[226:229], v[158:161], v[18:21]
	v_mfma_f32_16x16x32_bf16 v[6:9], v[196:199], v[174:177], v[6:9]
	v_mfma_f32_16x16x32_bf16 v[2:5], v[226:229], v[174:177], v[2:5]
	s_add_i32 s72, 0, 0x18000
	v_add_u32_e32 v94, s72, v201
	s_barrier
	ds_read_b128 v[74:77], v94
	ds_read_b128 v[82:85], v94 offset:1024
	ds_read_b128 v[86:89], v94 offset:2048
	ds_read_b128 v[94:97], v94 offset:3072
	s_add_u32 s64, s64, 0x40000
	s_addc_u32 s65, s65, 0
	s_mov_b32 m0, s31
	v_lshl_add_u64 v[146:147], s[64:65], 0, v[186:187]
	ds_read_b128 v[126:129], v202 offset:32768
	ds_read_b128 v[130:133], v202 offset:33792
	ds_read_b128 v[134:137], v202 offset:34816
	ds_read_b128 v[154:157], v202 offset:35840
	ds_read_b128 v[158:161], v202 offset:36864
	ds_read_b128 v[170:173], v202 offset:37888
	ds_read_b128 v[174:177], v202 offset:38912
	ds_read_b128 v[192:195], v202 offset:39936
	global_load_lds_dwordx4 v[146:147], off
	v_lshl_add_u64 v[146:147], s[64:65], 0, v[182:183]
	s_mov_b32 m0, s36
	s_nop 0
	global_load_lds_dwordx4 v[146:147], off
	s_waitcnt lgkmcnt(8)
	s_barrier
	s_waitcnt lgkmcnt(0)
	v_mfma_f32_16x16x32_bf16 v[146:149], v[74:77], v[126:129], v[166:169]
	v_mfma_f32_16x16x32_bf16 v[166:169], v[82:85], v[130:133], v[146:149]
	v_mfma_f32_16x16x32_bf16 v[146:149], v[86:89], v[126:129], v[162:165]
	v_mfma_f32_16x16x32_bf16 v[142:145], v[74:77], v[134:137], v[142:145]
	v_mfma_f32_16x16x32_bf16 v[138:141], v[86:89], v[134:137], v[138:141]
	v_mfma_f32_16x16x32_bf16 v[118:121], v[74:77], v[158:161], v[118:121]
	v_mfma_f32_16x16x32_bf16 v[114:117], v[86:89], v[158:161], v[114:117]
	v_mfma_f32_16x16x32_bf16 v[90:93], v[74:77], v[174:177], v[90:93]
	v_mfma_f32_16x16x32_bf16 v[78:81], v[86:89], v[174:177], v[78:81]
	v_mfma_f32_16x16x32_bf16 v[162:165], v[94:97], v[130:133], v[146:149]
	v_mfma_f32_16x16x32_bf16 v[142:145], v[82:85], v[154:157], v[142:145]
	v_mfma_f32_16x16x32_bf16 v[138:141], v[94:97], v[154:157], v[138:141]
	v_mfma_f32_16x16x32_bf16 v[118:121], v[82:85], v[170:173], v[118:121]
	v_mfma_f32_16x16x32_bf16 v[114:117], v[94:97], v[170:173], v[114:117]
	v_mfma_f32_16x16x32_bf16 v[90:93], v[82:85], v[192:195], v[90:93]
	v_mfma_f32_16x16x32_bf16 v[78:81], v[94:97], v[192:195], v[78:81]
	s_barrier
	s_add_i32 s64, 0, 0x1c000
	v_add_u32_e32 v146, s64, v201
	s_add_i32 s65, s72, s1
	ds_read_b128 v[196:199], v146
	ds_read_b128 v[204:207], v146 offset:1024
	ds_read_b128 v[226:229], v146 offset:2048
	ds_read_b128 v[230:233], v146 offset:3072
	v_lshl_add_u64 v[146:147], v[208:209], 0, s[86:87]
	s_mov_b32 m0, s65
	s_nop 0
	global_load_lds_dwordx4 v[146:147], off
	v_lshl_add_u64 v[146:147], v[234:235], 0, s[86:87]
	s_add_i32 m0, s65, 0x2000
	s_nop 0
	global_load_lds_dwordx4 v[146:147], off
	s_barrier
	s_waitcnt lgkmcnt(0)
	v_mfma_f32_16x16x32_bf16 v[146:149], v[196:199], v[126:129], v[150:153]
	v_mfma_f32_16x16x32_bf16 v[106:109], v[226:229], v[126:129], v[106:109]
	v_mfma_f32_16x16x32_bf16 v[150:153], v[204:207], v[130:133], v[146:149]
	v_mfma_f32_16x16x32_bf16 v[146:149], v[230:233], v[130:133], v[106:109]
	v_mfma_f32_16x16x32_bf16 v[106:109], v[196:199], v[134:137], v[110:113]
	v_mfma_f32_16x16x32_bf16 v[126:129], v[204:207], v[154:157], v[106:109]
	v_mfma_f32_16x16x32_bf16 v[106:109], v[226:229], v[134:137], v[122:125]
	v_mfma_f32_16x16x32_bf16 v[102:105], v[196:199], v[158:161], v[102:105]
	v_mfma_f32_16x16x32_bf16 v[98:101], v[226:229], v[158:161], v[98:101]
	v_mfma_f32_16x16x32_bf16 v[70:73], v[196:199], v[174:177], v[70:73]
	v_mfma_f32_16x16x32_bf16 v[66:69], v[226:229], v[174:177], v[66:69]
	v_mfma_f32_16x16x32_bf16 v[122:125], v[230:233], v[154:157], v[106:109]
	v_mfma_f32_16x16x32_bf16 v[102:105], v[204:207], v[170:173], v[102:105]
	v_mfma_f32_16x16x32_bf16 v[98:101], v[230:233], v[170:173], v[98:101]
	v_mfma_f32_16x16x32_bf16 v[70:73], v[204:207], v[192:195], v[70:73]
	v_mfma_f32_16x16x32_bf16 v[66:69], v[230:233], v[192:195], v[66:69]
	s_mov_b32 m0, s50
	v_lshl_add_u64 v[192:193], v[236:237], 0, s[86:87]
	s_barrier
; #define PG8_STAGE(bufoff, gbase, voff) do { _Pragma("unroll") for (int _i = 0; _i < 2; ++_i) \
;         __builtin_amdgcn_global_load_lds((const unsigned*)((const char*)(gbase) + (voff)[_i]), (LAS unsigned*)(lds + (bufoff) + ldsw + _i * 8192), 16, 0, 0); } while (0)
; #define PG8_LDA(dst, b, h) do { _Pragma("unroll") for (int m = 0; m < 4; ++m) _Pragma("unroll") for (int k = 0; k < 2; ++k) dst[m][k] = *(const LAS bf16x8*)(lds + PG8_SA(b, h) + aoff + m * 2048 + k * 1024); } while (0)
; #define PG8_MMA(ai, bj, At, Bt) do { __builtin_amdgcn_s_setprio(1); _Pragma("unroll") for (int m = 0; m < 4; ++m) _Pragma("unroll") for (int n = 0; n < 2; ++n) _Pragma("unroll") for (int k = 0; k < 2; ++k) \
;         acc[ai][bj][m][n] = __builtin_amdgcn_mfma_f32_16x16x32_bf16(Bt[n][k], At[m][k], acc[ai][bj][m][n], 0, 0, 0); __builtin_amdgcn_s_setprio(0); } while (0)
; #define PG8_WAIT_V(n) asm volatile("s_waitcnt vmcnt(" #n ")" ::: "memory")
; template <class Epi>
; __device__ __forceinline__ void gemm_phase(LAS unsigned char* lds, const Gemm g, const Epi& E) {
;     ...
;             PG8_LDA(At, 1, 1); PG8_STAGE(PG8_SA(1, 0), a3, voffA);
;             PG8_BAR; PG8_WAIT_L(0); PG8_MMA(1, 0, At, B0); PG8_BAR; PG8_SCHED;
;             PG8_STAGE(PG8_SB(1, 1), b3 + hstepB, voffB);
;             PG8_WAIT_V(6); PG8_BAR; PG8_MMA(1, 1, At, B1); PG8_BAR;
;         }
;     __device__ __forceinline__ void operator()(const AccT& acc, const Unit& u, int wr, int wc, int fr, int fq) const {
;     ...
;         const int gpm = mapA.src(u.pm);
;         const bool isq = u.pn < 4, isv = u.pn >= 8;
;         const bool lat = gpm >= 32 && !isv;
;         bf16_t* base = isq ? Q : (isv ? Vv + (size_t)(u.pn - 8) * 256 : Kk);
;         const int hh = isv ? 0 : (u.pn & 3);
;         const int ldo = isv ? 2048 : 1024;
;         const float osc = isq ? 0.0625f : 1.0f;
;         const int p0 = 16 * wc + 4 * fq;
;         f32x4 ctR[2][2], ctC[4][2];
;         if (lat) {
; #pragma unroll
;             for (int ai = 0; ai < 2; ++ai) { const int pr = ((gpm - 32) * 4 + 2 * ai + wr) & 31;
;                 ctR[ai][0] = *(const f32x4*)(cs + pr * 64 + p0); ctR[ai][1] = *(const f32x4*)(cs + pr * 64 + p0 + 2); }
; #pragma unroll
;             for (int m = 0; m < 4; ++m) { const int pc = m * 16 + fr;
;                 ctC[m][0] = *(const f32x4*)(cs + pc * 64 + p0); ctC[m][1] = *(const f32x4*)(cs + pc * 64 + p0 + 2); }
;         }
	ds_read_b128 v[106:109], v202 offset:49152
	ds_read_b128 v[110:113], v202 offset:50176
	ds_read_b128 v[130:133], v202 offset:51200
	ds_read_b128 v[134:137], v202 offset:52224
	ds_read_b128 v[154:157], v202 offset:53248
	ds_read_b128 v[158:161], v202 offset:54272
	ds_read_b128 v[170:173], v202 offset:55296
	ds_read_b128 v[174:177], v202 offset:56320
	global_load_lds_dwordx4 v[192:193], off
	v_lshl_add_u64 v[192:193], v[238:239], 0, s[86:87]
	s_mov_b32 m0, s66
	s_nop 0
	global_load_lds_dwordx4 v[192:193], off
	s_barrier
	s_waitcnt lgkmcnt(0)
	v_mfma_f32_16x16x32_bf16 v[62:65], v[74:77], v[106:109], v[62:65]
	v_mfma_f32_16x16x32_bf16 v[58:61], v[86:89], v[106:109], v[58:61]
	v_mfma_f32_16x16x32_bf16 v[46:49], v[74:77], v[130:133], v[46:49]
	v_mfma_f32_16x16x32_bf16 v[42:45], v[86:89], v[130:133], v[42:45]
	v_mfma_f32_16x16x32_bf16 v[30:33], v[74:77], v[154:157], v[30:33]
	v_mfma_f32_16x16x32_bf16 v[26:29], v[86:89], v[154:157], v[26:29]
	v_mfma_f32_16x16x32_bf16 v[14:17], v[74:77], v[170:173], v[14:17]
	v_mfma_f32_16x16x32_bf16 v[10:13], v[86:89], v[170:173], v[10:13]
	v_mfma_f32_16x16x32_bf16 v[62:65], v[82:85], v[110:113], v[62:65]
	v_mfma_f32_16x16x32_bf16 v[58:61], v[94:97], v[110:113], v[58:61]
	v_mfma_f32_16x16x32_bf16 v[46:49], v[82:85], v[134:137], v[46:49]
	v_mfma_f32_16x16x32_bf16 v[42:45], v[94:97], v[134:137], v[42:45]
	v_mfma_f32_16x16x32_bf16 v[30:33], v[82:85], v[158:161], v[30:33]
	v_mfma_f32_16x16x32_bf16 v[26:29], v[94:97], v[158:161], v[26:29]
	v_mfma_f32_16x16x32_bf16 v[14:17], v[82:85], v[174:177], v[14:17]
	v_mfma_f32_16x16x32_bf16 v[10:13], v[94:97], v[174:177], v[10:13]
	s_barrier
	s_add_u32 s60, s60, 0x40080
	s_addc_u32 s61, s61, 0
	s_add_i32 s64, s64, s1
	v_lshl_add_u64 v[74:75], s[60:61], 0, v[184:185]
	s_mov_b32 m0, s64
	s_nop 0
	global_load_lds_dwordx4 v[74:75], off
	v_lshl_add_u64 v[74:75], s[60:61], 0, v[180:181]
	s_add_i32 m0, s64, 0x2000
	s_nop 0
	global_load_lds_dwordx4 v[74:75], off
	s_waitcnt vmcnt(6)
	s_barrier
	v_mfma_f32_16x16x32_bf16 v[54:57], v[196:199], v[106:109], v[54:57]
	v_mfma_f32_16x16x32_bf16 v[50:53], v[226:229], v[106:109], v[50:53]
	v_mfma_f32_16x16x32_bf16 v[38:41], v[196:199], v[130:133], v[38:41]
	v_mfma_f32_16x16x32_bf16 v[34:37], v[226:229], v[130:133], v[34:37]
	v_mfma_f32_16x16x32_bf16 v[22:25], v[196:199], v[154:157], v[22:25]
	v_mfma_f32_16x16x32_bf16 v[18:21], v[226:229], v[154:157], v[18:21]
	v_mfma_f32_16x16x32_bf16 v[6:9], v[196:199], v[170:173], v[6:9]
	v_mfma_f32_16x16x32_bf16 v[2:5], v[226:229], v[170:173], v[2:5]
	v_mfma_f32_16x16x32_bf16 v[54:57], v[204:207], v[110:113], v[54:57]
	v_mfma_f32_16x16x32_bf16 v[50:53], v[230:233], v[110:113], v[50:53]
	v_mfma_f32_16x16x32_bf16 v[38:41], v[204:207], v[134:137], v[38:41]
	v_mfma_f32_16x16x32_bf16 v[34:37], v[230:233], v[134:137], v[34:37]
	v_mfma_f32_16x16x32_bf16 v[22:25], v[204:207], v[158:161], v[22:25]
	v_mfma_f32_16x16x32_bf16 v[18:21], v[230:233], v[158:161], v[18:21]
	v_mfma_f32_16x16x32_bf16 v[6:9], v[204:207], v[174:177], v[6:9]
	v_mfma_f32_16x16x32_bf16 v[2:5], v[230:233], v[174:177], v[2:5]
	s_add_i32 s53, s53, 2
	s_add_u32 s4, s4, 0x100
	s_addc_u32 s5, s5, 0
	s_add_u32 s15, s15, 0x100
	s_addc_u32 s52, s52, 0
	s_cmp_gt_u32 s53, 13
	s_barrier
	s_cbranch_scc0 .LBB0_331
	s_cmp_lt_i32 s10, 16
	s_cselect_b32 s4, s68, s18
	s_add_i32 s15, s10, s4
	s_cmp_lt_i32 s11, 8
	s_cselect_b64 s[60:61], -1, 0
	s_cmp_gt_i32 s15, 31
	s_cselect_b64 s[4:5], -1, 0
	s_and_b64 s[52:53], s[60:61], s[4:5]
	v_cndmask_b32_e64 v74, 0, 1, s[52:53]
	v_mov_b32_e32 v194, v200
	v_mov_b32_e32 v193, v1
	v_cmp_ne_u32_e64 s[4:5], 1, v74
	s_andn2_b64 vcc, exec, s[52:53]
	s_cbranch_vccnz .LBB0_334
	v_lshl_add_u32 v74, v193, 2, s67
	v_readlane_b32 s52, v254, 2
	s_lshl_b32 s15, s15, 8
	v_ashrrev_i32_e32 v75, 31, v74
	v_readlane_b32 s53, v254, 3
	s_add_i32 s15, s15, s44
	s_nop 0
	v_lshl_add_u64 v[74:75], v[74:75], 3, s[52:53]
	s_and_b32 s52, s15, 0x7c0
	s_addk_i32 s15, 0x80
	s_lshl_b32 s76, s52, 3
	s_and_b32 s15, s15, 0x7c0
	v_lshl_add_u64 v[76:77], v[74:75], 0, s[76:77]
	s_lshl_b32 s76, s15, 3
	global_load_dwordx4 v[170:173], v[76:77], off offset:16
	global_load_dwordx4 v[174:177], v[76:77], off
	v_lshl_add_u64 v[76:77], v[74:75], 0, s[76:77]
	global_load_dwordx4 v[86:89], v[76:77], off offset:16
	global_load_dwordx4 v[94:97], v[76:77], off
	v_lshlrev_b32_e32 v76, 6, v194
	v_ashrrev_i32_e32 v77, 31, v76
	v_lshl_add_u64 v[82:83], v[76:77], 3, v[74:75]
	global_load_dwordx4 v[154:157], v[82:83], off offset:16
	global_load_dwordx4 v[158:161], v[82:83], off
	v_add_u32_e32 v82, 0x400, v76
	v_ashrrev_i32_e32 v83, 31, v82
	v_lshl_add_u64 v[82:83], v[82:83], 3, v[74:75]
	global_load_dwordx4 v[130:133], v[82:83], off offset:16
	global_load_dwordx4 v[134:137], v[82:83], off
	v_add_u32_e32 v82, 0x800, v76
	v_ashrrev_i32_e32 v83, 31, v82
	v_add_u32_e32 v76, 0xc00, v76
	v_lshl_add_u64 v[82:83], v[82:83], 3, v[74:75]
	v_ashrrev_i32_e32 v77, 31, v76
	global_load_dwordx4 v[106:109], v[82:83], off offset:16
	global_load_dwordx4 v[110:113], v[82:83], off
	v_lshl_add_u64 v[82:83], v[76:77], 3, v[74:75]
	global_load_dwordx4 v[74:77], v[82:83], off offset:16
	s_nop 0
	global_load_dwordx4 v[82:85], v[82:83], off

; #define PG8_STAGE(bufoff, gbase, voff) do { _Pragma("unroll") for (int _i = 0; _i < 2; ++_i) \
;         __builtin_amdgcn_global_load_lds((const unsigned*)((const char*)(gbase) + (voff)[_i]), (LAS unsigned*)(lds + (bufoff) + ldsw + _i * 8192), 16, 0, 0); } while (0)
; #define PG8_LDA(dst, b, h) do { _Pragma("unroll") for (int m = 0; m < 4; ++m) _Pragma("unroll") for (int k = 0; k < 2; ++k) dst[m][k] = *(const LAS bf16x8*)(lds + PG8_SA(b, h) + aoff + m * 2048 + k * 1024); } while (0)
; #define PG8_LDB(dst, b, h) do { _Pragma("unroll") for (int n = 0; n < 2; ++n) _Pragma("unroll") for (int k = 0; k < 2; ++k) dst[n][k] = *(const LAS bf16x8*)(lds + PG8_SB(b, h) + boff + n * 2048 + k * 1024); } while (0)
; #define PG8_MMA(ai, bj, At, Bt) do { __builtin_amdgcn_s_setprio(1); _Pragma("unroll") for (int m = 0; m < 4; ++m) _Pragma("unroll") for (int n = 0; n < 2; ++n) _Pragma("unroll") for (int k = 0; k < 2; ++k) \
;         acc[ai][bj][m][n] = __builtin_amdgcn_mfma_f32_16x16x32_bf16(Bt[n][k], At[m][k], acc[ai][bj][m][n], 0, 0, 0); __builtin_amdgcn_s_setprio(0); } while (0)
; #define PG8_WAIT_L(n) asm volatile("s_waitcnt lgkmcnt(" #n ")" ::: "memory")
; #define PG8_BAR __builtin_amdgcn_s_barrier()
; #define PG8_SCHED __builtin_amdgcn_sched_barrier(0)
; template <class Epi>
; __device__ __forceinline__ void gemm_phase(LAS unsigned char* lds, const Gemm g, const Epi& E) {
;     ...
;         for (int t = 0; t < nt; t += 2) {
;             const bool last = (t == nt - 2);
;             const char* a1 = cA + (size_t)(t + 1) * kstep;
;             const char* a2 = last ? nA : cA + (size_t)(t + 2) * kstep; const char* b2 = last ? nB : cB + (size_t)(t + 2) * kstep;
;             const char* a3 = a2 + kstep; const char* b3 = b2 + kstep;
;             PG8_LDB(B0, 0, 0); PG8_SCHED; PG8_LDA(At, 0, 0); PG8_STAGE(PG8_SA(1, 1), a1 + hstepA, voffA);
;             PG8_WAIT_L(8); PG8_BAR; PG8_WAIT_L(0); PG8_MMA(0, 0, At, B0); PG8_BAR; PG8_SCHED;
;             PG8_LDB(B1, 0, 1); PG8_STAGE(PG8_SB(0, 0), b2, voffB);
;             PG8_BAR; PG8_WAIT_L(0); PG8_MMA(0, 1, At, B1); PG8_BAR;
;             PG8_LDA(At, 0, 1); PG8_STAGE(PG8_SA(0, 0), a2, voffA);
;             PG8_BAR; PG8_WAIT_L(0); PG8_MMA(1, 0, At, B0); PG8_BAR; PG8_SCHED;
.LBB0_475:
	s_add_u32 s16, s14, 0xfffc0080
	s_addc_u32 s17, s15, -1
	s_add_i32 s66, 0, 0x10000
	v_add_u32_e32 v86, s66, v226
	ds_read_b128 v[66:69], v86
	ds_read_b128 v[70:73], v86 offset:1024
	ds_read_b128 v[82:85], v86 offset:2048
	ds_read_b128 v[86:89], v86 offset:3072
	s_cmp_eq_u32 s65, 12
	s_cselect_b32 s29, s11, s17
	s_cselect_b32 s28, s10, s16
	s_cselect_b32 s17, s5, s53
	s_cselect_b32 s16, s4, s9
	v_lshl_add_u64 v[192:193], s[14:15], 0, v[174:175]
	s_add_i32 m0, s13, 0xc000
	ds_read_b128 v[146:149], v227
	ds_read_b128 v[150:153], v227 offset:1024
	ds_read_b128 v[154:157], v227 offset:2048
	ds_read_b128 v[158:161], v227 offset:3072
	ds_read_b128 v[162:165], v227 offset:4096
	ds_read_b128 v[180:183], v227 offset:5120
	ds_read_b128 v[184:187], v227 offset:6144
	ds_read_b128 v[188:191], v227 offset:7168
	global_load_lds_dwordx4 v[192:193], off
	v_lshl_add_u64 v[192:193], s[14:15], 0, v[176:177]
	s_add_i32 m0, s13, 0xe000
	s_nop 0
	global_load_lds_dwordx4 v[192:193], off
	s_waitcnt lgkmcnt(8)
	s_barrier
	s_waitcnt lgkmcnt(0)
	v_mfma_f32_16x16x32_bf16 v[142:145], v[66:69], v[146:149], v[142:145]
	v_mfma_f32_16x16x32_bf16 v[138:141], v[82:85], v[146:149], v[138:141]
	v_mfma_f32_16x16x32_bf16 v[126:129], v[66:69], v[154:157], v[126:129]
	v_mfma_f32_16x16x32_bf16 v[122:125], v[82:85], v[154:157], v[122:125]
	v_mfma_f32_16x16x32_bf16 v[110:113], v[66:69], v[162:165], v[110:113]
	v_mfma_f32_16x16x32_bf16 v[106:109], v[82:85], v[162:165], v[106:109]
	v_mfma_f32_16x16x32_bf16 v[94:97], v[66:69], v[184:187], v[94:97]
	v_mfma_f32_16x16x32_bf16 v[90:93], v[82:85], v[184:187], v[90:93]
	v_mfma_f32_16x16x32_bf16 v[142:145], v[70:73], v[150:153], v[142:145]
	v_mfma_f32_16x16x32_bf16 v[138:141], v[86:89], v[150:153], v[138:141]
	v_mfma_f32_16x16x32_bf16 v[126:129], v[70:73], v[158:161], v[126:129]
	v_mfma_f32_16x16x32_bf16 v[122:125], v[86:89], v[158:161], v[122:125]
	v_mfma_f32_16x16x32_bf16 v[110:113], v[70:73], v[180:183], v[110:113]
	v_mfma_f32_16x16x32_bf16 v[106:109], v[86:89], v[180:183], v[106:109]
	v_mfma_f32_16x16x32_bf16 v[94:97], v[70:73], v[188:191], v[94:97]
	v_mfma_f32_16x16x32_bf16 v[90:93], v[86:89], v[188:191], v[90:93]
	s_barrier
	s_add_i32 s68, 0, 0x14000
	s_add_i32 s66, s66, s18
	v_add_u32_e32 v204, s68, v226
	v_lshl_add_u64 v[208:209], s[16:17], 0, v[170:171]
	s_mov_b32 m0, s66
	ds_read_b128 v[192:195], v204
	ds_read_b128 v[196:199], v204 offset:1024
	ds_read_b128 v[200:203], v204 offset:2048
	ds_read_b128 v[204:207], v204 offset:3072
	global_load_lds_dwordx4 v[208:209], off
	v_lshl_add_u64 v[228:229], s[16:17], 0, v[166:167]
	s_add_i32 m0, s66, 0x2000
	s_nop 0
	global_load_lds_dwordx4 v[228:229], off
	s_barrier
	s_waitcnt lgkmcnt(0)
	v_mfma_f32_16x16x32_bf16 v[134:137], v[192:195], v[146:149], v[134:137]
	v_mfma_f32_16x16x32_bf16 v[130:133], v[200:203], v[146:149], v[130:133]
	v_mfma_f32_16x16x32_bf16 v[118:121], v[192:195], v[154:157], v[118:121]
	v_mfma_f32_16x16x32_bf16 v[114:117], v[200:203], v[154:157], v[114:117]
	v_mfma_f32_16x16x32_bf16 v[102:105], v[192:195], v[162:165], v[102:105]
	v_mfma_f32_16x16x32_bf16 v[98:101], v[200:203], v[162:165], v[98:101]
	v_mfma_f32_16x16x32_bf16 v[78:81], v[192:195], v[184:187], v[78:81]
	v_mfma_f32_16x16x32_bf16 v[74:77], v[200:203], v[184:187], v[74:77]
	v_mfma_f32_16x16x32_bf16 v[134:137], v[196:199], v[150:153], v[134:137]
	v_mfma_f32_16x16x32_bf16 v[130:133], v[204:207], v[150:153], v[130:133]
	v_mfma_f32_16x16x32_bf16 v[118:121], v[196:199], v[158:161], v[118:121]
	v_mfma_f32_16x16x32_bf16 v[114:117], v[204:207], v[158:161], v[114:117]
	v_mfma_f32_16x16x32_bf16 v[102:105], v[196:199], v[180:183], v[102:105]
	v_mfma_f32_16x16x32_bf16 v[98:101], v[204:207], v[180:183], v[98:101]
	v_mfma_f32_16x16x32_bf16 v[78:81], v[196:199], v[188:191], v[78:81]
	v_mfma_f32_16x16x32_bf16 v[74:77], v[204:207], v[188:191], v[74:77]
	s_mov_b32 m0, s13
	v_lshl_add_u64 v[230:231], s[28:29], 0, v[172:173]
	s_barrier
	ds_read_b128 v[146:149], v227 offset:16384
	ds_read_b128 v[150:153], v227 offset:17408
	ds_read_b128 v[154:157], v227 offset:18432
	ds_read_b128 v[158:161], v227 offset:19456
	ds_read_b128 v[162:165], v227 offset:20480
	ds_read_b128 v[180:183], v227 offset:21504
	ds_read_b128 v[184:187], v227 offset:22528
	ds_read_b128 v[188:191], v227 offset:23552
	global_load_lds_dwordx4 v[230:231], off
	v_lshl_add_u64 v[232:233], s[28:29], 0, v[168:169]
	s_mov_b32 m0, s31
	s_nop 0
	global_load_lds_dwordx4 v[232:233], off
	s_barrier
	s_waitcnt lgkmcnt(0)
	v_mfma_f32_16x16x32_bf16 v[62:65], v[66:69], v[146:149], v[62:65]
	v_mfma_f32_16x16x32_bf16 v[58:61], v[82:85], v[146:149], v[58:61]
	v_mfma_f32_16x16x32_bf16 v[46:49], v[66:69], v[154:157], v[46:49]
	v_mfma_f32_16x16x32_bf16 v[42:45], v[82:85], v[154:157], v[42:45]
	v_mfma_f32_16x16x32_bf16 v[30:33], v[66:69], v[162:165], v[30:33]
	v_mfma_f32_16x16x32_bf16 v[26:29], v[82:85], v[162:165], v[26:29]
	v_mfma_f32_16x16x32_bf16 v[14:17], v[66:69], v[184:187], v[14:17]
	v_mfma_f32_16x16x32_bf16 v[10:13], v[82:85], v[184:187], v[10:13]
	v_mfma_f32_16x16x32_bf16 v[62:65], v[70:73], v[150:153], v[62:65]
	v_mfma_f32_16x16x32_bf16 v[58:61], v[86:89], v[150:153], v[58:61]
	v_mfma_f32_16x16x32_bf16 v[46:49], v[70:73], v[158:161], v[46:49]
	v_mfma_f32_16x16x32_bf16 v[42:45], v[86:89], v[158:161], v[42:45]
	v_mfma_f32_16x16x32_bf16 v[30:33], v[70:73], v[180:183], v[30:33]
	v_mfma_f32_16x16x32_bf16 v[26:29], v[86:89], v[180:183], v[26:29]
	v_mfma_f32_16x16x32_bf16 v[14:17], v[70:73], v[188:191], v[14:17]
	v_mfma_f32_16x16x32_bf16 v[10:13], v[86:89], v[188:191], v[10:13]
	s_barrier
; #define PG8_STAGE(bufoff, gbase, voff) do { _Pragma("unroll") for (int _i = 0; _i < 2; ++_i) \
;         __builtin_amdgcn_global_load_lds((const unsigned*)((const char*)(gbase) + (voff)[_i]), (LAS unsigned*)(lds + (bufoff) + ldsw + _i * 8192), 16, 0, 0); } while (0)
; #define PG8_LDA(dst, b, h) do { _Pragma("unroll") for (int m = 0; m < 4; ++m) _Pragma("unroll") for (int k = 0; k < 2; ++k) dst[m][k] = *(const LAS bf16x8*)(lds + PG8_SA(b, h) + aoff + m * 2048 + k * 1024); } while (0)
; #define PG8_LDB(dst, b, h) do { _Pragma("unroll") for (int n = 0; n < 2; ++n) _Pragma("unroll") for (int k = 0; k < 2; ++k) dst[n][k] = *(const LAS bf16x8*)(lds + PG8_SB(b, h) + boff + n * 2048 + k * 1024); } while (0)
; #define PG8_MMA(ai, bj, At, Bt) do { __builtin_amdgcn_s_setprio(1); _Pragma("unroll") for (int m = 0; m < 4; ++m) _Pragma("unroll") for (int n = 0; n < 2; ++n) _Pragma("unroll") for (int k = 0; k < 2; ++k) \
;         acc[ai][bj][m][n] = __builtin_amdgcn_mfma_f32_16x16x32_bf16(Bt[n][k], At[m][k], acc[ai][bj][m][n], 0, 0, 0); __builtin_amdgcn_s_setprio(0); } while (0)
; #define PG8_WAIT_V(n) asm volatile("s_waitcnt vmcnt(" #n ")" ::: "memory")
; #define PG8_WAIT_L(n) asm volatile("s_waitcnt lgkmcnt(" #n ")" ::: "memory")
; #define PG8_BAR __builtin_amdgcn_s_barrier()
; #define PG8_SCHED __builtin_amdgcn_sched_barrier(0)
; template <class Epi>
; __device__ __forceinline__ void gemm_phase(LAS unsigned char* lds, const Gemm g, const Epi& E) {
;     ...
;             PG8_BAR; PG8_WAIT_L(0); PG8_MMA(1, 0, At, B0); PG8_BAR; PG8_SCHED;
;             PG8_STAGE(PG8_SB(0, 1), b2 + hstepB, voffB);
;             PG8_WAIT_V(6); PG8_BAR; PG8_MMA(1, 1, At, B1); PG8_BAR;
;             PG8_LDB(B0, 1, 0); PG8_SCHED; PG8_LDA(At, 1, 0); PG8_STAGE(PG8_SA(0, 1), a2 + hstepA, voffA);
;             PG8_WAIT_L(8); PG8_BAR; PG8_WAIT_L(0); PG8_MMA(0, 0, At, B0); PG8_BAR; PG8_SCHED;
;             PG8_LDB(B1, 1, 1); PG8_STAGE(PG8_SB(1, 0), b3, voffB);
;             PG8_BAR; PG8_WAIT_L(0); PG8_MMA(0, 1, At, B1); PG8_BAR;
	s_add_u32 s66, s16, 0x40000
	s_addc_u32 s67, s17, 0
	s_add_i32 s68, s68, s18
	v_lshl_add_u64 v[66:67], s[66:67], 0, v[170:171]
	s_mov_b32 m0, s68
	s_nop 0
	global_load_lds_dwordx4 v[66:67], off
	v_lshl_add_u64 v[66:67], s[66:67], 0, v[166:167]
	s_add_i32 m0, s68, 0x2000
	s_nop 0
	global_load_lds_dwordx4 v[66:67], off
	s_waitcnt vmcnt(6)
	s_barrier
	v_mfma_f32_16x16x32_bf16 v[54:57], v[192:195], v[146:149], v[54:57]
	v_mfma_f32_16x16x32_bf16 v[50:53], v[200:203], v[146:149], v[50:53]
	v_mfma_f32_16x16x32_bf16 v[38:41], v[192:195], v[154:157], v[38:41]
	v_mfma_f32_16x16x32_bf16 v[34:37], v[200:203], v[154:157], v[34:37]
	v_mfma_f32_16x16x32_bf16 v[22:25], v[192:195], v[162:165], v[22:25]
	v_mfma_f32_16x16x32_bf16 v[18:21], v[200:203], v[162:165], v[18:21]
	v_mfma_f32_16x16x32_bf16 v[6:9], v[192:195], v[184:187], v[6:9]
	v_mfma_f32_16x16x32_bf16 v[2:5], v[200:203], v[184:187], v[2:5]
	v_mfma_f32_16x16x32_bf16 v[54:57], v[196:199], v[150:153], v[54:57]
	v_mfma_f32_16x16x32_bf16 v[50:53], v[204:207], v[150:153], v[50:53]
	v_mfma_f32_16x16x32_bf16 v[38:41], v[196:199], v[158:161], v[38:41]
	v_mfma_f32_16x16x32_bf16 v[34:37], v[204:207], v[158:161], v[34:37]
	v_mfma_f32_16x16x32_bf16 v[22:25], v[196:199], v[180:183], v[22:25]
	v_mfma_f32_16x16x32_bf16 v[18:21], v[204:207], v[180:183], v[18:21]
	v_mfma_f32_16x16x32_bf16 v[6:9], v[196:199], v[188:191], v[6:9]
	v_mfma_f32_16x16x32_bf16 v[2:5], v[204:207], v[188:191], v[2:5]
	s_add_i32 s66, 0, 0x18000
	v_add_u32_e32 v86, s66, v226
	s_barrier
	ds_read_b128 v[66:69], v86
	ds_read_b128 v[70:73], v86 offset:1024
	ds_read_b128 v[82:85], v86 offset:2048
	ds_read_b128 v[86:89], v86 offset:3072
	s_add_u32 s28, s28, 0x40000
	s_addc_u32 s29, s29, 0
	s_mov_b32 m0, s36
	v_lshl_add_u64 v[192:193], s[28:29], 0, v[172:173]
	ds_read_b128 v[146:149], v227 offset:32768
	ds_read_b128 v[150:153], v227 offset:33792
	ds_read_b128 v[154:157], v227 offset:34816
	ds_read_b128 v[158:161], v227 offset:35840
	ds_read_b128 v[162:165], v227 offset:36864
	ds_read_b128 v[180:183], v227 offset:37888
	ds_read_b128 v[184:187], v227 offset:38912
	ds_read_b128 v[188:191], v227 offset:39936
	global_load_lds_dwordx4 v[192:193], off
	v_lshl_add_u64 v[192:193], s[28:29], 0, v[168:169]
	s_mov_b32 m0, s44
	s_nop 0
	global_load_lds_dwordx4 v[192:193], off
	s_waitcnt lgkmcnt(8)
	s_barrier
	s_waitcnt lgkmcnt(0)
	v_mfma_f32_16x16x32_bf16 v[142:145], v[66:69], v[146:149], v[142:145]
	v_mfma_f32_16x16x32_bf16 v[138:141], v[82:85], v[146:149], v[138:141]
	v_mfma_f32_16x16x32_bf16 v[126:129], v[66:69], v[154:157], v[126:129]
	v_mfma_f32_16x16x32_bf16 v[122:125], v[82:85], v[154:157], v[122:125]
	v_mfma_f32_16x16x32_bf16 v[110:113], v[66:69], v[162:165], v[110:113]
	v_mfma_f32_16x16x32_bf16 v[106:109], v[82:85], v[162:165], v[106:109]
	v_mfma_f32_16x16x32_bf16 v[94:97], v[66:69], v[184:187], v[94:97]
	v_mfma_f32_16x16x32_bf16 v[90:93], v[82:85], v[184:187], v[90:93]
	v_mfma_f32_16x16x32_bf16 v[142:145], v[70:73], v[150:153], v[142:145]
	v_mfma_f32_16x16x32_bf16 v[138:141], v[86:89], v[150:153], v[138:141]
	v_mfma_f32_16x16x32_bf16 v[126:129], v[70:73], v[158:161], v[126:129]
	v_mfma_f32_16x16x32_bf16 v[122:125], v[86:89], v[158:161], v[122:125]
	v_mfma_f32_16x16x32_bf16 v[110:113], v[70:73], v[180:183], v[110:113]
	v_mfma_f32_16x16x32_bf16 v[106:109], v[86:89], v[180:183], v[106:109]
	v_mfma_f32_16x16x32_bf16 v[94:97], v[70:73], v[188:191], v[94:97]
	v_mfma_f32_16x16x32_bf16 v[90:93], v[86:89], v[188:191], v[90:93]
	s_barrier
	s_add_i32 s28, 0, 0x1c000
	s_add_i32 s29, s66, s18
	v_add_u32_e32 v204, s28, v226
	v_lshl_add_u64 v[208:209], v[208:209], 0, s[86:87]
	s_mov_b32 m0, s29
	ds_read_b128 v[192:195], v204
	ds_read_b128 v[196:199], v204 offset:1024
	ds_read_b128 v[200:203], v204 offset:2048
	ds_read_b128 v[204:207], v204 offset:3072
	global_load_lds_dwordx4 v[208:209], off
	v_lshl_add_u64 v[208:209], v[228:229], 0, s[86:87]
	s_add_i32 m0, s29, 0x2000
	s_nop 0
	global_load_lds_dwordx4 v[208:209], off
	s_barrier
	s_waitcnt lgkmcnt(0)
	v_mfma_f32_16x16x32_bf16 v[134:137], v[192:195], v[146:149], v[134:137]
	v_mfma_f32_16x16x32_bf16 v[130:133], v[200:203], v[146:149], v[130:133]
	v_mfma_f32_16x16x32_bf16 v[118:121], v[192:195], v[154:157], v[118:121]
	v_mfma_f32_16x16x32_bf16 v[114:117], v[200:203], v[154:157], v[114:117]
	v_mfma_f32_16x16x32_bf16 v[102:105], v[192:195], v[162:165], v[102:105]
	v_mfma_f32_16x16x32_bf16 v[98:101], v[200:203], v[162:165], v[98:101]
	v_mfma_f32_16x16x32_bf16 v[78:81], v[192:195], v[184:187], v[78:81]
	v_mfma_f32_16x16x32_bf16 v[74:77], v[200:203], v[184:187], v[74:77]
	v_mfma_f32_16x16x32_bf16 v[134:137], v[196:199], v[150:153], v[134:137]
	v_mfma_f32_16x16x32_bf16 v[130:133], v[204:207], v[150:153], v[130:133]
	v_mfma_f32_16x16x32_bf16 v[118:121], v[196:199], v[158:161], v[118:121]
	v_mfma_f32_16x16x32_bf16 v[114:117], v[204:207], v[158:161], v[114:117]
	v_mfma_f32_16x16x32_bf16 v[102:105], v[196:199], v[180:183], v[102:105]
	v_mfma_f32_16x16x32_bf16 v[98:101], v[204:207], v[180:183], v[98:101]
	v_mfma_f32_16x16x32_bf16 v[78:81], v[196:199], v[188:191], v[78:81]
	v_mfma_f32_16x16x32_bf16 v[74:77], v[204:207], v[188:191], v[74:77]
	s_mov_b32 m0, s59
	v_lshl_add_u64 v[208:209], v[230:231], 0, s[86:87]
	s_barrier
	ds_read_b128 v[146:149], v227 offset:49152
	ds_read_b128 v[150:153], v227 offset:50176
	ds_read_b128 v[154:157], v227 offset:51200
	ds_read_b128 v[158:161], v227 offset:52224
	ds_read_b128 v[162:165], v227 offset:53248
	ds_read_b128 v[180:183], v227 offset:54272
	ds_read_b128 v[184:187], v227 offset:55296
	ds_read_b128 v[188:191], v227 offset:56320
	global_load_lds_dwordx4 v[208:209], off
	v_lshl_add_u64 v[208:209], v[232:233], 0, s[86:87]
	s_mov_b32 m0, s60
	s_nop 0
	global_load_lds_dwordx4 v[208:209], off
	s_barrier
; #define PG8_STAGE(bufoff, gbase, voff) do { _Pragma("unroll") for (int _i = 0; _i < 2; ++_i) \
;         __builtin_amdgcn_global_load_lds((const unsigned*)((const char*)(gbase) + (voff)[_i]), (LAS unsigned*)(lds + (bufoff) + ldsw + _i * 8192), 16, 0, 0); } while (0)
; #define PG8_LDA(dst, b, h) do { _Pragma("unroll") for (int m = 0; m < 4; ++m) _Pragma("unroll") for (int k = 0; k < 2; ++k) dst[m][k] = *(const LAS bf16x8*)(lds + PG8_SA(b, h) + aoff + m * 2048 + k * 1024); } while (0)
; #define PG8_MMA(ai, bj, At, Bt) do { __builtin_amdgcn_s_setprio(1); _Pragma("unroll") for (int m = 0; m < 4; ++m) _Pragma("unroll") for (int n = 0; n < 2; ++n) _Pragma("unroll") for (int k = 0; k < 2; ++k) \
;         acc[ai][bj][m][n] = __builtin_amdgcn_mfma_f32_16x16x32_bf16(Bt[n][k], At[m][k], acc[ai][bj][m][n], 0, 0, 0); __builtin_amdgcn_s_setprio(0); } while (0)
; #define PG8_WAIT_V(n) asm volatile("s_waitcnt vmcnt(" #n ")" ::: "memory")
; template <class Epi>
; __device__ __forceinline__ void gemm_phase(LAS unsigned char* lds, const Gemm g, const Epi& E) {
;     ...
;             PG8_BAR; PG8_WAIT_L(0); PG8_MMA(0, 1, At, B1); PG8_BAR;
;             PG8_LDA(At, 1, 1); PG8_STAGE(PG8_SA(1, 0), a3, voffA);
;             PG8_BAR; PG8_WAIT_L(0); PG8_MMA(1, 0, At, B0); PG8_BAR; PG8_SCHED;
;             PG8_STAGE(PG8_SB(1, 1), b3 + hstepB, voffB);
;             PG8_WAIT_V(6); PG8_BAR; PG8_MMA(1, 1, At, B1); PG8_BAR;
;         }
;     __device__ __forceinline__ void operator()(const AccT& acc, const Unit& u, int wr, int wc, int fr, int fq) const {
;     ...
;         const int row0 = mapA.src(u.pm) * 256 + wr * 64 + fr, col0 = u.pn * 256 + wc * 32 + 8 * fq;
;         const int hd = u.pn >> 1;
;         f32x4 gw[2][2]; f32x2 st[2][4];
; #pragma unroll
;         for (int bj = 0; bj < 2; ++bj) { gw[bj][0] = *(const f32x4*)(gnw + col0 + bj * 128); gw[bj][1] = *(const f32x4*)(gnw + col0 + bj * 128 + 4); }
; #pragma unroll
;         for (int ai = 0; ai < 2; ++ai)
; #pragma unroll
;             for (int m = 0; m < 4; ++m) st[ai][m] = ST[(size_t)(row0 + ai * 128 + m * 16) * 4 + hd];
; #pragma unroll
;         for (int ai = 0; ai < 2; ++ai) {
;             u32x4 yv[4][2];
; #pragma unroll
;             for (int m = 0; m < 4; ++m)
; #pragma unroll
;                 for (int bj = 0; bj < 2; ++bj) yv[m][bj] = *(const u32x4*)(Y + (size_t)(row0 + ai * 128 + m * 16) * 2048 + col0 + bj * 128);
	s_waitcnt lgkmcnt(0)
	v_mfma_f32_16x16x32_bf16 v[62:65], v[66:69], v[146:149], v[62:65]
	v_mfma_f32_16x16x32_bf16 v[58:61], v[82:85], v[146:149], v[58:61]
	v_mfma_f32_16x16x32_bf16 v[46:49], v[66:69], v[154:157], v[46:49]
	v_mfma_f32_16x16x32_bf16 v[42:45], v[82:85], v[154:157], v[42:45]
	v_mfma_f32_16x16x32_bf16 v[30:33], v[66:69], v[162:165], v[30:33]
	v_mfma_f32_16x16x32_bf16 v[26:29], v[82:85], v[162:165], v[26:29]
	v_mfma_f32_16x16x32_bf16 v[14:17], v[66:69], v[184:187], v[14:17]
	v_mfma_f32_16x16x32_bf16 v[10:13], v[82:85], v[184:187], v[10:13]
	v_mfma_f32_16x16x32_bf16 v[62:65], v[70:73], v[150:153], v[62:65]
	v_mfma_f32_16x16x32_bf16 v[58:61], v[86:89], v[150:153], v[58:61]
	v_mfma_f32_16x16x32_bf16 v[46:49], v[70:73], v[158:161], v[46:49]
	v_mfma_f32_16x16x32_bf16 v[42:45], v[86:89], v[158:161], v[42:45]
	v_mfma_f32_16x16x32_bf16 v[30:33], v[70:73], v[180:183], v[30:33]
	v_mfma_f32_16x16x32_bf16 v[26:29], v[86:89], v[180:183], v[26:29]
	v_mfma_f32_16x16x32_bf16 v[14:17], v[70:73], v[188:191], v[14:17]
	v_mfma_f32_16x16x32_bf16 v[10:13], v[86:89], v[188:191], v[10:13]
	s_barrier
	s_add_u32 s16, s16, 0x40080
	s_addc_u32 s17, s17, 0
	s_add_i32 s28, s28, s18
	v_lshl_add_u64 v[66:67], s[16:17], 0, v[170:171]
	s_mov_b32 m0, s28
	s_nop 0
	global_load_lds_dwordx4 v[66:67], off
	v_lshl_add_u64 v[66:67], s[16:17], 0, v[166:167]
	s_add_i32 m0, s28, 0x2000
	s_nop 0
	global_load_lds_dwordx4 v[66:67], off
	s_waitcnt vmcnt(6)
	s_barrier
	v_mfma_f32_16x16x32_bf16 v[54:57], v[192:195], v[146:149], v[54:57]
	v_mfma_f32_16x16x32_bf16 v[50:53], v[200:203], v[146:149], v[50:53]
	v_mfma_f32_16x16x32_bf16 v[38:41], v[192:195], v[154:157], v[38:41]
	v_mfma_f32_16x16x32_bf16 v[34:37], v[200:203], v[154:157], v[34:37]
	v_mfma_f32_16x16x32_bf16 v[22:25], v[192:195], v[162:165], v[22:25]
	v_mfma_f32_16x16x32_bf16 v[18:21], v[200:203], v[162:165], v[18:21]
	v_mfma_f32_16x16x32_bf16 v[6:9], v[192:195], v[184:187], v[6:9]
	v_mfma_f32_16x16x32_bf16 v[2:5], v[200:203], v[184:187], v[2:5]
	v_mfma_f32_16x16x32_bf16 v[54:57], v[196:199], v[150:153], v[54:57]
	v_mfma_f32_16x16x32_bf16 v[50:53], v[204:207], v[150:153], v[50:53]
	v_mfma_f32_16x16x32_bf16 v[38:41], v[196:199], v[158:161], v[38:41]
	v_mfma_f32_16x16x32_bf16 v[34:37], v[204:207], v[158:161], v[34:37]
	v_mfma_f32_16x16x32_bf16 v[22:25], v[196:199], v[180:183], v[22:25]
	v_mfma_f32_16x16x32_bf16 v[18:21], v[204:207], v[180:183], v[18:21]
	v_mfma_f32_16x16x32_bf16 v[6:9], v[196:199], v[188:191], v[6:9]
	v_mfma_f32_16x16x32_bf16 v[2:5], v[204:207], v[188:191], v[2:5]
	s_add_i32 s65, s65, 2
	s_add_u32 s14, s14, 0x100
	s_addc_u32 s15, s15, 0
	s_add_u32 s9, s9, 0x100
	s_addc_u32 s53, s53, 0
	s_cmp_gt_u32 s65, 13
	s_barrier
	s_cbranch_scc0 .LBB0_475
	v_readlane_b32 s9, v255, 27
	s_cmp_ge_i32 s52, s9
	s_cselect_b32 s9, s25, 0
	s_lshl_b32 s14, s12, 8
	v_mov_b32_e32 v148, v225
	v_mov_b32_e32 v66, v1
	s_add_i32 s9, s52, s9
	s_or_b32 s14, s14, s58
	s_lshl_b32 s9, s9, 8
	v_lshl_add_u32 v146, v66, 3, s14
	s_ashr_i32 s14, s12, 1
	s_add_i32 s9, s9, s50
	s_ashr_i32 s15, s14, 31
	v_add_u32_e32 v148, s9, v148
	s_lshl_b64 s[14:15], s[14:15], 3
	s_add_u32 s14, s26, s14
	v_ashrrev_i32_e32 v149, 31, v148
	v_add_u32_e32 v152, 16, v148
	v_add_u32_e32 v156, 32, v148
	v_add_u32_e32 v202, 48, v148
	v_ashrrev_i32_e32 v147, 31, v146
	s_addc_u32 s15, s27, s15
	v_lshlrev_b64 v[150:151], 5, v[148:149]
	v_ashrrev_i32_e32 v153, 31, v152
	v_ashrrev_i32_e32 v157, 31, v156
	v_ashrrev_i32_e32 v203, 31, v202
	v_add_u32_e32 v190, 0x80, v148
	v_lshl_add_u64 v[70:71], v[146:147], 2, s[6:7]
	v_lshl_add_u64 v[150:151], s[14:15], 0, v[150:151]
	v_lshlrev_b64 v[154:155], 5, v[152:153]
	v_lshlrev_b64 v[158:159], 5, v[156:157]
	v_lshlrev_b64 v[160:161], 5, v[202:203]
	v_ashrrev_i32_e32 v191, 31, v190
	v_add_u32_e32 v192, 0x90, v148
	v_add_u32_e32 v194, 0xa0, v148
	v_add_u32_e32 v196, 0xb0, v148
	v_lshlrev_b64 v[182:183], 1, v[146:147]
	global_load_dwordx4 v[82:85], v[70:71], off offset:16
	global_load_dwordx4 v[86:89], v[70:71], off
	global_load_dwordx4 v[66:69], v[70:71], off offset:528
	s_nop 0
	global_load_dwordx4 v[70:73], v[70:71], off offset:512
	v_lshl_add_u64 v[154:155], s[14:15], 0, v[154:155]
	v_lshl_add_u64 v[158:159], s[14:15], 0, v[158:159]
	v_lshl_add_u64 v[160:161], s[14:15], 0, v[160:161]
	global_load_dwordx2 v[240:241], v[150:151], off
	global_load_dwordx2 v[208:209], v[154:155], off
	global_load_dwordx2 v[204:205], v[158:159], off
	global_load_dwordx2 v[200:201], v[160:161], off
	v_lshlrev_b64 v[150:151], 5, v[190:191]
	v_ashrrev_i32_e32 v193, 31, v192
	v_ashrrev_i32_e32 v195, 31, v194
	v_ashrrev_i32_e32 v197, 31, v196
	v_lshl_add_u64 v[198:199], s[38:39], 0, v[182:183]
	v_lshlrev_b64 v[242:243], 12, v[148:149]
	v_lshl_add_u64 v[150:151], s[14:15], 0, v[150:151]
	v_lshlrev_b64 v[154:155], 5, v[192:193]
	v_lshlrev_b64 v[158:159], 5, v[194:195]
	v_lshlrev_b64 v[160:161], 5, v[196:197]
	v_lshl_add_u64 v[146:147], v[198:199], 0, v[242:243]
	v_lshlrev_b64 v[244:245], 12, v[152:153]
	v_lshl_add_u64 v[154:155], s[14:15], 0, v[154:155]
	v_lshl_add_u64 v[158:159], s[14:15], 0, v[158:159]
	v_lshl_add_u64 v[160:161], s[14:15], 0, v[160:161]
	global_load_dwordx2 v[188:189], v[150:151], off
	global_load_dwordx2 v[186:187], v[154:155], off
	global_load_dwordx2 v[184:185], v[158:159], off
	global_load_dwordx2 v[180:181], v[160:161], off
	global_load_dwordx4 v[228:231], v[146:147], off
	global_load_dwordx4 v[232:235], v[146:147], off offset:256
	v_lshl_add_u64 v[146:147], v[198:199], 0, v[244:245]
	v_lshlrev_b64 v[206:207], 12, v[156:157]
	global_load_dwordx4 v[236:239], v[146:147], off
	global_load_dwordx4 v[162:165], v[146:147], off offset:256
	v_lshl_add_u64 v[146:147], v[198:199], 0, v[206:207]
	v_lshlrev_b64 v[202:203], 12, v[202:203]
	global_load_dwordx4 v[158:161], v[146:147], off
	global_load_dwordx4 v[154:157], v[146:147], off offset:256
	v_lshl_add_u64 v[146:147], v[198:199], 0, v[202:203]
	global_load_dwordx4 v[150:153], v[146:147], off
	s_nop 0
	global_load_dwordx4 v[146:149], v[146:147], off offset:256
	s_waitcnt vmcnt(0)
; __device__ __forceinline__ unsigned cvt_pk_bf16(float lo, float hi) { unsigned r; asm("v_cvt_pk_bf16_f32 %0, %1, %2" : "=v"(r) : "v"(lo), "v"(hi)); return r; }
; __device__ __forceinline__ float bf_lo(unsigned u) { return __uint_as_float(u << 16); }
; __device__ __forceinline__ float bf_hi(unsigned u) { return __uint_as_float(u & 0xffff0000u); }
; __device__ __forceinline__ f32x4 silu4(f32x4 v) {
;     f32x4 e, r;
; #pragma unroll
;     for (int j = 0; j < 4; ++j) e[j] = __builtin_amdgcn_exp2f(v[j] * -1.4426950408889634f);
; #pragma unroll
;     for (int j = 0; j < 4; ++j) r[j] = __builtin_amdgcn_rcpf(1.0f + e[j]);
;     return v * r;
; }
;     __device__ __forceinline__ void operator()(const AccT& acc, const Unit& u, int wr, int wc, int fr, int fq) const {
;     ...
;             for (int m = 0; m < 4; ++m) { bf16_t* rowp = A2 + (size_t)(row0 + ai * 128 + m * 16) * 2048 + col0;
;                 const float mu = st[ai][m][0], rs = st[ai][m][1];
; #pragma unroll
;                 for (int bj = 0; bj < 2; ++bj) { const f32x4 v0 = acc[ai][bj][m][0], v1 = acc[ai][bj][m][1]; const u32x4 yw = yv[m][bj];
;                     const f32x4 y0 = (f32x4){bf_lo(yw.x), bf_hi(yw.x), bf_lo(yw.y), bf_hi(yw.y)}, y1 = (f32x4){bf_lo(yw.z), bf_hi(yw.z), bf_lo(yw.w), bf_hi(yw.w)};
;                     const f32x4 n0 = (y0 - mu) * rs * gw[bj][0], n1 = (y1 - mu) * rs * gw[bj][1];
;                     const f32x4 s0 = silu4(v0) * n0, s1 = silu4(v1) * n1;
;                     u32x4 w; w.x = cvt_pk_bf16(s0[0], s0[1]); w.y = cvt_pk_bf16(s0[2], s0[3]); w.z = cvt_pk_bf16(s1[0], s1[1]); w.w = cvt_pk_bf16(s1[2], s1[3]);
;                     *(u32x4*)(rowp + bj * 128) = w; } }
	v_lshlrev_b32_e32 v246, 16, v228
	v_and_b32_e32 v228, 0xffff0000, v228
	v_lshlrev_b32_e32 v247, 16, v229
	v_and_b32_e32 v248, 0xffff0000, v229
	v_lshlrev_b32_e32 v249, 16, v230
	v_and_b32_e32 v250, 0xffff0000, v230
	v_lshlrev_b32_e32 v251, 16, v231
	v_and_b32_e32 v252, 0xffff0000, v231
	v_sub_f32_e32 v229, v228, v240
	v_sub_f32_e32 v228, v246, v240
	v_sub_f32_e32 v231, v248, v240
	v_sub_f32_e32 v230, v247, v240
	v_sub_f32_e32 v247, v250, v240
	v_sub_f32_e32 v246, v249, v240
	v_sub_f32_e32 v249, v252, v240
	v_sub_f32_e32 v248, v251, v240
	v_mul_f32_e32 v250, 0xbfb8aa3b, v142
	v_mul_f32_e32 v251, 0xbfb8aa3b, v143
	v_mul_f32_e32 v252, 0xbfb8aa3b, v144
	v_mul_f32_e32 v253, 0xbfb8aa3b, v145
	v_exp_f32_e32 v250, v250
	v_exp_f32_e32 v251, v251
	v_exp_f32_e32 v252, v252
	v_exp_f32_e32 v253, v253
	v_add_f32_e32 v250, 1.0, v250
	v_add_f32_e32 v251, 1.0, v251
	v_add_f32_e32 v252, 1.0, v252
	v_add_f32_e32 v253, 1.0, v253
	v_rcp_f32_e32 v250, v250
	v_rcp_f32_e32 v251, v251
	v_rcp_f32_e32 v252, v252
	v_rcp_f32_e32 v253, v253
	v_pk_mul_f32 v[228:229], v[240:241], v[228:229] op_sel:[1,0]
	v_pk_mul_f32 v[142:143], v[142:143], v[250:251]
	v_mul_f32_e32 v250, 0xbfb8aa3b, v138
	v_pk_mul_f32 v[144:145], v[144:145], v[252:253]
	v_mul_f32_e32 v251, 0xbfb8aa3b, v139
	v_mul_f32_e32 v252, 0xbfb8aa3b, v140
	v_mul_f32_e32 v253, 0xbfb8aa3b, v141
	v_exp_f32_e32 v250, v250
	v_exp_f32_e32 v251, v251
	v_exp_f32_e32 v252, v252
	v_exp_f32_e32 v253, v253
	v_add_f32_e32 v250, 1.0, v250
	v_add_f32_e32 v251, 1.0, v251
	v_add_f32_e32 v252, 1.0, v252
	v_add_f32_e32 v253, 1.0, v253
	v_rcp_f32_e32 v250, v250
	v_rcp_f32_e32 v251, v251
	v_rcp_f32_e32 v252, v252
	v_rcp_f32_e32 v253, v253
	v_pk_mul_f32 v[248:249], v[240:241], v[248:249] op_sel:[1,0]
	v_pk_mul_f32 v[246:247], v[240:241], v[246:247] op_sel:[1,0]
	v_pk_mul_f32 v[230:231], v[240:241], v[230:231] op_sel:[1,0]
	v_pk_mul_f32 v[228:229], v[86:87], v[228:229]
	v_pk_mul_f32 v[246:247], v[82:83], v[246:247]
	v_pk_mul_f32 v[248:249], v[84:85], v[248:249]
	v_pk_mul_f32 v[138:139], v[138:139], v[250:251]
	v_pk_mul_f32 v[140:141], v[140:141], v[252:253]
	v_pk_mul_f32 v[230:231], v[88:89], v[230:231]
	v_pk_mul_f32 v[142:143], v[142:143], v[228:229]
	v_pk_mul_f32 v[228:229], v[140:141], v[248:249]
	v_pk_mul_f32 v[140:141], v[138:139], v[246:247]
	v_pk_mul_f32 v[144:145], v[144:145], v[230:231]
	v_cvt_pk_bf16_f32 v140, v140, v141
	v_cvt_pk_bf16_f32 v141, v228, v229
	v_mul_f32_e32 v228, 0xbfb8aa3b, v134
	v_mul_f32_e32 v229, 0xbfb8aa3b, v135
	v_mul_f32_e32 v230, 0xbfb8aa3b, v136
	v_mul_f32_e32 v231, 0xbfb8aa3b, v137
	v_exp_f32_e32 v228, v228
	v_exp_f32_e32 v229, v229
	v_exp_f32_e32 v230, v230
	v_exp_f32_e32 v231, v231
	v_add_f32_e32 v228, 1.0, v228
	v_add_f32_e32 v229, 1.0, v229
	v_add_f32_e32 v230, 1.0, v230
	v_add_f32_e32 v231, 1.0, v231
	v_rcp_f32_e32 v228, v228
	v_rcp_f32_e32 v229, v229
	v_rcp_f32_e32 v230, v230
	v_rcp_f32_e32 v231, v231
	v_lshl_add_u64 v[242:243], s[34:35], 0, v[242:243]
	v_pk_mul_f32 v[134:135], v[134:135], v[228:229]
	v_mul_f32_e32 v228, 0xbfb8aa3b, v130
	v_pk_mul_f32 v[136:137], v[136:137], v[230:231]
	v_mul_f32_e32 v229, 0xbfb8aa3b, v131
	v_mul_f32_e32 v230, 0xbfb8aa3b, v132
	v_mul_f32_e32 v231, 0xbfb8aa3b, v133
	v_exp_f32_e32 v228, v228
	v_exp_f32_e32 v229, v229
	v_exp_f32_e32 v230, v230
	v_exp_f32_e32 v231, v231
	v_add_f32_e32 v228, 1.0, v228
	v_add_f32_e32 v229, 1.0, v229
	v_add_f32_e32 v230, 1.0, v230
	v_add_f32_e32 v231, 1.0, v231
	v_lshl_add_u64 v[242:243], v[242:243], 0, v[182:183]
	v_cvt_pk_bf16_f32 v138, v142, v143
	v_cvt_pk_bf16_f32 v139, v144, v145
	v_rcp_f32_e32 v228, v228
	v_rcp_f32_e32 v229, v229
	v_rcp_f32_e32 v230, v230
	v_rcp_f32_e32 v231, v231
	global_store_dwordx4 v[242:243], v[138:141], off
	v_lshlrev_b32_e32 v142, 16, v234
	v_and_b32_e32 v143, 0xffff0000, v234
	v_lshlrev_b32_e32 v138, 16, v232
	v_and_b32_e32 v139, 0xffff0000, v232
	v_lshlrev_b32_e32 v140, 16, v233
	v_and_b32_e32 v141, 0xffff0000, v233
	v_lshlrev_b32_e32 v144, 16, v235
	v_and_b32_e32 v145, 0xffff0000, v235
	v_sub_f32_e32 v139, v139, v240
	v_sub_f32_e32 v138, v138, v240
	v_sub_f32_e32 v141, v141, v240
	v_sub_f32_e32 v140, v140, v240
	v_sub_f32_e32 v143, v143, v240
	v_sub_f32_e32 v142, v142, v240
	v_sub_f32_e32 v145, v145, v240
	v_sub_f32_e32 v144, v144, v240
	v_pk_mul_f32 v[140:141], v[240:241], v[140:141] op_sel:[1,0]
	v_pk_mul_f32 v[138:139], v[240:241], v[138:139] op_sel:[1,0]
	v_pk_mul_f32 v[144:145], v[240:241], v[144:145] op_sel:[1,0]
	v_pk_mul_f32 v[142:143], v[240:241], v[142:143] op_sel:[1,0]
	v_pk_mul_f32 v[138:139], v[70:71], v[138:139]
	v_pk_mul_f32 v[140:141], v[72:73], v[140:141]
	v_pk_mul_f32 v[142:143], v[66:67], v[142:143]
	v_pk_mul_f32 v[144:145], v[68:69], v[144:145]
	v_pk_mul_f32 v[130:131], v[130:131], v[228:229]
	v_pk_mul_f32 v[132:133], v[132:133], v[230:231]
	v_pk_mul_f32 v[136:137], v[136:137], v[140:141]
	v_pk_mul_f32 v[134:135], v[134:135], v[138:139]
	v_pk_mul_f32 v[138:139], v[132:133], v[144:145]
	v_pk_mul_f32 v[132:133], v[130:131], v[142:143]
	v_mul_f32_e32 v140, 0xbfb8aa3b, v126
	v_mul_f32_e32 v141, 0xbfb8aa3b, v127
	v_mul_f32_e32 v142, 0xbfb8aa3b, v128
	v_mul_f32_e32 v143, 0xbfb8aa3b, v129
	v_exp_f32_e32 v140, v140
	v_exp_f32_e32 v141, v141
	v_exp_f32_e32 v142, v142
	v_exp_f32_e32 v143, v143
	v_add_f32_e32 v140, 1.0, v140
	v_add_f32_e32 v141, 1.0, v141
	v_add_f32_e32 v142, 1.0, v142
	v_add_f32_e32 v143, 1.0, v143
	v_rcp_f32_e32 v140, v140
	v_rcp_f32_e32 v141, v141
	v_rcp_f32_e32 v142, v142
	v_rcp_f32_e32 v143, v143
	v_cvt_pk_bf16_f32 v132, v132, v133
	v_pk_mul_f32 v[126:127], v[126:127], v[140:141]
	v_mul_f32_e32 v140, 0xbfb8aa3b, v122
	v_pk_mul_f32 v[128:129], v[128:129], v[142:143]
; __device__ __forceinline__ unsigned cvt_pk_bf16(float lo, float hi) { unsigned r; asm("v_cvt_pk_bf16_f32 %0, %1, %2" : "=v"(r) : "v"(lo), "v"(hi)); return r; }
; __device__ __forceinline__ float bf_lo(unsigned u) { return __uint_as_float(u << 16); }
; __device__ __forceinline__ float bf_hi(unsigned u) { return __uint_as_float(u & 0xffff0000u); }
; __device__ __forceinline__ f32x4 silu4(f32x4 v) {
;     f32x4 e, r;
; #pragma unroll
;     for (int j = 0; j < 4; ++j) e[j] = __builtin_amdgcn_exp2f(v[j] * -1.4426950408889634f);
; #pragma unroll
;     for (int j = 0; j < 4; ++j) r[j] = __builtin_amdgcn_rcpf(1.0f + e[j]);
;     return v * r;
; }
;     __device__ __forceinline__ void operator()(const AccT& acc, const Unit& u, int wr, int wc, int fr, int fq) const {
;     ...
;             for (int m = 0; m < 4; ++m) { bf16_t* rowp = A2 + (size_t)(row0 + ai * 128 + m * 16) * 2048 + col0;
;                 const float mu = st[ai][m][0], rs = st[ai][m][1];
; #pragma unroll
;                 for (int bj = 0; bj < 2; ++bj) { const f32x4 v0 = acc[ai][bj][m][0], v1 = acc[ai][bj][m][1]; const u32x4 yw = yv[m][bj];
;                     const f32x4 y0 = (f32x4){bf_lo(yw.x), bf_hi(yw.x), bf_lo(yw.y), bf_hi(yw.y)}, y1 = (f32x4){bf_lo(yw.z), bf_hi(yw.z), bf_lo(yw.w), bf_hi(yw.w)};
;                     const f32x4 n0 = (y0 - mu) * rs * gw[bj][0], n1 = (y1 - mu) * rs * gw[bj][1];
;                     const f32x4 s0 = silu4(v0) * n0, s1 = silu4(v1) * n1;
;                     u32x4 w; w.x = cvt_pk_bf16(s0[0], s0[1]); w.y = cvt_pk_bf16(s0[2], s0[3]); w.z = cvt_pk_bf16(s1[0], s1[1]); w.w = cvt_pk_bf16(s1[2], s1[3]);
;                     *(u32x4*)(rowp + bj * 128) = w; } }
	v_mul_f32_e32 v141, 0xbfb8aa3b, v123
	v_mul_f32_e32 v142, 0xbfb8aa3b, v124
	v_mul_f32_e32 v143, 0xbfb8aa3b, v125
	v_exp_f32_e32 v140, v140
	v_exp_f32_e32 v141, v141
	v_exp_f32_e32 v142, v142
	v_exp_f32_e32 v143, v143
	v_add_f32_e32 v140, 1.0, v140
	v_add_f32_e32 v141, 1.0, v141
	v_add_f32_e32 v142, 1.0, v142
	v_add_f32_e32 v143, 1.0, v143
	v_cvt_pk_bf16_f32 v133, v138, v139
	v_rcp_f32_e32 v140, v140
	v_rcp_f32_e32 v141, v141
	v_rcp_f32_e32 v142, v142
	v_rcp_f32_e32 v143, v143
	v_cvt_pk_bf16_f32 v130, v134, v135
	v_cvt_pk_bf16_f32 v131, v136, v137
	global_store_dwordx4 v[242:243], v[130:133], off offset:256
	v_lshlrev_b32_e32 v136, 16, v238
	v_and_b32_e32 v137, 0xffff0000, v238
	v_lshlrev_b32_e32 v132, 16, v236
	v_and_b32_e32 v133, 0xffff0000, v236
	v_lshlrev_b32_e32 v138, 16, v239
	v_and_b32_e32 v139, 0xffff0000, v239
	v_lshlrev_b32_e32 v134, 16, v237
	v_and_b32_e32 v135, 0xffff0000, v237
	v_sub_f32_e32 v133, v133, v208
	v_sub_f32_e32 v132, v132, v208
	v_sub_f32_e32 v137, v137, v208
	v_sub_f32_e32 v136, v136, v208
	v_sub_f32_e32 v139, v139, v208
	v_sub_f32_e32 v138, v138, v208
	v_sub_f32_e32 v135, v135, v208
	v_sub_f32_e32 v134, v134, v208
	v_pk_mul_f32 v[132:133], v[208:209], v[132:133] op_sel:[1,0]
	v_pk_mul_f32 v[138:139], v[208:209], v[138:139] op_sel:[1,0]
	v_pk_mul_f32 v[136:137], v[208:209], v[136:137] op_sel:[1,0]
	v_pk_mul_f32 v[134:135], v[208:209], v[134:135] op_sel:[1,0]
	v_pk_mul_f32 v[132:133], v[86:87], v[132:133]
	v_pk_mul_f32 v[136:137], v[82:83], v[136:137]
	v_pk_mul_f32 v[138:139], v[84:85], v[138:139]
	v_pk_mul_f32 v[122:123], v[122:123], v[140:141]
	v_pk_mul_f32 v[124:125], v[124:125], v[142:143]
	v_pk_mul_f32 v[134:135], v[88:89], v[134:135]
	v_pk_mul_f32 v[126:127], v[126:127], v[132:133]
	v_pk_mul_f32 v[132:133], v[124:125], v[138:139]
	v_pk_mul_f32 v[124:125], v[122:123], v[136:137]
	v_pk_mul_f32 v[128:129], v[128:129], v[134:135]
	v_cvt_pk_bf16_f32 v124, v124, v125
	v_cvt_pk_bf16_f32 v125, v132, v133
	v_mul_f32_e32 v132, 0xbfb8aa3b, v118
	v_mul_f32_e32 v133, 0xbfb8aa3b, v119
	v_mul_f32_e32 v134, 0xbfb8aa3b, v120
	v_mul_f32_e32 v135, 0xbfb8aa3b, v121
	v_exp_f32_e32 v132, v132
	v_exp_f32_e32 v133, v133
	v_exp_f32_e32 v134, v134
	v_exp_f32_e32 v135, v135
	v_add_f32_e32 v132, 1.0, v132
	v_add_f32_e32 v133, 1.0, v133
	v_add_f32_e32 v134, 1.0, v134
	v_add_f32_e32 v135, 1.0, v135
	v_rcp_f32_e32 v132, v132
	v_rcp_f32_e32 v133, v133
	v_rcp_f32_e32 v134, v134
	v_rcp_f32_e32 v135, v135
	v_lshl_add_u64 v[130:131], s[34:35], 0, v[244:245]
	v_pk_mul_f32 v[118:119], v[118:119], v[132:133]
	v_mul_f32_e32 v132, 0xbfb8aa3b, v114
	v_pk_mul_f32 v[120:121], v[120:121], v[134:135]
	v_mul_f32_e32 v133, 0xbfb8aa3b, v115
	v_mul_f32_e32 v134, 0xbfb8aa3b, v116
	v_mul_f32_e32 v135, 0xbfb8aa3b, v117
	v_exp_f32_e32 v132, v132
	v_exp_f32_e32 v133, v133
	v_exp_f32_e32 v134, v134
	v_exp_f32_e32 v135, v135
	v_add_f32_e32 v132, 1.0, v132
	v_add_f32_e32 v133, 1.0, v133
	v_add_f32_e32 v134, 1.0, v134
	v_add_f32_e32 v135, 1.0, v135
	v_lshl_add_u64 v[130:131], v[130:131], 0, v[182:183]
	v_cvt_pk_bf16_f32 v122, v126, v127
	v_cvt_pk_bf16_f32 v123, v128, v129
	v_rcp_f32_e32 v132, v132
	v_rcp_f32_e32 v133, v133
	v_rcp_f32_e32 v134, v134
	v_rcp_f32_e32 v135, v135
	global_store_dwordx4 v[130:131], v[122:125], off
	v_lshlrev_b32_e32 v126, 16, v164
	v_and_b32_e32 v127, 0xffff0000, v164
	v_lshlrev_b32_e32 v122, 16, v162
	v_and_b32_e32 v123, 0xffff0000, v162
	v_lshlrev_b32_e32 v124, 16, v163
	v_and_b32_e32 v125, 0xffff0000, v163
	v_lshlrev_b32_e32 v128, 16, v165
	v_and_b32_e32 v129, 0xffff0000, v165
	v_sub_f32_e32 v123, v123, v208
	v_sub_f32_e32 v122, v122, v208
	v_sub_f32_e32 v125, v125, v208
	v_sub_f32_e32 v124, v124, v208
	v_sub_f32_e32 v127, v127, v208
	v_sub_f32_e32 v126, v126, v208
	v_sub_f32_e32 v129, v129, v208
	v_sub_f32_e32 v128, v128, v208
	v_pk_mul_f32 v[124:125], v[208:209], v[124:125] op_sel:[1,0]
	v_pk_mul_f32 v[122:123], v[208:209], v[122:123] op_sel:[1,0]
	v_pk_mul_f32 v[128:129], v[208:209], v[128:129] op_sel:[1,0]
	v_pk_mul_f32 v[126:127], v[208:209], v[126:127] op_sel:[1,0]
	v_pk_mul_f32 v[122:123], v[70:71], v[122:123]
	v_pk_mul_f32 v[124:125], v[72:73], v[124:125]
	v_pk_mul_f32 v[126:127], v[66:67], v[126:127]
	v_pk_mul_f32 v[128:129], v[68:69], v[128:129]
	v_pk_mul_f32 v[114:115], v[114:115], v[132:133]
	v_pk_mul_f32 v[116:117], v[116:117], v[134:135]
	v_pk_mul_f32 v[120:121], v[120:121], v[124:125]
	v_pk_mul_f32 v[118:119], v[118:119], v[122:123]
	v_pk_mul_f32 v[122:123], v[116:117], v[128:129]
	v_pk_mul_f32 v[116:117], v[114:115], v[126:127]
	v_mul_f32_e32 v124, 0xbfb8aa3b, v110
	v_mul_f32_e32 v125, 0xbfb8aa3b, v111
	v_mul_f32_e32 v126, 0xbfb8aa3b, v112
	v_mul_f32_e32 v127, 0xbfb8aa3b, v113
	v_exp_f32_e32 v124, v124
	v_exp_f32_e32 v125, v125
	v_exp_f32_e32 v126, v126
	v_exp_f32_e32 v127, v127
	v_add_f32_e32 v124, 1.0, v124
	v_add_f32_e32 v125, 1.0, v125
	v_add_f32_e32 v126, 1.0, v126
	v_add_f32_e32 v127, 1.0, v127
	v_rcp_f32_e32 v124, v124
	v_rcp_f32_e32 v125, v125
	v_rcp_f32_e32 v126, v126
	v_rcp_f32_e32 v127, v127
	v_cvt_pk_bf16_f32 v116, v116, v117
	v_pk_mul_f32 v[110:111], v[110:111], v[124:125]
	v_mul_f32_e32 v124, 0xbfb8aa3b, v106
	v_pk_mul_f32 v[112:113], v[112:113], v[126:127]
	v_mul_f32_e32 v125, 0xbfb8aa3b, v107
	v_mul_f32_e32 v126, 0xbfb8aa3b, v108
	v_mul_f32_e32 v127, 0xbfb8aa3b, v109
	v_exp_f32_e32 v124, v124
	v_exp_f32_e32 v125, v125
	v_exp_f32_e32 v126, v126
	v_exp_f32_e32 v127, v127
	v_add_f32_e32 v124, 1.0, v124
	v_add_f32_e32 v125, 1.0, v125
	v_add_f32_e32 v126, 1.0, v126
	v_add_f32_e32 v127, 1.0, v127
	v_cvt_pk_bf16_f32 v117, v122, v123
	v_rcp_f32_e32 v124, v124
	v_rcp_f32_e32 v125, v125
	v_rcp_f32_e32 v126, v126
; __device__ __forceinline__ unsigned cvt_pk_bf16(float lo, float hi) { unsigned r; asm("v_cvt_pk_bf16_f32 %0, %1, %2" : "=v"(r) : "v"(lo), "v"(hi)); return r; }
; __device__ __forceinline__ float bf_lo(unsigned u) { return __uint_as_float(u << 16); }
; __device__ __forceinline__ float bf_hi(unsigned u) { return __uint_as_float(u & 0xffff0000u); }
; __device__ __forceinline__ f32x4 silu4(f32x4 v) {
;     f32x4 e, r;
; #pragma unroll
;     for (int j = 0; j < 4; ++j) e[j] = __builtin_amdgcn_exp2f(v[j] * -1.4426950408889634f);
; #pragma unroll
;     for (int j = 0; j < 4; ++j) r[j] = __builtin_amdgcn_rcpf(1.0f + e[j]);
;     return v * r;
; }
;     __device__ __forceinline__ void operator()(const AccT& acc, const Unit& u, int wr, int wc, int fr, int fq) const {
;     ...
;             for (int m = 0; m < 4; ++m) { bf16_t* rowp = A2 + (size_t)(row0 + ai * 128 + m * 16) * 2048 + col0;
;                 const float mu = st[ai][m][0], rs = st[ai][m][1];
; #pragma unroll
;                 for (int bj = 0; bj < 2; ++bj) { const f32x4 v0 = acc[ai][bj][m][0], v1 = acc[ai][bj][m][1]; const u32x4 yw = yv[m][bj];
;                     const f32x4 y0 = (f32x4){bf_lo(yw.x), bf_hi(yw.x), bf_lo(yw.y), bf_hi(yw.y)}, y1 = (f32x4){bf_lo(yw.z), bf_hi(yw.z), bf_lo(yw.w), bf_hi(yw.w)};
;                     const f32x4 n0 = (y0 - mu) * rs * gw[bj][0], n1 = (y1 - mu) * rs * gw[bj][1];
;                     const f32x4 s0 = silu4(v0) * n0, s1 = silu4(v1) * n1;
;                     u32x4 w; w.x = cvt_pk_bf16(s0[0], s0[1]); w.y = cvt_pk_bf16(s0[2], s0[3]); w.z = cvt_pk_bf16(s1[0], s1[1]); w.w = cvt_pk_bf16(s1[2], s1[3]);
;                     *(u32x4*)(rowp + bj * 128) = w; } }
	v_rcp_f32_e32 v127, v127
	v_cvt_pk_bf16_f32 v114, v118, v119
	v_cvt_pk_bf16_f32 v115, v120, v121
	global_store_dwordx4 v[130:131], v[114:117], off offset:256
	v_lshlrev_b32_e32 v120, 16, v160
	v_and_b32_e32 v121, 0xffff0000, v160
	v_lshlrev_b32_e32 v116, 16, v158
	v_and_b32_e32 v117, 0xffff0000, v158
	v_lshlrev_b32_e32 v122, 16, v161
	v_and_b32_e32 v123, 0xffff0000, v161
	v_lshlrev_b32_e32 v118, 16, v159
	v_and_b32_e32 v119, 0xffff0000, v159
	v_sub_f32_e32 v117, v117, v204
	v_sub_f32_e32 v116, v116, v204
	v_sub_f32_e32 v121, v121, v204
	v_sub_f32_e32 v120, v120, v204
	v_sub_f32_e32 v123, v123, v204
	v_sub_f32_e32 v122, v122, v204
	v_sub_f32_e32 v119, v119, v204
	v_sub_f32_e32 v118, v118, v204
	v_pk_mul_f32 v[116:117], v[204:205], v[116:117] op_sel:[1,0]
	v_pk_mul_f32 v[122:123], v[204:205], v[122:123] op_sel:[1,0]
	v_pk_mul_f32 v[120:121], v[204:205], v[120:121] op_sel:[1,0]
	v_pk_mul_f32 v[118:119], v[204:205], v[118:119] op_sel:[1,0]
	v_pk_mul_f32 v[116:117], v[86:87], v[116:117]
	v_pk_mul_f32 v[120:121], v[82:83], v[120:121]
	v_pk_mul_f32 v[122:123], v[84:85], v[122:123]
	v_pk_mul_f32 v[106:107], v[106:107], v[124:125]
	v_pk_mul_f32 v[108:109], v[108:109], v[126:127]
	v_pk_mul_f32 v[118:119], v[88:89], v[118:119]
	v_pk_mul_f32 v[110:111], v[110:111], v[116:117]
	v_pk_mul_f32 v[116:117], v[108:109], v[122:123]
	v_pk_mul_f32 v[108:109], v[106:107], v[120:121]
	v_pk_mul_f32 v[112:113], v[112:113], v[118:119]
	v_cvt_pk_bf16_f32 v108, v108, v109
	v_cvt_pk_bf16_f32 v109, v116, v117
	v_mul_f32_e32 v116, 0xbfb8aa3b, v102
	v_mul_f32_e32 v117, 0xbfb8aa3b, v103
	v_mul_f32_e32 v118, 0xbfb8aa3b, v104
	v_mul_f32_e32 v119, 0xbfb8aa3b, v105
	v_exp_f32_e32 v116, v116
	v_exp_f32_e32 v117, v117
	v_exp_f32_e32 v118, v118
	v_exp_f32_e32 v119, v119
	v_add_f32_e32 v116, 1.0, v116
	v_add_f32_e32 v117, 1.0, v117
	v_add_f32_e32 v118, 1.0, v118
	v_add_f32_e32 v119, 1.0, v119
	v_rcp_f32_e32 v116, v116
	v_rcp_f32_e32 v117, v117
	v_rcp_f32_e32 v118, v118
	v_rcp_f32_e32 v119, v119
	v_lshl_add_u64 v[114:115], s[34:35], 0, v[206:207]
	v_pk_mul_f32 v[102:103], v[102:103], v[116:117]
	v_mul_f32_e32 v116, 0xbfb8aa3b, v98
	v_pk_mul_f32 v[104:105], v[104:105], v[118:119]
	v_mul_f32_e32 v117, 0xbfb8aa3b, v99
	v_mul_f32_e32 v118, 0xbfb8aa3b, v100
	v_mul_f32_e32 v119, 0xbfb8aa3b, v101
	v_exp_f32_e32 v116, v116
	v_exp_f32_e32 v117, v117
	v_exp_f32_e32 v118, v118
	v_exp_f32_e32 v119, v119
	v_add_f32_e32 v116, 1.0, v116
	v_add_f32_e32 v117, 1.0, v117
	v_add_f32_e32 v118, 1.0, v118
	v_add_f32_e32 v119, 1.0, v119
	v_lshl_add_u64 v[114:115], v[114:115], 0, v[182:183]
	v_cvt_pk_bf16_f32 v106, v110, v111
	v_cvt_pk_bf16_f32 v107, v112, v113
	v_rcp_f32_e32 v116, v116
	v_rcp_f32_e32 v117, v117
	v_rcp_f32_e32 v118, v118
	v_rcp_f32_e32 v119, v119
	global_store_dwordx4 v[114:115], v[106:109], off
	v_lshlrev_b32_e32 v110, 16, v156
	v_and_b32_e32 v111, 0xffff0000, v156
	v_lshlrev_b32_e32 v106, 16, v154
	v_and_b32_e32 v107, 0xffff0000, v154
	v_lshlrev_b32_e32 v108, 16, v155
	v_and_b32_e32 v109, 0xffff0000, v155
	v_lshlrev_b32_e32 v112, 16, v157
	v_and_b32_e32 v113, 0xffff0000, v157
	v_sub_f32_e32 v107, v107, v204
	v_sub_f32_e32 v106, v106, v204
	v_sub_f32_e32 v109, v109, v204
	v_sub_f32_e32 v108, v108, v204
	v_sub_f32_e32 v111, v111, v204
	v_sub_f32_e32 v110, v110, v204
	v_sub_f32_e32 v113, v113, v204
	v_sub_f32_e32 v112, v112, v204
	v_pk_mul_f32 v[108:109], v[204:205], v[108:109] op_sel:[1,0]
	v_pk_mul_f32 v[106:107], v[204:205], v[106:107] op_sel:[1,0]
	v_pk_mul_f32 v[112:113], v[204:205], v[112:113] op_sel:[1,0]
	v_pk_mul_f32 v[110:111], v[204:205], v[110:111] op_sel:[1,0]
	v_pk_mul_f32 v[106:107], v[70:71], v[106:107]
	v_pk_mul_f32 v[108:109], v[72:73], v[108:109]
	v_pk_mul_f32 v[110:111], v[66:67], v[110:111]
	v_pk_mul_f32 v[112:113], v[68:69], v[112:113]
	v_pk_mul_f32 v[98:99], v[98:99], v[116:117]
	v_pk_mul_f32 v[100:101], v[100:101], v[118:119]
	v_pk_mul_f32 v[104:105], v[104:105], v[108:109]
	v_pk_mul_f32 v[102:103], v[102:103], v[106:107]
	v_pk_mul_f32 v[106:107], v[100:101], v[112:113]
	v_pk_mul_f32 v[100:101], v[98:99], v[110:111]
	v_mul_f32_e32 v108, 0xbfb8aa3b, v94
	v_mul_f32_e32 v109, 0xbfb8aa3b, v95
	v_mul_f32_e32 v110, 0xbfb8aa3b, v96
	v_mul_f32_e32 v111, 0xbfb8aa3b, v97
	v_exp_f32_e32 v108, v108
	v_exp_f32_e32 v109, v109
	v_exp_f32_e32 v110, v110
	v_exp_f32_e32 v111, v111
	v_add_f32_e32 v108, 1.0, v108
	v_add_f32_e32 v109, 1.0, v109
	v_add_f32_e32 v110, 1.0, v110
	v_add_f32_e32 v111, 1.0, v111
	v_rcp_f32_e32 v108, v108
	v_rcp_f32_e32 v109, v109
	v_rcp_f32_e32 v110, v110
	v_rcp_f32_e32 v111, v111
	v_cvt_pk_bf16_f32 v100, v100, v101
	v_pk_mul_f32 v[94:95], v[94:95], v[108:109]
	v_mul_f32_e32 v108, 0xbfb8aa3b, v90
	v_pk_mul_f32 v[96:97], v[96:97], v[110:111]
	v_mul_f32_e32 v109, 0xbfb8aa3b, v91
	v_mul_f32_e32 v110, 0xbfb8aa3b, v92
	v_mul_f32_e32 v111, 0xbfb8aa3b, v93
	v_exp_f32_e32 v108, v108
	v_exp_f32_e32 v109, v109
	v_exp_f32_e32 v110, v110
	v_exp_f32_e32 v111, v111
	v_add_f32_e32 v108, 1.0, v108
	v_add_f32_e32 v109, 1.0, v109
	v_add_f32_e32 v110, 1.0, v110
	v_add_f32_e32 v111, 1.0, v111
	v_cvt_pk_bf16_f32 v101, v106, v107
	v_rcp_f32_e32 v108, v108
	v_rcp_f32_e32 v109, v109
	v_rcp_f32_e32 v110, v110
	v_rcp_f32_e32 v111, v111
	v_cvt_pk_bf16_f32 v98, v102, v103
	v_cvt_pk_bf16_f32 v99, v104, v105
	global_store_dwordx4 v[114:115], v[98:101], off offset:256
	v_lshlrev_b32_e32 v104, 16, v152
	v_and_b32_e32 v105, 0xffff0000, v152
	v_lshlrev_b32_e32 v100, 16, v150
	v_and_b32_e32 v101, 0xffff0000, v150
	v_lshlrev_b32_e32 v106, 16, v153
	v_and_b32_e32 v107, 0xffff0000, v153
	v_lshlrev_b32_e32 v102, 16, v151
	v_and_b32_e32 v103, 0xffff0000, v151
	v_sub_f32_e32 v101, v101, v200
; __device__ __forceinline__ unsigned cvt_pk_bf16(float lo, float hi) { unsigned r; asm("v_cvt_pk_bf16_f32 %0, %1, %2" : "=v"(r) : "v"(lo), "v"(hi)); return r; }
; __device__ __forceinline__ float bf_lo(unsigned u) { return __uint_as_float(u << 16); }
; __device__ __forceinline__ float bf_hi(unsigned u) { return __uint_as_float(u & 0xffff0000u); }
;     __device__ __forceinline__ void operator()(const AccT& acc, const Unit& u, int wr, int wc, int fr, int fq) const {
;     ...
;             for (int m = 0; m < 4; ++m)
; #pragma unroll
;                 for (int bj = 0; bj < 2; ++bj) yv[m][bj] = *(const u32x4*)(Y + (size_t)(row0 + ai * 128 + m * 16) * 2048 + col0 + bj * 128);
;             __builtin_amdgcn_sched_barrier(0);
; #pragma unroll
;             for (int m = 0; m < 4; ++m) { bf16_t* rowp = A2 + (size_t)(row0 + ai * 128 + m * 16) * 2048 + col0;
;                 const float mu = st[ai][m][0], rs = st[ai][m][1];
; #pragma unroll
;                 for (int bj = 0; bj < 2; ++bj) { const f32x4 v0 = acc[ai][bj][m][0], v1 = acc[ai][bj][m][1]; const u32x4 yw = yv[m][bj];
;                     const f32x4 y0 = (f32x4){bf_lo(yw.x), bf_hi(yw.x), bf_lo(yw.y), bf_hi(yw.y)}, y1 = (f32x4){bf_lo(yw.z), bf_hi(yw.z), bf_lo(yw.w), bf_hi(yw.w)};
;                     const f32x4 n0 = (y0 - mu) * rs * gw[bj][0], n1 = (y1 - mu) * rs * gw[bj][1];
;                     const f32x4 s0 = silu4(v0) * n0, s1 = silu4(v1) * n1;
;                     u32x4 w; w.x = cvt_pk_bf16(s0[0], s0[1]); w.y = cvt_pk_bf16(s0[2], s0[3]); w.z = cvt_pk_bf16(s1[0], s1[1]); w.w = cvt_pk_bf16(s1[2], s1[3]);
;                     *(u32x4*)(rowp + bj * 128) = w; } }
	v_sub_f32_e32 v100, v100, v200
	v_sub_f32_e32 v105, v105, v200
	v_sub_f32_e32 v104, v104, v200
	v_sub_f32_e32 v107, v107, v200
	v_sub_f32_e32 v106, v106, v200
	v_sub_f32_e32 v103, v103, v200
	v_sub_f32_e32 v102, v102, v200
	v_pk_mul_f32 v[100:101], v[200:201], v[100:101] op_sel:[1,0]
	v_pk_mul_f32 v[106:107], v[200:201], v[106:107] op_sel:[1,0]
	v_pk_mul_f32 v[104:105], v[200:201], v[104:105] op_sel:[1,0]
	v_pk_mul_f32 v[102:103], v[200:201], v[102:103] op_sel:[1,0]
	v_pk_mul_f32 v[100:101], v[86:87], v[100:101]
	v_pk_mul_f32 v[104:105], v[82:83], v[104:105]
	v_pk_mul_f32 v[106:107], v[84:85], v[106:107]
	v_pk_mul_f32 v[90:91], v[90:91], v[108:109]
	v_pk_mul_f32 v[92:93], v[92:93], v[110:111]
	v_pk_mul_f32 v[102:103], v[88:89], v[102:103]
	v_pk_mul_f32 v[94:95], v[94:95], v[100:101]
	v_pk_mul_f32 v[100:101], v[92:93], v[106:107]
	v_pk_mul_f32 v[92:93], v[90:91], v[104:105]
	v_pk_mul_f32 v[96:97], v[96:97], v[102:103]
	v_cvt_pk_bf16_f32 v92, v92, v93
	v_cvt_pk_bf16_f32 v93, v100, v101
	v_mul_f32_e32 v100, 0xbfb8aa3b, v78
	v_mul_f32_e32 v101, 0xbfb8aa3b, v79
	v_mul_f32_e32 v102, 0xbfb8aa3b, v80
	v_mul_f32_e32 v103, 0xbfb8aa3b, v81
	v_exp_f32_e32 v100, v100
	v_exp_f32_e32 v101, v101
	v_exp_f32_e32 v102, v102
	v_exp_f32_e32 v103, v103
	v_add_f32_e32 v100, 1.0, v100
	v_add_f32_e32 v101, 1.0, v101
	v_add_f32_e32 v102, 1.0, v102
	v_add_f32_e32 v103, 1.0, v103
	v_rcp_f32_e32 v100, v100
	v_rcp_f32_e32 v101, v101
	v_rcp_f32_e32 v102, v102
	v_rcp_f32_e32 v103, v103
	v_lshl_add_u64 v[98:99], s[34:35], 0, v[202:203]
	v_pk_mul_f32 v[78:79], v[78:79], v[100:101]
	v_mul_f32_e32 v100, 0xbfb8aa3b, v74
	v_pk_mul_f32 v[80:81], v[80:81], v[102:103]
	v_mul_f32_e32 v101, 0xbfb8aa3b, v75
	v_mul_f32_e32 v102, 0xbfb8aa3b, v76
	v_mul_f32_e32 v103, 0xbfb8aa3b, v77
	v_exp_f32_e32 v100, v100
	v_exp_f32_e32 v101, v101
	v_exp_f32_e32 v102, v102
	v_exp_f32_e32 v103, v103
	v_add_f32_e32 v100, 1.0, v100
	v_add_f32_e32 v101, 1.0, v101
	v_add_f32_e32 v102, 1.0, v102
	v_add_f32_e32 v103, 1.0, v103
	v_lshl_add_u64 v[98:99], v[98:99], 0, v[182:183]
	v_cvt_pk_bf16_f32 v90, v94, v95
	v_cvt_pk_bf16_f32 v91, v96, v97
	v_rcp_f32_e32 v100, v100
	v_rcp_f32_e32 v101, v101
	v_rcp_f32_e32 v102, v102
	v_rcp_f32_e32 v103, v103
	global_store_dwordx4 v[98:99], v[90:93], off
	v_lshlrev_b32_e32 v94, 16, v148
	v_and_b32_e32 v95, 0xffff0000, v148
	v_lshlrev_b32_e32 v90, 16, v146
	v_and_b32_e32 v91, 0xffff0000, v146
	v_lshlrev_b32_e32 v96, 16, v149
	v_and_b32_e32 v97, 0xffff0000, v149
	v_lshlrev_b32_e32 v92, 16, v147
	v_and_b32_e32 v93, 0xffff0000, v147
	v_sub_f32_e32 v91, v91, v200
	v_sub_f32_e32 v90, v90, v200
	v_sub_f32_e32 v95, v95, v200
	v_sub_f32_e32 v94, v94, v200
	v_sub_f32_e32 v97, v97, v200
	v_sub_f32_e32 v96, v96, v200
	v_sub_f32_e32 v93, v93, v200
	v_sub_f32_e32 v92, v92, v200
	v_pk_mul_f32 v[90:91], v[200:201], v[90:91] op_sel:[1,0]
	v_pk_mul_f32 v[96:97], v[200:201], v[96:97] op_sel:[1,0]
	v_pk_mul_f32 v[94:95], v[200:201], v[94:95] op_sel:[1,0]
	v_pk_mul_f32 v[92:93], v[200:201], v[92:93] op_sel:[1,0]
	v_pk_mul_f32 v[90:91], v[70:71], v[90:91]
	v_pk_mul_f32 v[94:95], v[66:67], v[94:95]
	v_pk_mul_f32 v[96:97], v[68:69], v[96:97]
	v_pk_mul_f32 v[74:75], v[74:75], v[100:101]
	v_pk_mul_f32 v[76:77], v[76:77], v[102:103]
	v_pk_mul_f32 v[92:93], v[72:73], v[92:93]
	v_pk_mul_f32 v[78:79], v[78:79], v[90:91]
	v_pk_mul_f32 v[90:91], v[76:77], v[96:97]
	v_pk_mul_f32 v[76:77], v[74:75], v[94:95]
	v_pk_mul_f32 v[80:81], v[80:81], v[92:93]
	v_cvt_pk_bf16_f32 v74, v78, v79
	v_cvt_pk_bf16_f32 v76, v76, v77
	v_cvt_pk_bf16_f32 v77, v90, v91
	s_nop 0
	v_cvt_pk_bf16_f32 v75, v80, v81
	global_store_dwordx4 v[98:99], v[74:77], off offset:256
	v_lshlrev_b64 v[118:119], 12, v[190:191]
	s_nop 0
	v_lshl_add_u64 v[74:75], v[198:199], 0, v[118:119]
	v_lshlrev_b64 v[120:121], 12, v[192:193]
	global_load_dwordx4 v[106:109], v[74:75], off
	global_load_dwordx4 v[110:113], v[74:75], off offset:256
	v_lshl_add_u64 v[74:75], v[198:199], 0, v[120:121]
	v_lshlrev_b64 v[104:105], 12, v[194:195]
	global_load_dwordx4 v[114:117], v[74:75], off
	global_load_dwordx4 v[98:101], v[74:75], off offset:256
	v_lshl_add_u64 v[74:75], v[198:199], 0, v[104:105]
	v_lshlrev_b64 v[102:103], 12, v[196:197]
	global_load_dwordx4 v[94:97], v[74:75], off
	global_load_dwordx4 v[90:93], v[74:75], off offset:256
	v_lshl_add_u64 v[74:75], v[198:199], 0, v[102:103]
	global_load_dwordx4 v[78:81], v[74:75], off
	s_nop 0
	global_load_dwordx4 v[74:77], v[74:75], off offset:256
	s_waitcnt vmcnt(0)
; __device__ __forceinline__ unsigned cvt_pk_bf16(float lo, float hi) { unsigned r; asm("v_cvt_pk_bf16_f32 %0, %1, %2" : "=v"(r) : "v"(lo), "v"(hi)); return r; }
; __device__ __forceinline__ float bf_lo(unsigned u) { return __uint_as_float(u << 16); }
; __device__ __forceinline__ float bf_hi(unsigned u) { return __uint_as_float(u & 0xffff0000u); }
; __device__ __forceinline__ f32x4 silu4(f32x4 v) {
;     f32x4 e, r;
; #pragma unroll
;     for (int j = 0; j < 4; ++j) e[j] = __builtin_amdgcn_exp2f(v[j] * -1.4426950408889634f);
; #pragma unroll
;     for (int j = 0; j < 4; ++j) r[j] = __builtin_amdgcn_rcpf(1.0f + e[j]);
;     return v * r;
; }
;     __device__ __forceinline__ void operator()(const AccT& acc, const Unit& u, int wr, int wc, int fr, int fq) const {
;     ...
;             for (int m = 0; m < 4; ++m) { bf16_t* rowp = A2 + (size_t)(row0 + ai * 128 + m * 16) * 2048 + col0;
;                 const float mu = st[ai][m][0], rs = st[ai][m][1];
; #pragma unroll
;                 for (int bj = 0; bj < 2; ++bj) { const f32x4 v0 = acc[ai][bj][m][0], v1 = acc[ai][bj][m][1]; const u32x4 yw = yv[m][bj];
;                     const f32x4 y0 = (f32x4){bf_lo(yw.x), bf_hi(yw.x), bf_lo(yw.y), bf_hi(yw.y)}, y1 = (f32x4){bf_lo(yw.z), bf_hi(yw.z), bf_lo(yw.w), bf_hi(yw.w)};
;                     const f32x4 n0 = (y0 - mu) * rs * gw[bj][0], n1 = (y1 - mu) * rs * gw[bj][1];
;                     const f32x4 s0 = silu4(v0) * n0, s1 = silu4(v1) * n1;
;                     u32x4 w; w.x = cvt_pk_bf16(s0[0], s0[1]); w.y = cvt_pk_bf16(s0[2], s0[3]); w.z = cvt_pk_bf16(s1[0], s1[1]); w.w = cvt_pk_bf16(s1[2], s1[3]);
;                     *(u32x4*)(rowp + bj * 128) = w; } }
	v_lshlrev_b32_e32 v122, 16, v106
	v_and_b32_e32 v106, 0xffff0000, v106
	v_lshlrev_b32_e32 v123, 16, v107
	v_and_b32_e32 v124, 0xffff0000, v107
	v_lshlrev_b32_e32 v125, 16, v108
	v_and_b32_e32 v126, 0xffff0000, v108
	v_lshlrev_b32_e32 v127, 16, v109
	v_and_b32_e32 v128, 0xffff0000, v109
	v_sub_f32_e32 v107, v106, v188
	v_sub_f32_e32 v106, v122, v188
	v_sub_f32_e32 v109, v124, v188
	v_sub_f32_e32 v108, v123, v188
	v_sub_f32_e32 v123, v126, v188
	v_sub_f32_e32 v122, v125, v188
	v_sub_f32_e32 v125, v128, v188
	v_sub_f32_e32 v124, v127, v188
	v_mul_f32_e32 v126, 0xbfb8aa3b, v62
	v_mul_f32_e32 v127, 0xbfb8aa3b, v63
	v_mul_f32_e32 v128, 0xbfb8aa3b, v64
	v_mul_f32_e32 v129, 0xbfb8aa3b, v65
	v_exp_f32_e32 v126, v126
	v_exp_f32_e32 v127, v127
	v_exp_f32_e32 v128, v128
	v_exp_f32_e32 v129, v129
	v_add_f32_e32 v126, 1.0, v126
	v_add_f32_e32 v127, 1.0, v127
	v_add_f32_e32 v128, 1.0, v128
	v_add_f32_e32 v129, 1.0, v129
	v_rcp_f32_e32 v126, v126
	v_rcp_f32_e32 v127, v127
	v_rcp_f32_e32 v128, v128
	v_rcp_f32_e32 v129, v129
	v_pk_mul_f32 v[106:107], v[188:189], v[106:107] op_sel:[1,0]
	v_pk_mul_f32 v[62:63], v[62:63], v[126:127]
	v_mul_f32_e32 v126, 0xbfb8aa3b, v58
	v_pk_mul_f32 v[64:65], v[64:65], v[128:129]
	v_mul_f32_e32 v127, 0xbfb8aa3b, v59
	v_mul_f32_e32 v128, 0xbfb8aa3b, v60
	v_mul_f32_e32 v129, 0xbfb8aa3b, v61
	v_exp_f32_e32 v126, v126
	v_exp_f32_e32 v127, v127
	v_exp_f32_e32 v128, v128
	v_exp_f32_e32 v129, v129
	v_add_f32_e32 v126, 1.0, v126
	v_add_f32_e32 v127, 1.0, v127
	v_add_f32_e32 v128, 1.0, v128
	v_add_f32_e32 v129, 1.0, v129
	v_rcp_f32_e32 v126, v126
	v_rcp_f32_e32 v127, v127
	v_rcp_f32_e32 v128, v128
	v_rcp_f32_e32 v129, v129
	v_pk_mul_f32 v[124:125], v[188:189], v[124:125] op_sel:[1,0]
	v_pk_mul_f32 v[122:123], v[188:189], v[122:123] op_sel:[1,0]
	v_pk_mul_f32 v[108:109], v[188:189], v[108:109] op_sel:[1,0]
	v_pk_mul_f32 v[106:107], v[86:87], v[106:107]
	v_pk_mul_f32 v[122:123], v[82:83], v[122:123]
	v_pk_mul_f32 v[124:125], v[84:85], v[124:125]
	v_pk_mul_f32 v[58:59], v[58:59], v[126:127]
	v_pk_mul_f32 v[60:61], v[60:61], v[128:129]
	v_pk_mul_f32 v[108:109], v[88:89], v[108:109]
	v_pk_mul_f32 v[62:63], v[62:63], v[106:107]
	v_pk_mul_f32 v[106:107], v[60:61], v[124:125]
	v_pk_mul_f32 v[60:61], v[58:59], v[122:123]
	v_pk_mul_f32 v[64:65], v[64:65], v[108:109]
	v_cvt_pk_bf16_f32 v60, v60, v61
	v_cvt_pk_bf16_f32 v61, v106, v107
	v_mul_f32_e32 v106, 0xbfb8aa3b, v54
	v_mul_f32_e32 v107, 0xbfb8aa3b, v55
	v_mul_f32_e32 v108, 0xbfb8aa3b, v56
	v_mul_f32_e32 v109, 0xbfb8aa3b, v57
	v_exp_f32_e32 v106, v106
	v_exp_f32_e32 v107, v107
	v_exp_f32_e32 v108, v108
	v_exp_f32_e32 v109, v109
	v_add_f32_e32 v106, 1.0, v106
	v_add_f32_e32 v107, 1.0, v107
	v_add_f32_e32 v108, 1.0, v108
	v_add_f32_e32 v109, 1.0, v109
	v_rcp_f32_e32 v106, v106
	v_rcp_f32_e32 v107, v107
	v_rcp_f32_e32 v108, v108
	v_rcp_f32_e32 v109, v109
	v_lshl_add_u64 v[118:119], s[34:35], 0, v[118:119]
	v_pk_mul_f32 v[54:55], v[54:55], v[106:107]
	v_mul_f32_e32 v106, 0xbfb8aa3b, v50
	v_pk_mul_f32 v[56:57], v[56:57], v[108:109]
	v_mul_f32_e32 v107, 0xbfb8aa3b, v51
	v_mul_f32_e32 v108, 0xbfb8aa3b, v52
	v_mul_f32_e32 v109, 0xbfb8aa3b, v53
	v_exp_f32_e32 v106, v106
	v_exp_f32_e32 v107, v107
	v_exp_f32_e32 v108, v108
	v_exp_f32_e32 v109, v109
	v_add_f32_e32 v106, 1.0, v106
	v_add_f32_e32 v107, 1.0, v107
	v_add_f32_e32 v108, 1.0, v108
	v_add_f32_e32 v109, 1.0, v109
	v_lshl_add_u64 v[118:119], v[118:119], 0, v[182:183]
	v_cvt_pk_bf16_f32 v58, v62, v63
	v_cvt_pk_bf16_f32 v59, v64, v65
	v_rcp_f32_e32 v106, v106
	v_rcp_f32_e32 v107, v107
	v_rcp_f32_e32 v108, v108
	v_rcp_f32_e32 v109, v109
	global_store_dwordx4 v[118:119], v[58:61], off
	v_lshlrev_b32_e32 v62, 16, v112
	v_and_b32_e32 v63, 0xffff0000, v112
	v_lshlrev_b32_e32 v58, 16, v110
	v_and_b32_e32 v59, 0xffff0000, v110
	v_lshlrev_b32_e32 v60, 16, v111
	v_and_b32_e32 v61, 0xffff0000, v111
	v_lshlrev_b32_e32 v64, 16, v113
	v_and_b32_e32 v65, 0xffff0000, v113
	v_sub_f32_e32 v59, v59, v188
	v_sub_f32_e32 v58, v58, v188
	v_sub_f32_e32 v61, v61, v188
	v_sub_f32_e32 v60, v60, v188
	v_sub_f32_e32 v63, v63, v188
	v_sub_f32_e32 v62, v62, v188
	v_sub_f32_e32 v65, v65, v188
	v_sub_f32_e32 v64, v64, v188
	v_pk_mul_f32 v[60:61], v[188:189], v[60:61] op_sel:[1,0]
	v_pk_mul_f32 v[58:59], v[188:189], v[58:59] op_sel:[1,0]
	v_pk_mul_f32 v[64:65], v[188:189], v[64:65] op_sel:[1,0]
	v_pk_mul_f32 v[62:63], v[188:189], v[62:63] op_sel:[1,0]
	v_pk_mul_f32 v[58:59], v[70:71], v[58:59]
	v_pk_mul_f32 v[60:61], v[72:73], v[60:61]
	v_pk_mul_f32 v[62:63], v[66:67], v[62:63]
	v_pk_mul_f32 v[64:65], v[68:69], v[64:65]
	v_pk_mul_f32 v[50:51], v[50:51], v[106:107]
	v_pk_mul_f32 v[52:53], v[52:53], v[108:109]
	v_pk_mul_f32 v[56:57], v[56:57], v[60:61]
	v_pk_mul_f32 v[54:55], v[54:55], v[58:59]
	v_pk_mul_f32 v[58:59], v[52:53], v[64:65]
	v_pk_mul_f32 v[52:53], v[50:51], v[62:63]
	v_mul_f32_e32 v60, 0xbfb8aa3b, v46
	v_mul_f32_e32 v61, 0xbfb8aa3b, v47
	v_mul_f32_e32 v62, 0xbfb8aa3b, v48
	v_mul_f32_e32 v63, 0xbfb8aa3b, v49
	v_exp_f32_e32 v60, v60
	v_exp_f32_e32 v61, v61
	v_exp_f32_e32 v62, v62
	v_exp_f32_e32 v63, v63
	v_add_f32_e32 v60, 1.0, v60
	v_add_f32_e32 v61, 1.0, v61
	v_add_f32_e32 v62, 1.0, v62
	v_add_f32_e32 v63, 1.0, v63
	v_rcp_f32_e32 v60, v60
	v_rcp_f32_e32 v61, v61
	v_rcp_f32_e32 v62, v62
	v_rcp_f32_e32 v63, v63
	v_cvt_pk_bf16_f32 v52, v52, v53
	v_pk_mul_f32 v[46:47], v[46:47], v[60:61]
	v_mul_f32_e32 v60, 0xbfb8aa3b, v42
	v_pk_mul_f32 v[48:49], v[48:49], v[62:63]
	v_mul_f32_e32 v61, 0xbfb8aa3b, v43
	v_mul_f32_e32 v62, 0xbfb8aa3b, v44
	v_mul_f32_e32 v63, 0xbfb8aa3b, v45
	v_exp_f32_e32 v60, v60
	v_exp_f32_e32 v61, v61
	v_exp_f32_e32 v62, v62
	v_exp_f32_e32 v63, v63
; __device__ __forceinline__ unsigned cvt_pk_bf16(float lo, float hi) { unsigned r; asm("v_cvt_pk_bf16_f32 %0, %1, %2" : "=v"(r) : "v"(lo), "v"(hi)); return r; }
; __device__ __forceinline__ float bf_lo(unsigned u) { return __uint_as_float(u << 16); }
; __device__ __forceinline__ float bf_hi(unsigned u) { return __uint_as_float(u & 0xffff0000u); }
;     __device__ __forceinline__ void operator()(const AccT& acc, const Unit& u, int wr, int wc, int fr, int fq) const {
;     ...
;             for (int m = 0; m < 4; ++m) { bf16_t* rowp = A2 + (size_t)(row0 + ai * 128 + m * 16) * 2048 + col0;
;                 const float mu = st[ai][m][0], rs = st[ai][m][1];
; #pragma unroll
;                 for (int bj = 0; bj < 2; ++bj) { const f32x4 v0 = acc[ai][bj][m][0], v1 = acc[ai][bj][m][1]; const u32x4 yw = yv[m][bj];
;                     const f32x4 y0 = (f32x4){bf_lo(yw.x), bf_hi(yw.x), bf_lo(yw.y), bf_hi(yw.y)}, y1 = (f32x4){bf_lo(yw.z), bf_hi(yw.z), bf_lo(yw.w), bf_hi(yw.w)};
;                     const f32x4 n0 = (y0 - mu) * rs * gw[bj][0], n1 = (y1 - mu) * rs * gw[bj][1];
;                     const f32x4 s0 = silu4(v0) * n0, s1 = silu4(v1) * n1;
;                     u32x4 w; w.x = cvt_pk_bf16(s0[0], s0[1]); w.y = cvt_pk_bf16(s0[2], s0[3]); w.z = cvt_pk_bf16(s1[0], s1[1]); w.w = cvt_pk_bf16(s1[2], s1[3]);
;                     *(u32x4*)(rowp + bj * 128) = w; } }
	v_add_f32_e32 v60, 1.0, v60
	v_add_f32_e32 v61, 1.0, v61
	v_add_f32_e32 v62, 1.0, v62
	v_add_f32_e32 v63, 1.0, v63
	v_cvt_pk_bf16_f32 v53, v58, v59
	v_rcp_f32_e32 v60, v60
	v_rcp_f32_e32 v61, v61
	v_rcp_f32_e32 v62, v62
	v_rcp_f32_e32 v63, v63
	v_cvt_pk_bf16_f32 v50, v54, v55
	v_cvt_pk_bf16_f32 v51, v56, v57
	global_store_dwordx4 v[118:119], v[50:53], off offset:256
	v_lshlrev_b32_e32 v56, 16, v116
	v_and_b32_e32 v57, 0xffff0000, v116
	v_lshlrev_b32_e32 v52, 16, v114
	v_and_b32_e32 v53, 0xffff0000, v114
	v_lshlrev_b32_e32 v58, 16, v117
	v_and_b32_e32 v59, 0xffff0000, v117
	v_lshlrev_b32_e32 v54, 16, v115
	v_and_b32_e32 v55, 0xffff0000, v115
	v_sub_f32_e32 v53, v53, v186
	v_sub_f32_e32 v52, v52, v186
	v_sub_f32_e32 v57, v57, v186
	v_sub_f32_e32 v56, v56, v186
	v_sub_f32_e32 v59, v59, v186
	v_sub_f32_e32 v58, v58, v186
	v_sub_f32_e32 v55, v55, v186
	v_sub_f32_e32 v54, v54, v186
	v_pk_mul_f32 v[52:53], v[186:187], v[52:53] op_sel:[1,0]
	v_pk_mul_f32 v[58:59], v[186:187], v[58:59] op_sel:[1,0]
	v_pk_mul_f32 v[56:57], v[186:187], v[56:57] op_sel:[1,0]
	v_pk_mul_f32 v[54:55], v[186:187], v[54:55] op_sel:[1,0]
	v_pk_mul_f32 v[52:53], v[86:87], v[52:53]
	v_pk_mul_f32 v[56:57], v[82:83], v[56:57]
	v_pk_mul_f32 v[58:59], v[84:85], v[58:59]
	v_pk_mul_f32 v[42:43], v[42:43], v[60:61]
	v_pk_mul_f32 v[44:45], v[44:45], v[62:63]
	v_pk_mul_f32 v[54:55], v[88:89], v[54:55]
	v_pk_mul_f32 v[46:47], v[46:47], v[52:53]
	v_pk_mul_f32 v[52:53], v[44:45], v[58:59]
	v_pk_mul_f32 v[44:45], v[42:43], v[56:57]
	v_pk_mul_f32 v[48:49], v[48:49], v[54:55]
	v_cvt_pk_bf16_f32 v44, v44, v45
	v_cvt_pk_bf16_f32 v45, v52, v53
	v_mul_f32_e32 v52, 0xbfb8aa3b, v38
	v_mul_f32_e32 v53, 0xbfb8aa3b, v39
	v_mul_f32_e32 v54, 0xbfb8aa3b, v40
	v_mul_f32_e32 v55, 0xbfb8aa3b, v41
	v_exp_f32_e32 v52, v52
	v_exp_f32_e32 v53, v53
	v_exp_f32_e32 v54, v54
	v_exp_f32_e32 v55, v55
	v_add_f32_e32 v52, 1.0, v52
	v_add_f32_e32 v53, 1.0, v53
	v_add_f32_e32 v54, 1.0, v54
	v_add_f32_e32 v55, 1.0, v55
	v_rcp_f32_e32 v52, v52
	v_rcp_f32_e32 v53, v53
	v_rcp_f32_e32 v54, v54
	v_rcp_f32_e32 v55, v55
	v_lshl_add_u64 v[50:51], s[34:35], 0, v[120:121]
	v_pk_mul_f32 v[38:39], v[38:39], v[52:53]
	v_mul_f32_e32 v52, 0xbfb8aa3b, v34
	v_pk_mul_f32 v[40:41], v[40:41], v[54:55]
	v_mul_f32_e32 v53, 0xbfb8aa3b, v35
	v_mul_f32_e32 v54, 0xbfb8aa3b, v36
	v_mul_f32_e32 v55, 0xbfb8aa3b, v37
	v_exp_f32_e32 v52, v52
	v_exp_f32_e32 v53, v53
	v_exp_f32_e32 v54, v54
	v_exp_f32_e32 v55, v55
	v_add_f32_e32 v52, 1.0, v52
	v_add_f32_e32 v53, 1.0, v53
	v_add_f32_e32 v54, 1.0, v54
	v_add_f32_e32 v55, 1.0, v55
	v_lshl_add_u64 v[50:51], v[50:51], 0, v[182:183]
	v_cvt_pk_bf16_f32 v42, v46, v47
	v_cvt_pk_bf16_f32 v43, v48, v49
	v_rcp_f32_e32 v52, v52
	v_rcp_f32_e32 v53, v53
	v_rcp_f32_e32 v54, v54
	v_rcp_f32_e32 v55, v55
	global_store_dwordx4 v[50:51], v[42:45], off
	v_lshlrev_b32_e32 v46, 16, v100
	v_and_b32_e32 v47, 0xffff0000, v100
	v_lshlrev_b32_e32 v42, 16, v98
	v_and_b32_e32 v43, 0xffff0000, v98
	v_lshlrev_b32_e32 v44, 16, v99
	v_and_b32_e32 v45, 0xffff0000, v99
	v_lshlrev_b32_e32 v48, 16, v101
	v_and_b32_e32 v49, 0xffff0000, v101
	v_sub_f32_e32 v43, v43, v186
	v_sub_f32_e32 v42, v42, v186
	v_sub_f32_e32 v45, v45, v186
	v_sub_f32_e32 v44, v44, v186
	v_sub_f32_e32 v47, v47, v186
	v_sub_f32_e32 v46, v46, v186
	v_sub_f32_e32 v49, v49, v186
	v_sub_f32_e32 v48, v48, v186
	v_pk_mul_f32 v[44:45], v[186:187], v[44:45] op_sel:[1,0]
	v_pk_mul_f32 v[42:43], v[186:187], v[42:43] op_sel:[1,0]
	v_pk_mul_f32 v[48:49], v[186:187], v[48:49] op_sel:[1,0]
	v_pk_mul_f32 v[46:47], v[186:187], v[46:47] op_sel:[1,0]
	v_pk_mul_f32 v[42:43], v[70:71], v[42:43]
	v_pk_mul_f32 v[44:45], v[72:73], v[44:45]
	v_pk_mul_f32 v[46:47], v[66:67], v[46:47]
	v_pk_mul_f32 v[48:49], v[68:69], v[48:49]
	v_pk_mul_f32 v[34:35], v[34:35], v[52:53]
	v_pk_mul_f32 v[36:37], v[36:37], v[54:55]
	v_pk_mul_f32 v[40:41], v[40:41], v[44:45]
	v_pk_mul_f32 v[38:39], v[38:39], v[42:43]
	v_pk_mul_f32 v[42:43], v[36:37], v[48:49]
	v_pk_mul_f32 v[36:37], v[34:35], v[46:47]
	v_mul_f32_e32 v44, 0xbfb8aa3b, v30
	v_mul_f32_e32 v45, 0xbfb8aa3b, v31
	v_mul_f32_e32 v46, 0xbfb8aa3b, v32
	v_mul_f32_e32 v47, 0xbfb8aa3b, v33
	v_exp_f32_e32 v44, v44
	v_exp_f32_e32 v45, v45
	v_exp_f32_e32 v46, v46
	v_exp_f32_e32 v47, v47
	v_add_f32_e32 v44, 1.0, v44
	v_add_f32_e32 v45, 1.0, v45
	v_add_f32_e32 v46, 1.0, v46
	v_add_f32_e32 v47, 1.0, v47
	v_rcp_f32_e32 v44, v44
	v_rcp_f32_e32 v45, v45
	v_rcp_f32_e32 v46, v46
	v_rcp_f32_e32 v47, v47
	v_cvt_pk_bf16_f32 v36, v36, v37
	v_pk_mul_f32 v[30:31], v[30:31], v[44:45]
	v_mul_f32_e32 v44, 0xbfb8aa3b, v26
	v_pk_mul_f32 v[32:33], v[32:33], v[46:47]
	v_mul_f32_e32 v45, 0xbfb8aa3b, v27
	v_mul_f32_e32 v46, 0xbfb8aa3b, v28
	v_mul_f32_e32 v47, 0xbfb8aa3b, v29
	v_exp_f32_e32 v44, v44
	v_exp_f32_e32 v45, v45
	v_exp_f32_e32 v46, v46
	v_exp_f32_e32 v47, v47
	v_add_f32_e32 v44, 1.0, v44
	v_add_f32_e32 v45, 1.0, v45
	v_add_f32_e32 v46, 1.0, v46
	v_add_f32_e32 v47, 1.0, v47
	v_cvt_pk_bf16_f32 v37, v42, v43
	v_rcp_f32_e32 v44, v44
	v_rcp_f32_e32 v45, v45
	v_rcp_f32_e32 v46, v46
	v_rcp_f32_e32 v47, v47
	v_cvt_pk_bf16_f32 v34, v38, v39
	v_cvt_pk_bf16_f32 v35, v40, v41
	global_store_dwordx4 v[50:51], v[34:37], off offset:256
	v_lshlrev_b32_e32 v40, 16, v96
	v_and_b32_e32 v41, 0xffff0000, v96
	v_lshlrev_b32_e32 v36, 16, v94
	v_and_b32_e32 v37, 0xffff0000, v94
	v_lshlrev_b32_e32 v42, 16, v97
	v_and_b32_e32 v43, 0xffff0000, v97
	v_lshlrev_b32_e32 v38, 16, v95
	v_and_b32_e32 v39, 0xffff0000, v95
	v_sub_f32_e32 v37, v37, v184
	v_sub_f32_e32 v36, v36, v184
	v_sub_f32_e32 v41, v41, v184
	v_sub_f32_e32 v40, v40, v184
	v_sub_f32_e32 v43, v43, v184
	v_sub_f32_e32 v42, v42, v184
; __device__ __forceinline__ unsigned cvt_pk_bf16(float lo, float hi) { unsigned r; asm("v_cvt_pk_bf16_f32 %0, %1, %2" : "=v"(r) : "v"(lo), "v"(hi)); return r; }
; __device__ __forceinline__ float bf_lo(unsigned u) { return __uint_as_float(u << 16); }
; __device__ __forceinline__ float bf_hi(unsigned u) { return __uint_as_float(u & 0xffff0000u); }
;     __device__ __forceinline__ void operator()(const AccT& acc, const Unit& u, int wr, int wc, int fr, int fq) const {
;     ...
;             for (int m = 0; m < 4; ++m) { bf16_t* rowp = A2 + (size_t)(row0 + ai * 128 + m * 16) * 2048 + col0;
;                 const float mu = st[ai][m][0], rs = st[ai][m][1];
; #pragma unroll
;                 for (int bj = 0; bj < 2; ++bj) { const f32x4 v0 = acc[ai][bj][m][0], v1 = acc[ai][bj][m][1]; const u32x4 yw = yv[m][bj];
;                     const f32x4 y0 = (f32x4){bf_lo(yw.x), bf_hi(yw.x), bf_lo(yw.y), bf_hi(yw.y)}, y1 = (f32x4){bf_lo(yw.z), bf_hi(yw.z), bf_lo(yw.w), bf_hi(yw.w)};
;                     const f32x4 n0 = (y0 - mu) * rs * gw[bj][0], n1 = (y1 - mu) * rs * gw[bj][1];
;                     const f32x4 s0 = silu4(v0) * n0, s1 = silu4(v1) * n1;
;                     u32x4 w; w.x = cvt_pk_bf16(s0[0], s0[1]); w.y = cvt_pk_bf16(s0[2], s0[3]); w.z = cvt_pk_bf16(s1[0], s1[1]); w.w = cvt_pk_bf16(s1[2], s1[3]);
;                     *(u32x4*)(rowp + bj * 128) = w; } }
	v_sub_f32_e32 v39, v39, v184
	v_sub_f32_e32 v38, v38, v184
	v_pk_mul_f32 v[36:37], v[184:185], v[36:37] op_sel:[1,0]
	v_pk_mul_f32 v[42:43], v[184:185], v[42:43] op_sel:[1,0]
	v_pk_mul_f32 v[40:41], v[184:185], v[40:41] op_sel:[1,0]
	v_pk_mul_f32 v[38:39], v[184:185], v[38:39] op_sel:[1,0]
	v_pk_mul_f32 v[36:37], v[86:87], v[36:37]
	v_pk_mul_f32 v[40:41], v[82:83], v[40:41]
	v_pk_mul_f32 v[42:43], v[84:85], v[42:43]
	v_pk_mul_f32 v[26:27], v[26:27], v[44:45]
	v_pk_mul_f32 v[28:29], v[28:29], v[46:47]
	v_pk_mul_f32 v[38:39], v[88:89], v[38:39]
	v_pk_mul_f32 v[30:31], v[30:31], v[36:37]
	v_pk_mul_f32 v[36:37], v[28:29], v[42:43]
	v_pk_mul_f32 v[28:29], v[26:27], v[40:41]
	v_pk_mul_f32 v[32:33], v[32:33], v[38:39]
	v_cvt_pk_bf16_f32 v28, v28, v29
	v_cvt_pk_bf16_f32 v29, v36, v37
	v_mul_f32_e32 v36, 0xbfb8aa3b, v22
	v_mul_f32_e32 v37, 0xbfb8aa3b, v23
	v_mul_f32_e32 v38, 0xbfb8aa3b, v24
	v_mul_f32_e32 v39, 0xbfb8aa3b, v25
	v_exp_f32_e32 v36, v36
	v_exp_f32_e32 v37, v37
	v_exp_f32_e32 v38, v38
	v_exp_f32_e32 v39, v39
	v_add_f32_e32 v36, 1.0, v36
	v_add_f32_e32 v37, 1.0, v37
	v_add_f32_e32 v38, 1.0, v38
	v_add_f32_e32 v39, 1.0, v39
	v_rcp_f32_e32 v36, v36
	v_rcp_f32_e32 v37, v37
	v_rcp_f32_e32 v38, v38
	v_rcp_f32_e32 v39, v39
	v_lshl_add_u64 v[34:35], s[34:35], 0, v[104:105]
	v_pk_mul_f32 v[22:23], v[22:23], v[36:37]
	v_mul_f32_e32 v36, 0xbfb8aa3b, v18
	v_pk_mul_f32 v[24:25], v[24:25], v[38:39]
	v_mul_f32_e32 v37, 0xbfb8aa3b, v19
	v_mul_f32_e32 v38, 0xbfb8aa3b, v20
	v_mul_f32_e32 v39, 0xbfb8aa3b, v21
	v_exp_f32_e32 v36, v36
	v_exp_f32_e32 v37, v37
	v_exp_f32_e32 v38, v38
	v_exp_f32_e32 v39, v39
	v_add_f32_e32 v36, 1.0, v36
	v_add_f32_e32 v37, 1.0, v37
	v_add_f32_e32 v38, 1.0, v38
	v_add_f32_e32 v39, 1.0, v39
	v_lshl_add_u64 v[34:35], v[34:35], 0, v[182:183]
	v_cvt_pk_bf16_f32 v26, v30, v31
	v_cvt_pk_bf16_f32 v27, v32, v33
	v_rcp_f32_e32 v36, v36
	v_rcp_f32_e32 v37, v37
	v_rcp_f32_e32 v38, v38
	v_rcp_f32_e32 v39, v39
	global_store_dwordx4 v[34:35], v[26:29], off
	v_lshlrev_b32_e32 v30, 16, v92
	v_and_b32_e32 v31, 0xffff0000, v92
	v_lshlrev_b32_e32 v26, 16, v90
	v_and_b32_e32 v27, 0xffff0000, v90
	v_lshlrev_b32_e32 v28, 16, v91
	v_and_b32_e32 v29, 0xffff0000, v91
	v_lshlrev_b32_e32 v32, 16, v93
	v_and_b32_e32 v33, 0xffff0000, v93
	v_sub_f32_e32 v27, v27, v184
	v_sub_f32_e32 v26, v26, v184
	v_sub_f32_e32 v29, v29, v184
	v_sub_f32_e32 v28, v28, v184
	v_sub_f32_e32 v31, v31, v184
	v_sub_f32_e32 v30, v30, v184
	v_sub_f32_e32 v33, v33, v184
	v_sub_f32_e32 v32, v32, v184
	v_pk_mul_f32 v[28:29], v[184:185], v[28:29] op_sel:[1,0]
	v_pk_mul_f32 v[26:27], v[184:185], v[26:27] op_sel:[1,0]
	v_pk_mul_f32 v[32:33], v[184:185], v[32:33] op_sel:[1,0]
	v_pk_mul_f32 v[30:31], v[184:185], v[30:31] op_sel:[1,0]
	v_pk_mul_f32 v[26:27], v[70:71], v[26:27]
	v_pk_mul_f32 v[28:29], v[72:73], v[28:29]
	v_pk_mul_f32 v[30:31], v[66:67], v[30:31]
	v_pk_mul_f32 v[32:33], v[68:69], v[32:33]
	v_pk_mul_f32 v[18:19], v[18:19], v[36:37]
	v_pk_mul_f32 v[20:21], v[20:21], v[38:39]
	v_pk_mul_f32 v[24:25], v[24:25], v[28:29]
	v_pk_mul_f32 v[22:23], v[22:23], v[26:27]
	v_pk_mul_f32 v[26:27], v[20:21], v[32:33]
	v_pk_mul_f32 v[20:21], v[18:19], v[30:31]
	v_mul_f32_e32 v28, 0xbfb8aa3b, v14
	v_mul_f32_e32 v29, 0xbfb8aa3b, v15
	v_mul_f32_e32 v30, 0xbfb8aa3b, v16
	v_mul_f32_e32 v31, 0xbfb8aa3b, v17
	v_exp_f32_e32 v28, v28
	v_exp_f32_e32 v29, v29
	v_exp_f32_e32 v30, v30
	v_exp_f32_e32 v31, v31
	v_add_f32_e32 v28, 1.0, v28
	v_add_f32_e32 v29, 1.0, v29
	v_add_f32_e32 v30, 1.0, v30
	v_add_f32_e32 v31, 1.0, v31
	v_rcp_f32_e32 v28, v28
	v_rcp_f32_e32 v29, v29
	v_rcp_f32_e32 v30, v30
	v_rcp_f32_e32 v31, v31
	v_cvt_pk_bf16_f32 v20, v20, v21
	v_pk_mul_f32 v[14:15], v[14:15], v[28:29]
	v_mul_f32_e32 v28, 0xbfb8aa3b, v10
	v_pk_mul_f32 v[16:17], v[16:17], v[30:31]
	v_mul_f32_e32 v29, 0xbfb8aa3b, v11
	v_mul_f32_e32 v30, 0xbfb8aa3b, v12
	v_mul_f32_e32 v31, 0xbfb8aa3b, v13
	v_exp_f32_e32 v28, v28
	v_exp_f32_e32 v29, v29
	v_exp_f32_e32 v30, v30
	v_exp_f32_e32 v31, v31
	v_add_f32_e32 v28, 1.0, v28
	v_add_f32_e32 v29, 1.0, v29
	v_add_f32_e32 v30, 1.0, v30
	v_add_f32_e32 v31, 1.0, v31
	v_cvt_pk_bf16_f32 v21, v26, v27
	v_rcp_f32_e32 v28, v28
	v_rcp_f32_e32 v29, v29
; __device__ __forceinline__ unsigned cvt_pk_bf16(float lo, float hi) { unsigned r; asm("v_cvt_pk_bf16_f32 %0, %1, %2" : "=v"(r) : "v"(lo), "v"(hi)); return r; }
; __device__ __forceinline__ float bf_lo(unsigned u) { return __uint_as_float(u << 16); }
; __device__ __forceinline__ float bf_hi(unsigned u) { return __uint_as_float(u & 0xffff0000u); }
; #define PG8_WAIT_V(n) asm volatile("s_waitcnt vmcnt(" #n ")" ::: "memory")
; #define PG8_BAR __builtin_amdgcn_s_barrier()
; template <class Epi>
; __device__ __forceinline__ void gemm_phase(LAS unsigned char* lds, const Gemm g, const Epi& E) {
;     ...
;         cur = nxt; cA = nA; cB = nB; ++ui;
;     }
;     PG8_WAIT_V(0);
;     if (wr == 0) PG8_BAR;
;     __device__ __forceinline__ void operator()(const AccT& acc, const Unit& u, int wr, int wc, int fr, int fq) const {
;     ...
;             for (int m = 0; m < 4; ++m) { bf16_t* rowp = A2 + (size_t)(row0 + ai * 128 + m * 16) * 2048 + col0;
;                 const float mu = st[ai][m][0], rs = st[ai][m][1];
; #pragma unroll
;                 for (int bj = 0; bj < 2; ++bj) { const f32x4 v0 = acc[ai][bj][m][0], v1 = acc[ai][bj][m][1]; const u32x4 yw = yv[m][bj];
;                     const f32x4 y0 = (f32x4){bf_lo(yw.x), bf_hi(yw.x), bf_lo(yw.y), bf_hi(yw.y)}, y1 = (f32x4){bf_lo(yw.z), bf_hi(yw.z), bf_lo(yw.w), bf_hi(yw.w)};
;                     const f32x4 n0 = (y0 - mu) * rs * gw[bj][0], n1 = (y1 - mu) * rs * gw[bj][1];
;                     const f32x4 s0 = silu4(v0) * n0, s1 = silu4(v1) * n1;
;                     u32x4 w; w.x = cvt_pk_bf16(s0[0], s0[1]); w.y = cvt_pk_bf16(s0[2], s0[3]); w.z = cvt_pk_bf16(s1[0], s1[1]); w.w = cvt_pk_bf16(s1[2], s1[3]);
;                     *(u32x4*)(rowp + bj * 128) = w; } }
	v_rcp_f32_e32 v30, v30
	v_rcp_f32_e32 v31, v31
	v_cvt_pk_bf16_f32 v18, v22, v23
	v_cvt_pk_bf16_f32 v19, v24, v25
	global_store_dwordx4 v[34:35], v[18:21], off offset:256
	v_lshlrev_b32_e32 v24, 16, v80
	v_and_b32_e32 v25, 0xffff0000, v80
	v_lshlrev_b32_e32 v20, 16, v78
	v_and_b32_e32 v21, 0xffff0000, v78
	v_lshlrev_b32_e32 v26, 16, v81
	v_and_b32_e32 v27, 0xffff0000, v81
	v_lshlrev_b32_e32 v22, 16, v79
	v_and_b32_e32 v23, 0xffff0000, v79
	v_sub_f32_e32 v21, v21, v180
	v_sub_f32_e32 v20, v20, v180
	v_sub_f32_e32 v25, v25, v180
	v_sub_f32_e32 v24, v24, v180
	v_sub_f32_e32 v27, v27, v180
	v_sub_f32_e32 v26, v26, v180
	v_sub_f32_e32 v23, v23, v180
	v_sub_f32_e32 v22, v22, v180
	v_pk_mul_f32 v[20:21], v[180:181], v[20:21] op_sel:[1,0]
	v_pk_mul_f32 v[26:27], v[180:181], v[26:27] op_sel:[1,0]
	v_pk_mul_f32 v[24:25], v[180:181], v[24:25] op_sel:[1,0]
	v_pk_mul_f32 v[22:23], v[180:181], v[22:23] op_sel:[1,0]
	v_pk_mul_f32 v[20:21], v[86:87], v[20:21]
	v_pk_mul_f32 v[24:25], v[82:83], v[24:25]
	v_pk_mul_f32 v[26:27], v[84:85], v[26:27]
	v_pk_mul_f32 v[10:11], v[10:11], v[28:29]
	v_pk_mul_f32 v[12:13], v[12:13], v[30:31]
	v_pk_mul_f32 v[22:23], v[88:89], v[22:23]
	v_pk_mul_f32 v[14:15], v[14:15], v[20:21]
	v_pk_mul_f32 v[20:21], v[12:13], v[26:27]
	v_pk_mul_f32 v[12:13], v[10:11], v[24:25]
	v_pk_mul_f32 v[16:17], v[16:17], v[22:23]
	v_cvt_pk_bf16_f32 v12, v12, v13
	v_cvt_pk_bf16_f32 v13, v20, v21
	v_mul_f32_e32 v20, 0xbfb8aa3b, v6
	v_mul_f32_e32 v21, 0xbfb8aa3b, v7
	v_mul_f32_e32 v22, 0xbfb8aa3b, v8
	v_mul_f32_e32 v23, 0xbfb8aa3b, v9
	v_exp_f32_e32 v20, v20
	v_exp_f32_e32 v21, v21
	v_exp_f32_e32 v22, v22
	v_exp_f32_e32 v23, v23
	v_add_f32_e32 v20, 1.0, v20
	v_add_f32_e32 v21, 1.0, v21
	v_add_f32_e32 v22, 1.0, v22
	v_add_f32_e32 v23, 1.0, v23
	v_rcp_f32_e32 v20, v20
	v_rcp_f32_e32 v21, v21
	v_rcp_f32_e32 v22, v22
	v_rcp_f32_e32 v23, v23
	v_lshl_add_u64 v[18:19], s[34:35], 0, v[102:103]
	v_pk_mul_f32 v[6:7], v[6:7], v[20:21]
	v_mul_f32_e32 v20, 0xbfb8aa3b, v2
	v_pk_mul_f32 v[8:9], v[8:9], v[22:23]
	v_mul_f32_e32 v21, 0xbfb8aa3b, v3
	v_mul_f32_e32 v22, 0xbfb8aa3b, v4
	v_mul_f32_e32 v23, 0xbfb8aa3b, v5
	v_exp_f32_e32 v20, v20
	v_exp_f32_e32 v21, v21
	v_exp_f32_e32 v22, v22
	v_exp_f32_e32 v23, v23
	v_add_f32_e32 v20, 1.0, v20
	v_add_f32_e32 v21, 1.0, v21
	v_add_f32_e32 v22, 1.0, v22
	v_add_f32_e32 v23, 1.0, v23
	v_lshl_add_u64 v[18:19], v[18:19], 0, v[182:183]
	v_cvt_pk_bf16_f32 v10, v14, v15
	v_cvt_pk_bf16_f32 v11, v16, v17
	v_rcp_f32_e32 v20, v20
	v_rcp_f32_e32 v21, v21
	v_rcp_f32_e32 v22, v22
	v_rcp_f32_e32 v23, v23
	global_store_dwordx4 v[18:19], v[10:13], off
	v_lshlrev_b32_e32 v14, 16, v76
	v_and_b32_e32 v15, 0xffff0000, v76
	v_lshlrev_b32_e32 v10, 16, v74
	v_and_b32_e32 v11, 0xffff0000, v74
	v_lshlrev_b32_e32 v16, 16, v77
	v_and_b32_e32 v17, 0xffff0000, v77
	v_lshlrev_b32_e32 v12, 16, v75
	v_and_b32_e32 v13, 0xffff0000, v75
	v_sub_f32_e32 v11, v11, v180
	v_sub_f32_e32 v10, v10, v180
	v_sub_f32_e32 v15, v15, v180
	v_sub_f32_e32 v14, v14, v180
	v_sub_f32_e32 v17, v17, v180
	v_sub_f32_e32 v16, v16, v180
	v_sub_f32_e32 v13, v13, v180
	v_sub_f32_e32 v12, v12, v180
	v_pk_mul_f32 v[10:11], v[180:181], v[10:11] op_sel:[1,0]
	v_pk_mul_f32 v[16:17], v[180:181], v[16:17] op_sel:[1,0]
	v_pk_mul_f32 v[14:15], v[180:181], v[14:15] op_sel:[1,0]
	v_pk_mul_f32 v[12:13], v[180:181], v[12:13] op_sel:[1,0]
	v_pk_mul_f32 v[10:11], v[70:71], v[10:11]
	v_pk_mul_f32 v[14:15], v[66:67], v[14:15]
	v_pk_mul_f32 v[16:17], v[68:69], v[16:17]
	v_pk_mul_f32 v[2:3], v[2:3], v[20:21]
	v_pk_mul_f32 v[4:5], v[4:5], v[22:23]
	v_pk_mul_f32 v[12:13], v[72:73], v[12:13]
	v_pk_mul_f32 v[6:7], v[6:7], v[10:11]
	v_pk_mul_f32 v[10:11], v[4:5], v[16:17]
	v_pk_mul_f32 v[4:5], v[2:3], v[14:15]
	v_pk_mul_f32 v[8:9], v[8:9], v[12:13]
	v_cvt_pk_bf16_f32 v2, v6, v7
	v_cvt_pk_bf16_f32 v4, v4, v5
	v_cvt_pk_bf16_f32 v5, v10, v11
	s_nop 0
	v_cvt_pk_bf16_f32 v3, v8, v9
	global_store_dwordx4 v[18:19], v[2:5], off offset:256
	s_and_b64 vcc, exec, s[2:3]
	s_mov_b32 s12, s8
	s_mov_b32 s52, s64
	s_mov_b64 s[16:17], s[4:5]
	s_mov_b64 s[14:15], s[10:11]
	s_cbranch_vccz .LBB0_470
	s_waitcnt vmcnt(0)
	s_cmpk_gt_u32 s1, 0xff
	s_cbranch_scc1 .LBB0_479
	s_barrier

; #define PG8_STAGE(bufoff, gbase, voff) do { _Pragma("unroll") for (int _i = 0; _i < 2; ++_i) \
;         __builtin_amdgcn_global_load_lds((const unsigned*)((const char*)(gbase) + (voff)[_i]), (LAS unsigned*)(lds + (bufoff) + ldsw + _i * 8192), 16, 0, 0); } while (0)
; #define PG8_LDA(dst, b, h) do { _Pragma("unroll") for (int m = 0; m < 4; ++m) _Pragma("unroll") for (int k = 0; k < 2; ++k) dst[m][k] = *(const LAS bf16x8*)(lds + PG8_SA(b, h) + aoff + m * 2048 + k * 1024); } while (0)
; #define PG8_LDB(dst, b, h) do { _Pragma("unroll") for (int n = 0; n < 2; ++n) _Pragma("unroll") for (int k = 0; k < 2; ++k) dst[n][k] = *(const LAS bf16x8*)(lds + PG8_SB(b, h) + boff + n * 2048 + k * 1024); } while (0)
; #define PG8_MMA(ai, bj, At, Bt) do { __builtin_amdgcn_s_setprio(1); _Pragma("unroll") for (int m = 0; m < 4; ++m) _Pragma("unroll") for (int n = 0; n < 2; ++n) _Pragma("unroll") for (int k = 0; k < 2; ++k) \
;         acc[ai][bj][m][n] = __builtin_amdgcn_mfma_f32_16x16x32_bf16(Bt[n][k], At[m][k], acc[ai][bj][m][n], 0, 0, 0); __builtin_amdgcn_s_setprio(0); } while (0)
; #define PG8_WAIT_L(n) asm volatile("s_waitcnt lgkmcnt(" #n ")" ::: "memory")
; #define PG8_BAR __builtin_amdgcn_s_barrier()
; #define PG8_SCHED __builtin_amdgcn_sched_barrier(0)
; template <class Epi>
; __device__ __forceinline__ void gemm_phase(LAS unsigned char* lds, const Gemm g, const Epi& E) {
;     ...
;             PG8_LDB(B0, 0, 0); PG8_SCHED; PG8_LDA(At, 0, 0); PG8_STAGE(PG8_SA(1, 1), a1 + hstepA, voffA);
;             PG8_WAIT_L(8); PG8_BAR; PG8_WAIT_L(0); PG8_MMA(0, 0, At, B0); PG8_BAR; PG8_SCHED;
;             PG8_LDB(B1, 0, 1); PG8_STAGE(PG8_SB(0, 0), b2, voffB);
;             PG8_BAR; PG8_WAIT_L(0); PG8_MMA(0, 1, At, B1); PG8_BAR;
;             PG8_LDA(At, 0, 1); PG8_STAGE(PG8_SA(0, 0), a2, voffA);
;             PG8_BAR; PG8_WAIT_L(0); PG8_MMA(1, 0, At, B0); PG8_BAR; PG8_SCHED;
.LBB0_495:
	s_add_u32 s14, s12, 0xfff80080
	s_addc_u32 s15, s13, -1
	s_add_i32 s66, 0, 0x10000
	v_add_u32_e32 v142, s66, v159
	ds_read_b128 v[130:133], v142
	ds_read_b128 v[134:137], v142 offset:1024
	ds_read_b128 v[138:141], v142 offset:2048
	ds_read_b128 v[142:145], v142 offset:3072
	s_cmp_eq_u32 s65, 28
	s_cselect_b32 s17, s9, s15
	s_cselect_b32 s16, s8, s14
	s_cselect_b32 s15, s5, s64
	s_cselect_b32 s14, s4, s7
	v_lshl_add_u64 v[192:193], s[12:13], 0, v[150:151]
	s_add_i32 m0, s11, 0xc000
	ds_read_b128 v[154:157], v160
	ds_read_b128 v[162:165], v160 offset:1024
	ds_read_b128 v[166:169], v160 offset:2048
	ds_read_b128 v[170:173], v160 offset:3072
	ds_read_b128 v[174:177], v160 offset:4096
	ds_read_b128 v[180:183], v160 offset:5120
	ds_read_b128 v[184:187], v160 offset:6144
	ds_read_b128 v[188:191], v160 offset:7168
	global_load_lds_dwordx4 v[192:193], off
	v_lshl_add_u64 v[192:193], s[12:13], 0, v[152:153]
	s_add_i32 m0, s11, 0xe000
	s_nop 0
	global_load_lds_dwordx4 v[192:193], off
	s_waitcnt lgkmcnt(8)
	s_barrier
	s_waitcnt lgkmcnt(0)
	v_mfma_f32_16x16x32_bf16 v[126:129], v[130:133], v[154:157], v[126:129]
	v_mfma_f32_16x16x32_bf16 v[122:125], v[138:141], v[154:157], v[122:125]
	v_mfma_f32_16x16x32_bf16 v[114:117], v[130:133], v[166:169], v[114:117]
	v_mfma_f32_16x16x32_bf16 v[106:109], v[138:141], v[166:169], v[106:109]
	v_mfma_f32_16x16x32_bf16 v[102:105], v[130:133], v[174:177], v[102:105]
	v_mfma_f32_16x16x32_bf16 v[90:93], v[138:141], v[174:177], v[90:93]
	v_mfma_f32_16x16x32_bf16 v[86:89], v[130:133], v[184:187], v[86:89]
	v_mfma_f32_16x16x32_bf16 v[74:77], v[138:141], v[184:187], v[74:77]
	v_mfma_f32_16x16x32_bf16 v[126:129], v[134:137], v[162:165], v[126:129]
	v_mfma_f32_16x16x32_bf16 v[122:125], v[142:145], v[162:165], v[122:125]
	v_mfma_f32_16x16x32_bf16 v[114:117], v[134:137], v[170:173], v[114:117]
	v_mfma_f32_16x16x32_bf16 v[106:109], v[142:145], v[170:173], v[106:109]
	v_mfma_f32_16x16x32_bf16 v[102:105], v[134:137], v[180:183], v[102:105]
	v_mfma_f32_16x16x32_bf16 v[90:93], v[142:145], v[180:183], v[90:93]
	v_mfma_f32_16x16x32_bf16 v[86:89], v[134:137], v[188:191], v[86:89]
	v_mfma_f32_16x16x32_bf16 v[74:77], v[142:145], v[188:191], v[74:77]
	s_barrier
	s_add_i32 s68, 0, 0x14000
	s_add_i32 s66, s66, s25
	v_add_u32_e32 v161, s68, v159
	v_lshl_add_u64 v[208:209], s[14:15], 0, v[148:149]
	s_mov_b32 m0, s66
	ds_read_b128 v[192:195], v161
	ds_read_b128 v[196:199], v161 offset:1024
	ds_read_b128 v[200:203], v161 offset:2048
	ds_read_b128 v[204:207], v161 offset:3072
	global_load_lds_dwordx4 v[208:209], off
	v_lshl_add_u64 v[226:227], s[14:15], 0, v[146:147]
	s_add_i32 m0, s66, 0x2000
	s_nop 0
	global_load_lds_dwordx4 v[226:227], off
	s_barrier
	s_waitcnt lgkmcnt(0)
	v_mfma_f32_16x16x32_bf16 v[118:121], v[192:195], v[154:157], v[118:121]
	v_mfma_f32_16x16x32_bf16 v[110:113], v[200:203], v[154:157], v[110:113]
	v_mfma_f32_16x16x32_bf16 v[98:101], v[192:195], v[166:169], v[98:101]
	v_mfma_f32_16x16x32_bf16 v[94:97], v[200:203], v[166:169], v[94:97]
	v_mfma_f32_16x16x32_bf16 v[82:85], v[192:195], v[174:177], v[82:85]
	v_mfma_f32_16x16x32_bf16 v[78:81], v[200:203], v[174:177], v[78:81]
	v_mfma_f32_16x16x32_bf16 v[70:73], v[192:195], v[184:187], v[70:73]
	v_mfma_f32_16x16x32_bf16 v[66:69], v[200:203], v[184:187], v[66:69]
	v_mfma_f32_16x16x32_bf16 v[118:121], v[196:199], v[162:165], v[118:121]
	v_mfma_f32_16x16x32_bf16 v[110:113], v[204:207], v[162:165], v[110:113]
	v_mfma_f32_16x16x32_bf16 v[98:101], v[196:199], v[170:173], v[98:101]
	v_mfma_f32_16x16x32_bf16 v[94:97], v[204:207], v[170:173], v[94:97]
	v_mfma_f32_16x16x32_bf16 v[82:85], v[196:199], v[180:183], v[82:85]
	v_mfma_f32_16x16x32_bf16 v[78:81], v[204:207], v[180:183], v[78:81]
	v_mfma_f32_16x16x32_bf16 v[70:73], v[196:199], v[188:191], v[70:73]
	v_mfma_f32_16x16x32_bf16 v[66:69], v[204:207], v[188:191], v[66:69]
	s_mov_b32 m0, s11
	v_lshl_add_u64 v[228:229], s[16:17], 0, v[148:149]
	s_barrier
	ds_read_b128 v[154:157], v160 offset:16384
	ds_read_b128 v[162:165], v160 offset:17408
	ds_read_b128 v[166:169], v160 offset:18432
	ds_read_b128 v[170:173], v160 offset:19456
	ds_read_b128 v[174:177], v160 offset:20480
	ds_read_b128 v[180:183], v160 offset:21504
	ds_read_b128 v[184:187], v160 offset:22528
	ds_read_b128 v[188:191], v160 offset:23552
	global_load_lds_dwordx4 v[228:229], off
	v_lshl_add_u64 v[230:231], s[16:17], 0, v[146:147]
	s_mov_b32 m0, s31
	s_nop 0
	global_load_lds_dwordx4 v[230:231], off
	s_barrier
	s_waitcnt lgkmcnt(0)
	v_mfma_f32_16x16x32_bf16 v[62:65], v[130:133], v[154:157], v[62:65]
	v_mfma_f32_16x16x32_bf16 v[58:61], v[138:141], v[154:157], v[58:61]
	v_mfma_f32_16x16x32_bf16 v[54:57], v[130:133], v[166:169], v[54:57]
	v_mfma_f32_16x16x32_bf16 v[42:45], v[138:141], v[166:169], v[42:45]
	v_mfma_f32_16x16x32_bf16 v[38:41], v[130:133], v[174:177], v[38:41]
	v_mfma_f32_16x16x32_bf16 v[26:29], v[138:141], v[174:177], v[26:29]
	v_mfma_f32_16x16x32_bf16 v[22:25], v[130:133], v[184:187], v[22:25]
	v_mfma_f32_16x16x32_bf16 v[10:13], v[138:141], v[184:187], v[10:13]
	v_mfma_f32_16x16x32_bf16 v[62:65], v[134:137], v[162:165], v[62:65]
	v_mfma_f32_16x16x32_bf16 v[58:61], v[142:145], v[162:165], v[58:61]
	v_mfma_f32_16x16x32_bf16 v[54:57], v[134:137], v[170:173], v[54:57]
	v_mfma_f32_16x16x32_bf16 v[42:45], v[142:145], v[170:173], v[42:45]
	v_mfma_f32_16x16x32_bf16 v[38:41], v[134:137], v[180:183], v[38:41]
	v_mfma_f32_16x16x32_bf16 v[26:29], v[142:145], v[180:183], v[26:29]
	v_mfma_f32_16x16x32_bf16 v[22:25], v[134:137], v[188:191], v[22:25]
	v_mfma_f32_16x16x32_bf16 v[10:13], v[142:145], v[188:191], v[10:13]
	s_barrier
; #define PG8_STAGE(bufoff, gbase, voff) do { _Pragma("unroll") for (int _i = 0; _i < 2; ++_i) \
;         __builtin_amdgcn_global_load_lds((const unsigned*)((const char*)(gbase) + (voff)[_i]), (LAS unsigned*)(lds + (bufoff) + ldsw + _i * 8192), 16, 0, 0); } while (0)
; #define PG8_LDA(dst, b, h) do { _Pragma("unroll") for (int m = 0; m < 4; ++m) _Pragma("unroll") for (int k = 0; k < 2; ++k) dst[m][k] = *(const LAS bf16x8*)(lds + PG8_SA(b, h) + aoff + m * 2048 + k * 1024); } while (0)
; #define PG8_LDB(dst, b, h) do { _Pragma("unroll") for (int n = 0; n < 2; ++n) _Pragma("unroll") for (int k = 0; k < 2; ++k) dst[n][k] = *(const LAS bf16x8*)(lds + PG8_SB(b, h) + boff + n * 2048 + k * 1024); } while (0)
; #define PG8_MMA(ai, bj, At, Bt) do { __builtin_amdgcn_s_setprio(1); _Pragma("unroll") for (int m = 0; m < 4; ++m) _Pragma("unroll") for (int n = 0; n < 2; ++n) _Pragma("unroll") for (int k = 0; k < 2; ++k) \
;         acc[ai][bj][m][n] = __builtin_amdgcn_mfma_f32_16x16x32_bf16(Bt[n][k], At[m][k], acc[ai][bj][m][n], 0, 0, 0); __builtin_amdgcn_s_setprio(0); } while (0)
; #define PG8_WAIT_V(n) asm volatile("s_waitcnt vmcnt(" #n ")" ::: "memory")
; #define PG8_WAIT_L(n) asm volatile("s_waitcnt lgkmcnt(" #n ")" ::: "memory")
; #define PG8_BAR __builtin_amdgcn_s_barrier()
; #define PG8_SCHED __builtin_amdgcn_sched_barrier(0)
; template <class Epi>
; __device__ __forceinline__ void gemm_phase(LAS unsigned char* lds, const Gemm g, const Epi& E) {
;     ...
;             PG8_STAGE(PG8_SB(0, 1), b2 + hstepB, voffB);
;             PG8_WAIT_V(6); PG8_BAR; PG8_MMA(1, 1, At, B1); PG8_BAR;
;             PG8_LDB(B0, 1, 0); PG8_SCHED; PG8_LDA(At, 1, 0); PG8_STAGE(PG8_SA(0, 1), a2 + hstepA, voffA);
;             PG8_WAIT_L(8); PG8_BAR; PG8_WAIT_L(0); PG8_MMA(0, 0, At, B0); PG8_BAR; PG8_SCHED;
;             PG8_LDB(B1, 1, 1); PG8_STAGE(PG8_SB(1, 0), b3, voffB);
;             PG8_BAR; PG8_WAIT_L(0); PG8_MMA(0, 1, At, B1); PG8_BAR;
;             PG8_LDA(At, 1, 1); PG8_STAGE(PG8_SA(1, 0), a3, voffA);
;             PG8_BAR; PG8_WAIT_L(0); PG8_MMA(1, 0, At, B0); PG8_BAR; PG8_SCHED;
	s_add_u32 s66, s14, 0x80000
	s_addc_u32 s67, s15, 0
	s_add_i32 s68, s68, s25
	v_lshl_add_u64 v[130:131], s[66:67], 0, v[148:149]
	s_mov_b32 m0, s68
	s_nop 0
	global_load_lds_dwordx4 v[130:131], off
	v_lshl_add_u64 v[130:131], s[66:67], 0, v[146:147]
	s_add_i32 m0, s68, 0x2000
	s_nop 0
	global_load_lds_dwordx4 v[130:131], off
	s_waitcnt vmcnt(6)
	s_barrier
	v_mfma_f32_16x16x32_bf16 v[50:53], v[192:195], v[154:157], v[50:53]
	v_mfma_f32_16x16x32_bf16 v[46:49], v[200:203], v[154:157], v[46:49]
	v_mfma_f32_16x16x32_bf16 v[34:37], v[192:195], v[166:169], v[34:37]
	v_mfma_f32_16x16x32_bf16 v[30:33], v[200:203], v[166:169], v[30:33]
	v_mfma_f32_16x16x32_bf16 v[18:21], v[192:195], v[174:177], v[18:21]
	v_mfma_f32_16x16x32_bf16 v[14:17], v[200:203], v[174:177], v[14:17]
	v_mfma_f32_16x16x32_bf16 v[6:9], v[192:195], v[184:187], v[6:9]
	v_mfma_f32_16x16x32_bf16 v[2:5], v[200:203], v[184:187], v[2:5]
	v_mfma_f32_16x16x32_bf16 v[50:53], v[196:199], v[162:165], v[50:53]
	v_mfma_f32_16x16x32_bf16 v[46:49], v[204:207], v[162:165], v[46:49]
	v_mfma_f32_16x16x32_bf16 v[34:37], v[196:199], v[170:173], v[34:37]
	v_mfma_f32_16x16x32_bf16 v[30:33], v[204:207], v[170:173], v[30:33]
	v_mfma_f32_16x16x32_bf16 v[18:21], v[196:199], v[180:183], v[18:21]
	v_mfma_f32_16x16x32_bf16 v[14:17], v[204:207], v[180:183], v[14:17]
	v_mfma_f32_16x16x32_bf16 v[6:9], v[196:199], v[188:191], v[6:9]
	v_mfma_f32_16x16x32_bf16 v[2:5], v[204:207], v[188:191], v[2:5]
	s_add_i32 s66, 0, 0x18000
	v_add_u32_e32 v142, s66, v159
	s_barrier
	ds_read_b128 v[130:133], v142
	ds_read_b128 v[134:137], v142 offset:1024
	ds_read_b128 v[138:141], v142 offset:2048
	ds_read_b128 v[142:145], v142 offset:3072
	s_add_u32 s16, s16, 0x80000
	s_addc_u32 s17, s17, 0
	s_mov_b32 m0, s36
	v_lshl_add_u64 v[192:193], s[16:17], 0, v[148:149]
	ds_read_b128 v[154:157], v160 offset:32768
	ds_read_b128 v[162:165], v160 offset:33792
	ds_read_b128 v[166:169], v160 offset:34816
	ds_read_b128 v[170:173], v160 offset:35840
	ds_read_b128 v[174:177], v160 offset:36864
	ds_read_b128 v[180:183], v160 offset:37888
	ds_read_b128 v[184:187], v160 offset:38912
	ds_read_b128 v[188:191], v160 offset:39936
	global_load_lds_dwordx4 v[192:193], off
	v_lshl_add_u64 v[192:193], s[16:17], 0, v[146:147]
	s_mov_b32 m0, s44
	s_nop 0
	global_load_lds_dwordx4 v[192:193], off
	s_waitcnt lgkmcnt(8)
	s_barrier
	s_waitcnt lgkmcnt(0)
	v_mfma_f32_16x16x32_bf16 v[126:129], v[130:133], v[154:157], v[126:129]
	v_mfma_f32_16x16x32_bf16 v[122:125], v[138:141], v[154:157], v[122:125]
	v_mfma_f32_16x16x32_bf16 v[114:117], v[130:133], v[166:169], v[114:117]
	v_mfma_f32_16x16x32_bf16 v[106:109], v[138:141], v[166:169], v[106:109]
	v_mfma_f32_16x16x32_bf16 v[102:105], v[130:133], v[174:177], v[102:105]
	v_mfma_f32_16x16x32_bf16 v[90:93], v[138:141], v[174:177], v[90:93]
	v_mfma_f32_16x16x32_bf16 v[86:89], v[130:133], v[184:187], v[86:89]
	v_mfma_f32_16x16x32_bf16 v[74:77], v[138:141], v[184:187], v[74:77]
	v_mfma_f32_16x16x32_bf16 v[126:129], v[134:137], v[162:165], v[126:129]
	v_mfma_f32_16x16x32_bf16 v[122:125], v[142:145], v[162:165], v[122:125]
	v_mfma_f32_16x16x32_bf16 v[114:117], v[134:137], v[170:173], v[114:117]
	v_mfma_f32_16x16x32_bf16 v[106:109], v[142:145], v[170:173], v[106:109]
	v_mfma_f32_16x16x32_bf16 v[102:105], v[134:137], v[180:183], v[102:105]
	v_mfma_f32_16x16x32_bf16 v[90:93], v[142:145], v[180:183], v[90:93]
	v_mfma_f32_16x16x32_bf16 v[86:89], v[134:137], v[188:191], v[86:89]
	v_mfma_f32_16x16x32_bf16 v[74:77], v[142:145], v[188:191], v[74:77]
	s_barrier
	s_add_i32 s16, 0, 0x1c000
	s_add_i32 s17, s66, s25
	v_add_u32_e32 v161, s16, v159
	v_lshl_add_u64 v[208:209], v[208:209], 0, s[86:87]
	s_mov_b32 m0, s17
	ds_read_b128 v[192:195], v161
	ds_read_b128 v[196:199], v161 offset:1024
	ds_read_b128 v[200:203], v161 offset:2048
	ds_read_b128 v[204:207], v161 offset:3072
	global_load_lds_dwordx4 v[208:209], off
	v_lshl_add_u64 v[208:209], v[226:227], 0, s[86:87]
	s_add_i32 m0, s17, 0x2000
	s_nop 0
	global_load_lds_dwordx4 v[208:209], off
	s_barrier
	s_waitcnt lgkmcnt(0)
	v_mfma_f32_16x16x32_bf16 v[118:121], v[192:195], v[154:157], v[118:121]
	v_mfma_f32_16x16x32_bf16 v[110:113], v[200:203], v[154:157], v[110:113]
	v_mfma_f32_16x16x32_bf16 v[98:101], v[192:195], v[166:169], v[98:101]
	v_mfma_f32_16x16x32_bf16 v[94:97], v[200:203], v[166:169], v[94:97]
	v_mfma_f32_16x16x32_bf16 v[82:85], v[192:195], v[174:177], v[82:85]
	v_mfma_f32_16x16x32_bf16 v[78:81], v[200:203], v[174:177], v[78:81]
	v_mfma_f32_16x16x32_bf16 v[70:73], v[192:195], v[184:187], v[70:73]
	v_mfma_f32_16x16x32_bf16 v[66:69], v[200:203], v[184:187], v[66:69]
	v_mfma_f32_16x16x32_bf16 v[118:121], v[196:199], v[162:165], v[118:121]
	v_mfma_f32_16x16x32_bf16 v[110:113], v[204:207], v[162:165], v[110:113]
	v_mfma_f32_16x16x32_bf16 v[98:101], v[196:199], v[170:173], v[98:101]
	v_mfma_f32_16x16x32_bf16 v[94:97], v[204:207], v[170:173], v[94:97]
	v_mfma_f32_16x16x32_bf16 v[82:85], v[196:199], v[180:183], v[82:85]
	v_mfma_f32_16x16x32_bf16 v[78:81], v[204:207], v[180:183], v[78:81]
	v_mfma_f32_16x16x32_bf16 v[70:73], v[196:199], v[188:191], v[70:73]
	v_mfma_f32_16x16x32_bf16 v[66:69], v[204:207], v[188:191], v[66:69]
	s_mov_b32 m0, s53
	v_lshl_add_u64 v[208:209], v[228:229], 0, s[86:87]
	s_barrier
	ds_read_b128 v[154:157], v160 offset:49152
	ds_read_b128 v[162:165], v160 offset:50176
	ds_read_b128 v[166:169], v160 offset:51200
	ds_read_b128 v[170:173], v160 offset:52224
	ds_read_b128 v[174:177], v160 offset:53248
	ds_read_b128 v[180:183], v160 offset:54272
	ds_read_b128 v[184:187], v160 offset:55296
	ds_read_b128 v[188:191], v160 offset:56320
	global_load_lds_dwordx4 v[208:209], off
	v_lshl_add_u64 v[208:209], v[230:231], 0, s[86:87]
	s_mov_b32 m0, s58
	s_nop 0
	global_load_lds_dwordx4 v[208:209], off
	s_barrier
; #define PG8_STAGE(bufoff, gbase, voff) do { _Pragma("unroll") for (int _i = 0; _i < 2; ++_i) \
;         __builtin_amdgcn_global_load_lds((const unsigned*)((const char*)(gbase) + (voff)[_i]), (LAS unsigned*)(lds + (bufoff) + ldsw + _i * 8192), 16, 0, 0); } while (0)
; #define PG8_MMA(ai, bj, At, Bt) do { __builtin_amdgcn_s_setprio(1); _Pragma("unroll") for (int m = 0; m < 4; ++m) _Pragma("unroll") for (int n = 0; n < 2; ++n) _Pragma("unroll") for (int k = 0; k < 2; ++k) \
;         acc[ai][bj][m][n] = __builtin_amdgcn_mfma_f32_16x16x32_bf16(Bt[n][k], At[m][k], acc[ai][bj][m][n], 0, 0, 0); __builtin_amdgcn_s_setprio(0); } while (0)
; #define PG8_WAIT_V(n) asm volatile("s_waitcnt vmcnt(" #n ")" ::: "memory")
; #define PG8_BAR __builtin_amdgcn_s_barrier()
; template <class Epi>
; __device__ __forceinline__ void gemm_phase(LAS unsigned char* lds, const Gemm g, const Epi& E) {
;     ...
;             PG8_STAGE(PG8_SB(1, 1), b3 + hstepB, voffB);
;             PG8_WAIT_V(6); PG8_BAR; PG8_MMA(1, 1, At, B1); PG8_BAR;
;     __device__ __forceinline__ void operator()(const AccT& acc, const Unit& u, int wr, int wc, int fr, int fq) const {
;     ...
;         const int gpm = mapA.src(u.pm);
;         const int mb = gpm < 32 ? 32 : (gpm - 32) >> 3;
;         const int row0 = gpm * 256 + wr * 64 + fr, col0 = u.pn * 256 + wc * 32 + 4 * fq;
;         const float* gp = modl + ((size_t)mb * 6 + gi) * 1024;
;         f32x4 gv[2][2];
; #pragma unroll
;         for (int bj = 0; bj < 2; ++bj)
; #pragma unroll
;             for (int n = 0; n < 2; ++n) { gv[bj][n] = *(const f32x4*)(gp + col0 + bj * 128 + n * 16); if (scale) gv[bj][n] = gv[bj][n] * *(const f32x4*)(scale + col0 + bj * 128 + n * 16); }
;         const float* sbase = (gpm < 32 ? Xc : Xl) + (size_t)row0 * 1024 + col0;
; #pragma unroll
;         for (int ai = 0; ai < 2; ++ai) {
;             f32x4 xo[4][2][2];
; #pragma unroll
;             for (int m = 0; m < 4; ++m)
; #pragma unroll
;                 for (int bj = 0; bj < 2; ++bj)
; #pragma unroll
;                     for (int n = 0; n < 2; ++n) xo[m][bj][n] = *(const f32x4*)(sbase + (size_t)(ai * 128 + m * 16) * 1024 + bj * 128 + n * 16);
	s_waitcnt lgkmcnt(0)
	v_mfma_f32_16x16x32_bf16 v[62:65], v[130:133], v[154:157], v[62:65]
	v_mfma_f32_16x16x32_bf16 v[58:61], v[138:141], v[154:157], v[58:61]
	v_mfma_f32_16x16x32_bf16 v[54:57], v[130:133], v[166:169], v[54:57]
	v_mfma_f32_16x16x32_bf16 v[42:45], v[138:141], v[166:169], v[42:45]
	v_mfma_f32_16x16x32_bf16 v[38:41], v[130:133], v[174:177], v[38:41]
	v_mfma_f32_16x16x32_bf16 v[26:29], v[138:141], v[174:177], v[26:29]
	v_mfma_f32_16x16x32_bf16 v[22:25], v[130:133], v[184:187], v[22:25]
	v_mfma_f32_16x16x32_bf16 v[10:13], v[138:141], v[184:187], v[10:13]
	v_mfma_f32_16x16x32_bf16 v[62:65], v[134:137], v[162:165], v[62:65]
	v_mfma_f32_16x16x32_bf16 v[58:61], v[142:145], v[162:165], v[58:61]
	v_mfma_f32_16x16x32_bf16 v[54:57], v[134:137], v[170:173], v[54:57]
	v_mfma_f32_16x16x32_bf16 v[42:45], v[142:145], v[170:173], v[42:45]
	v_mfma_f32_16x16x32_bf16 v[38:41], v[134:137], v[180:183], v[38:41]
	v_mfma_f32_16x16x32_bf16 v[26:29], v[142:145], v[180:183], v[26:29]
	v_mfma_f32_16x16x32_bf16 v[22:25], v[134:137], v[188:191], v[22:25]
	v_mfma_f32_16x16x32_bf16 v[10:13], v[142:145], v[188:191], v[10:13]
	s_barrier
	s_add_u32 s14, s14, 0x80080
	s_addc_u32 s15, s15, 0
	s_add_i32 s16, s16, s25
	v_lshl_add_u64 v[130:131], s[14:15], 0, v[148:149]
	s_mov_b32 m0, s16
	s_nop 0
	global_load_lds_dwordx4 v[130:131], off
	v_lshl_add_u64 v[130:131], s[14:15], 0, v[146:147]
	s_add_i32 m0, s16, 0x2000
	s_nop 0
	global_load_lds_dwordx4 v[130:131], off
	s_waitcnt vmcnt(6)
	s_barrier
	v_mfma_f32_16x16x32_bf16 v[50:53], v[192:195], v[154:157], v[50:53]
	v_mfma_f32_16x16x32_bf16 v[46:49], v[200:203], v[154:157], v[46:49]
	v_mfma_f32_16x16x32_bf16 v[34:37], v[192:195], v[166:169], v[34:37]
	v_mfma_f32_16x16x32_bf16 v[30:33], v[200:203], v[166:169], v[30:33]
	v_mfma_f32_16x16x32_bf16 v[18:21], v[192:195], v[174:177], v[18:21]
	v_mfma_f32_16x16x32_bf16 v[14:17], v[200:203], v[174:177], v[14:17]
	v_mfma_f32_16x16x32_bf16 v[6:9], v[192:195], v[184:187], v[6:9]
	v_mfma_f32_16x16x32_bf16 v[2:5], v[200:203], v[184:187], v[2:5]
	v_mfma_f32_16x16x32_bf16 v[50:53], v[196:199], v[162:165], v[50:53]
	v_mfma_f32_16x16x32_bf16 v[46:49], v[204:207], v[162:165], v[46:49]
	v_mfma_f32_16x16x32_bf16 v[34:37], v[196:199], v[170:173], v[34:37]
	v_mfma_f32_16x16x32_bf16 v[30:33], v[204:207], v[170:173], v[30:33]
	v_mfma_f32_16x16x32_bf16 v[18:21], v[196:199], v[180:183], v[18:21]
	v_mfma_f32_16x16x32_bf16 v[14:17], v[204:207], v[180:183], v[14:17]
	v_mfma_f32_16x16x32_bf16 v[6:9], v[196:199], v[188:191], v[6:9]
	v_mfma_f32_16x16x32_bf16 v[2:5], v[204:207], v[188:191], v[2:5]
	s_add_i32 s65, s65, 2
	s_add_u32 s12, s12, 0x100
	s_addc_u32 s13, s13, 0
	s_add_u32 s7, s7, 0x100
	s_addc_u32 s64, s64, 0
	s_cmp_gt_u32 s65, 29
	s_barrier
	s_cbranch_scc0 .LBB0_495
	v_readlane_b32 s7, v255, 27
	s_cmp_ge_i32 s61, s7
	s_cselect_b32 s7, s29, 0
	s_add_i32 s7, s61, s7
	s_cmp_lt_i32 s7, 32
	v_mov_b32_e32 v156, v158
	v_mov_b32_e32 v130, v1
	s_cselect_b64 s[12:13], -1, 0
	s_sub_i32 s14, s7, 32
	s_lshl_b32 s10, s10, 8
	s_ashr_i32 s14, s14, 3
	s_or_b32 s10, s10, s52
	v_lshl_add_u32 v130, v130, 2, s10
	s_mul_i32 s10, s14, 6
	s_and_b64 s[14:15], s[12:13], exec
	s_cselect_b32 s14, 0xc0, s10
	s_ashr_i32 s15, s14, 31
	s_lshl_b64 s[14:15], s[14:15], 12
	s_add_u32 s14, s88, s14
	s_addc_u32 s15, s89, s15
	s_lshl_b32 s7, s7, 8
	s_add_i32 s7, s7, s50
	v_ashrrev_i32_e32 v131, 31, v130
	v_add_u32_e32 v156, s7, v156
	s_and_b64 s[12:13], s[12:13], exec
	v_readlane_b32 s7, v255, 16
	v_readlane_b32 s10, v255, 18
	v_lshlrev_b64 v[154:155], 2, v[130:131]
	s_cselect_b32 s13, s7, s10
	v_readlane_b32 s7, v255, 17
	v_readlane_b32 s10, v255, 19
	v_ashrrev_i32_e32 v157, 31, v156
	v_lshl_add_u64 v[130:131], s[14:15], 0, v[154:155]
	s_mov_b64 s[14:15], 0x2000
	s_cselect_b32 s12, s7, s10
	v_lshlrev_b64 v[208:209], 12, v[156:157]
	v_lshl_add_u64 v[132:133], v[130:131], 0, s[14:15]
	v_add_co_u32_e32 v130, vcc, s71, v130
	v_lshl_add_u64 v[156:157], s[12:13], 0, v[208:209]
	s_nop 0
	v_addc_co_u32_e32 v131, vcc, 0, v131, vcc
	v_lshl_add_u64 v[156:157], v[156:157], 0, v[154:155]
	v_add_co_u32_e32 v192, vcc, s45, v156
	global_load_dwordx4 v[138:141], v[132:133], off offset:64
	global_load_dwordx4 v[134:137], v[132:133], off offset:512
	global_load_dwordx4 v[142:145], v[130:131], off
	s_nop 0
	global_load_dwordx4 v[130:133], v[132:133], off offset:576
	v_addc_co_u32_e32 v193, vcc, 0, v157, vcc
	v_add_co_u32_e32 v226, vcc, s19, v156
	global_load_dwordx4 v[162:165], v[156:157], off
	global_load_dwordx4 v[166:169], v[156:157], off offset:64
	global_load_dwordx4 v[170:173], v[156:157], off offset:512
	global_load_dwordx4 v[174:177], v[156:157], off offset:576
	v_addc_co_u32_e32 v227, vcc, 0, v157, vcc
	v_add_co_u32_e32 v242, vcc, s69, v156
	global_load_dwordx4 v[180:183], v[192:193], off
	global_load_dwordx4 v[184:187], v[192:193], off offset:64
	global_load_dwordx4 v[188:191], v[192:193], off offset:512
	s_nop 0
	global_load_dwordx4 v[192:195], v[192:193], off offset:576
	v_addc_co_u32_e32 v243, vcc, 0, v157, vcc
	global_load_dwordx4 v[196:199], v[226:227], off
	global_load_dwordx4 v[200:203], v[226:227], off offset:64
	global_load_dwordx4 v[204:207], v[226:227], off offset:512
	s_nop 0
	global_load_dwordx4 v[226:229], v[226:227], off offset:576
	s_nop 0
	global_load_dwordx4 v[230:233], v[242:243], off
	global_load_dwordx4 v[234:237], v[242:243], off offset:64
	global_load_dwordx4 v[238:241], v[242:243], off offset:512
	s_nop 0
	global_load_dwordx4 v[242:245], v[242:243], off offset:576
	v_readlane_b32 s12, v254, 0
	v_readlane_b32 s13, v254, 1
	s_waitcnt vmcnt(0)
;     __device__ __forceinline__ void operator()(const AccT& acc, const Unit& u, int wr, int wc, int fr, int fq) const {
;     ...
;                     for (int n = 0; n < 2; ++n) xo[m][bj][n] = *(const f32x4*)(sbase + (size_t)(ai * 128 + m * 16) * 1024 + bj * 128 + n * 16);
;             __builtin_amdgcn_sched_barrier(0);
; #pragma unroll
;             for (int m = 0; m < 4; ++m) { float* rowp = X + (size_t)(row0 + ai * 128 + m * 16) * 1024 + col0;
; #pragma unroll
;                 for (int bj = 0; bj < 2; ++bj)
; #pragma unroll
;                     for (int n = 0; n < 2; ++n) *(f32x4*)(rowp + bj * 128 + n * 16) = xo[m][bj][n] + gv[bj][n] * acc[ai][bj][m][n]; }
	v_pk_fma_f32 v[112:113], v[112:113], v[132:133], v[176:177]
	v_pk_fma_f32 v[110:111], v[110:111], v[130:131], v[174:175]
	v_lshl_add_u64 v[208:209], s[12:13], 0, v[208:209]
	v_lshl_add_u64 v[154:155], v[208:209], 0, v[154:155]
	v_pk_fma_f32 v[120:121], v[120:121], v[136:137], v[172:173]
	v_pk_fma_f32 v[118:119], v[118:119], v[134:135], v[170:171]
	global_store_dwordx4 v[154:155], v[110:113], off offset:576
	global_store_dwordx4 v[154:155], v[118:121], off offset:512
	v_pk_fma_f32 v[100:101], v[100:101], v[136:137], v[190:191]
	v_pk_fma_f32 v[110:111], v[114:115], v[142:143], v[180:181]
	v_add_co_u32_e32 v114, vcc, s45, v154
	v_lshl_add_u64 v[118:119], v[154:155], 0, s[84:85]
	s_nop 0
	v_addc_co_u32_e32 v115, vcc, 0, v155, vcc
	v_pk_fma_f32 v[98:99], v[98:99], v[134:135], v[188:189]
	global_store_dwordx4 v[118:119], v[98:101], off offset:512
	v_pk_fma_f32 v[84:85], v[84:85], v[136:137], v[206:207]
	v_pk_fma_f32 v[82:83], v[82:83], v[134:135], v[204:205]
	v_add_co_u32_e32 v100, vcc, s19, v154
	v_lshl_add_u64 v[98:99], v[154:155], 0, s[82:83]
	s_nop 0
	v_addc_co_u32_e32 v101, vcc, 0, v155, vcc
	v_pk_fma_f32 v[96:97], v[96:97], v[132:133], v[194:195]
	v_pk_fma_f32 v[94:95], v[94:95], v[130:131], v[192:193]
	global_store_dwordx4 v[98:99], v[82:85], off offset:512
	v_pk_fma_f32 v[80:81], v[80:81], v[132:133], v[228:229]
	v_pk_fma_f32 v[78:79], v[78:79], v[130:131], v[226:227]
	s_mov_b64 s[12:13], 0x30000
	v_add_co_u32_e32 v84, vcc, s69, v154
	v_pk_fma_f32 v[128:129], v[128:129], v[144:145], v[164:165]
	v_pk_fma_f32 v[126:127], v[126:127], v[142:143], v[162:163]
	v_pk_fma_f32 v[124:125], v[124:125], v[140:141], v[168:169]
	v_pk_fma_f32 v[122:123], v[122:123], v[138:139], v[166:167]
	v_pk_fma_f32 v[112:113], v[116:117], v[144:145], v[182:183]
	v_pk_fma_f32 v[108:109], v[108:109], v[140:141], v[186:187]
	v_pk_fma_f32 v[106:107], v[106:107], v[138:139], v[184:185]
	global_store_dwordx4 v[118:119], v[94:97], off offset:576
	v_pk_fma_f32 v[92:93], v[92:93], v[140:141], v[202:203]
	v_pk_fma_f32 v[90:91], v[90:91], v[138:139], v[200:201]
	v_pk_fma_f32 v[96:97], v[104:105], v[144:145], v[198:199]
	v_pk_fma_f32 v[94:95], v[102:103], v[142:143], v[196:197]
	global_store_dwordx4 v[98:99], v[78:81], off offset:576
	v_lshl_add_u64 v[82:83], v[154:155], 0, s[12:13]
	v_addc_co_u32_e32 v85, vcc, 0, v155, vcc
	v_pk_fma_f32 v[80:81], v[88:89], v[144:145], v[232:233]
	v_pk_fma_f32 v[78:79], v[86:87], v[142:143], v[230:231]
	v_pk_fma_f32 v[76:77], v[76:77], v[140:141], v[236:237]
	v_pk_fma_f32 v[74:75], v[74:75], v[138:139], v[234:235]
	v_pk_fma_f32 v[72:73], v[72:73], v[136:137], v[240:241]
	v_pk_fma_f32 v[70:71], v[70:71], v[134:135], v[238:239]
	v_pk_fma_f32 v[68:69], v[68:69], v[132:133], v[244:245]
	v_pk_fma_f32 v[66:67], v[66:67], v[130:131], v[242:243]
	global_store_dwordx4 v[154:155], v[126:129], off
	global_store_dwordx4 v[154:155], v[122:125], off offset:64
	global_store_dwordx4 v[114:115], v[110:113], off
	global_store_dwordx4 v[118:119], v[106:109], off offset:64
	global_store_dwordx4 v[100:101], v[94:97], off
	global_store_dwordx4 v[98:99], v[90:93], off offset:64
	global_store_dwordx4 v[84:85], v[78:81], off
	global_store_dwordx4 v[82:83], v[74:77], off offset:64
	global_store_dwordx4 v[82:83], v[70:73], off offset:512
	global_store_dwordx4 v[82:83], v[66:69], off offset:576
	s_mov_b32 s7, 0x80000
	v_add_co_u32_e32 v78, vcc, s7, v156
	s_mov_b32 s10, 0x90000
	s_nop 0
	v_addc_co_u32_e32 v79, vcc, 0, v157, vcc
	v_add_co_u32_e32 v94, vcc, s10, v156
	s_mov_b32 s12, 0xa0000
	s_nop 0
	v_addc_co_u32_e32 v95, vcc, 0, v157, vcc
	v_add_co_u32_e32 v110, vcc, s12, v156
	s_mov_b32 s13, 0xb0000
	s_nop 0
	v_addc_co_u32_e32 v111, vcc, 0, v157, vcc
	v_add_co_u32_e32 v126, vcc, s13, v156
	global_load_dwordx4 v[66:69], v[78:79], off
	global_load_dwordx4 v[70:73], v[78:79], off offset:64
	global_load_dwordx4 v[74:77], v[78:79], off offset:512
	s_nop 0
	global_load_dwordx4 v[78:81], v[78:79], off offset:576
	v_addc_co_u32_e32 v127, vcc, 0, v157, vcc
	global_load_dwordx4 v[82:85], v[94:95], off
	global_load_dwordx4 v[86:89], v[94:95], off offset:64
	global_load_dwordx4 v[90:93], v[94:95], off offset:512
	s_nop 0
	global_load_dwordx4 v[94:97], v[94:95], off offset:576
	s_nop 0
	global_load_dwordx4 v[98:101], v[110:111], off
	global_load_dwordx4 v[102:105], v[110:111], off offset:64
	global_load_dwordx4 v[106:109], v[110:111], off offset:512
	s_nop 0
	global_load_dwordx4 v[110:113], v[110:111], off offset:576
	s_nop 0
	global_load_dwordx4 v[114:117], v[126:127], off
	global_load_dwordx4 v[118:121], v[126:127], off offset:64
	global_load_dwordx4 v[122:125], v[126:127], off offset:512
	s_nop 0
	global_load_dwordx4 v[126:129], v[126:127], off offset:576
	s_mov_b64 s[14:15], 0x80000
	s_waitcnt vmcnt(0)
; #define PG8_WAIT_V(n) asm volatile("s_waitcnt vmcnt(" #n ")" ::: "memory")
; #define PG8_BAR __builtin_amdgcn_s_barrier()
; template <class Epi>
; __device__ __forceinline__ void gemm_phase(LAS unsigned char* lds, const Gemm g, const Epi& E) {
;     ...
;         cur = nxt; cA = nA; cB = nB; ++ui;
;     }
;     PG8_WAIT_V(0);
;     if (wr == 0) PG8_BAR;
;     __device__ __forceinline__ void operator()(const AccT& acc, const Unit& u, int wr, int wc, int fr, int fq) const {
;     ...
;             for (int m = 0; m < 4; ++m) { float* rowp = X + (size_t)(row0 + ai * 128 + m * 16) * 1024 + col0;
; #pragma unroll
;                 for (int bj = 0; bj < 2; ++bj)
; #pragma unroll
;                     for (int n = 0; n < 2; ++n) *(f32x4*)(rowp + bj * 128 + n * 16) = xo[m][bj][n] + gv[bj][n] * acc[ai][bj][m][n]; }
	v_pk_fma_f32 v[62:63], v[62:63], v[142:143], v[66:67]
	v_add_co_u32_e32 v66, vcc, s7, v154
	v_lshl_add_u64 v[156:157], v[154:155], 0, s[14:15]
	s_nop 0
	v_addc_co_u32_e32 v67, vcc, 0, v155, vcc
	v_pk_fma_f32 v[52:53], v[52:53], v[136:137], v[76:77]
	v_pk_fma_f32 v[50:51], v[50:51], v[134:135], v[74:75]
	global_store_dwordx4 v[156:157], v[50:53], off offset:512
	s_mov_b64 s[14:15], 0x90000
	v_pk_fma_f32 v[36:37], v[36:37], v[136:137], v[92:93]
	v_add_co_u32_e32 v52, vcc, s10, v154
	v_lshl_add_u64 v[50:51], v[154:155], 0, s[14:15]
	s_nop 0
	v_addc_co_u32_e32 v53, vcc, 0, v155, vcc
	v_pk_fma_f32 v[34:35], v[34:35], v[134:135], v[90:91]
	global_store_dwordx4 v[50:51], v[34:37], off offset:512
	s_mov_b64 s[14:15], 0xa0000
	v_pk_fma_f32 v[20:21], v[20:21], v[136:137], v[108:109]
	v_add_co_u32_e32 v36, vcc, s12, v154
	v_lshl_add_u64 v[34:35], v[154:155], 0, s[14:15]
	s_nop 0
	v_addc_co_u32_e32 v37, vcc, 0, v155, vcc
	v_pk_fma_f32 v[18:19], v[18:19], v[134:135], v[106:107]
	v_pk_fma_f32 v[48:49], v[48:49], v[132:133], v[80:81]
	v_pk_fma_f32 v[46:47], v[46:47], v[130:131], v[78:79]
	v_pk_fma_f32 v[32:33], v[32:33], v[132:133], v[96:97]
	v_pk_fma_f32 v[30:31], v[30:31], v[130:131], v[94:95]
	global_store_dwordx4 v[34:35], v[18:21], off offset:512
	v_pk_fma_f32 v[16:17], v[16:17], v[132:133], v[112:113]
	v_pk_fma_f32 v[14:15], v[14:15], v[130:131], v[110:111]
	s_mov_b64 s[14:15], 0xb0000
	v_add_co_u32_e32 v20, vcc, s13, v154
	v_pk_fma_f32 v[64:65], v[64:65], v[144:145], v[68:69]
	v_pk_fma_f32 v[60:61], v[60:61], v[140:141], v[72:73]
	v_pk_fma_f32 v[58:59], v[58:59], v[138:139], v[70:71]
	global_store_dwordx4 v[156:157], v[46:49], off offset:576
	v_pk_fma_f32 v[44:45], v[44:45], v[140:141], v[88:89]
	v_pk_fma_f32 v[42:43], v[42:43], v[138:139], v[86:87]
	v_pk_fma_f32 v[48:49], v[56:57], v[144:145], v[84:85]
	v_pk_fma_f32 v[46:47], v[54:55], v[142:143], v[82:83]
	global_store_dwordx4 v[50:51], v[30:33], off offset:576
	v_pk_fma_f32 v[28:29], v[28:29], v[140:141], v[104:105]
	v_pk_fma_f32 v[26:27], v[26:27], v[138:139], v[102:103]
	v_pk_fma_f32 v[32:33], v[40:41], v[144:145], v[100:101]
	v_pk_fma_f32 v[30:31], v[38:39], v[142:143], v[98:99]
	global_store_dwordx4 v[34:35], v[14:17], off offset:576
	v_lshl_add_u64 v[18:19], v[154:155], 0, s[14:15]
	v_addc_co_u32_e32 v21, vcc, 0, v155, vcc
	v_pk_fma_f32 v[16:17], v[24:25], v[144:145], v[116:117]
	v_pk_fma_f32 v[14:15], v[22:23], v[142:143], v[114:115]
	v_pk_fma_f32 v[12:13], v[12:13], v[140:141], v[120:121]
	v_pk_fma_f32 v[10:11], v[10:11], v[138:139], v[118:119]
	v_pk_fma_f32 v[8:9], v[8:9], v[136:137], v[124:125]
	v_pk_fma_f32 v[6:7], v[6:7], v[134:135], v[122:123]
	v_pk_fma_f32 v[4:5], v[4:5], v[132:133], v[128:129]
	v_pk_fma_f32 v[2:3], v[2:3], v[130:131], v[126:127]
	global_store_dwordx4 v[66:67], v[62:65], off
	global_store_dwordx4 v[156:157], v[58:61], off offset:64
	global_store_dwordx4 v[52:53], v[46:49], off
	global_store_dwordx4 v[50:51], v[42:45], off offset:64
	global_store_dwordx4 v[36:37], v[30:33], off
	global_store_dwordx4 v[34:35], v[26:29], off offset:64
	global_store_dwordx4 v[20:21], v[14:17], off
	global_store_dwordx4 v[18:19], v[10:13], off offset:64
	global_store_dwordx4 v[18:19], v[6:9], off offset:512
	global_store_dwordx4 v[18:19], v[2:5], off offset:576
	s_and_b64 vcc, exec, s[2:3]
	s_mov_b32 s10, s6
	s_mov_b32 s61, s60
	s_mov_b64 s[14:15], s[4:5]
	s_mov_b64 s[12:13], s[8:9]
	s_cbranch_vccz .LBB0_490
	s_waitcnt vmcnt(0)
	s_cmpk_gt_u32 s1, 0xff
	s_cbranch_scc1 .LBB0_499
	s_barrier

; #define PG8_STAGE(bufoff, gbase, voff) do { _Pragma("unroll") for (int _i = 0; _i < 2; ++_i) \
;         __builtin_amdgcn_global_load_lds((const unsigned*)((const char*)(gbase) + (voff)[_i]), (LAS unsigned*)(lds + (bufoff) + ldsw + _i * 8192), 16, 0, 0); } while (0)
; #define PG8_LDA(dst, b, h) do { _Pragma("unroll") for (int m = 0; m < 4; ++m) _Pragma("unroll") for (int k = 0; k < 2; ++k) dst[m][k] = *(const LAS bf16x8*)(lds + PG8_SA(b, h) + aoff + m * 2048 + k * 1024); } while (0)
; #define PG8_LDB(dst, b, h) do { _Pragma("unroll") for (int n = 0; n < 2; ++n) _Pragma("unroll") for (int k = 0; k < 2; ++k) dst[n][k] = *(const LAS bf16x8*)(lds + PG8_SB(b, h) + boff + n * 2048 + k * 1024); } while (0)
; #define PG8_MMA(ai, bj, At, Bt) do { __builtin_amdgcn_s_setprio(1); _Pragma("unroll") for (int m = 0; m < 4; ++m) _Pragma("unroll") for (int n = 0; n < 2; ++n) _Pragma("unroll") for (int k = 0; k < 2; ++k) \
;         acc[ai][bj][m][n] = __builtin_amdgcn_mfma_f32_16x16x32_bf16(Bt[n][k], At[m][k], acc[ai][bj][m][n], 0, 0, 0); __builtin_amdgcn_s_setprio(0); } while (0)
; #define PG8_WAIT_L(n) asm volatile("s_waitcnt lgkmcnt(" #n ")" ::: "memory")
; #define PG8_BAR __builtin_amdgcn_s_barrier()
; #define PG8_SCHED __builtin_amdgcn_sched_barrier(0)
; template <class Epi>
; __device__ __forceinline__ void gemm_phase(LAS unsigned char* lds, const Gemm g, const Epi& E) {
;     ...
;             PG8_LDB(B0, 0, 0); PG8_SCHED; PG8_LDA(At, 0, 0); PG8_STAGE(PG8_SA(1, 1), a1 + hstepA, voffA);
;             PG8_WAIT_L(8); PG8_BAR; PG8_WAIT_L(0); PG8_MMA(0, 0, At, B0); PG8_BAR; PG8_SCHED;
;             PG8_LDB(B1, 0, 1); PG8_STAGE(PG8_SB(0, 0), b2, voffB);
;             PG8_BAR; PG8_WAIT_L(0); PG8_MMA(0, 1, At, B1); PG8_BAR;
;             PG8_LDA(At, 0, 1); PG8_STAGE(PG8_SA(0, 0), a2, voffA);
;             PG8_BAR; PG8_WAIT_L(0); PG8_MMA(1, 0, At, B0); PG8_BAR; PG8_SCHED;
.LBB0_525:
	s_add_u32 s14, s12, 0xfffc0080
	s_addc_u32 s15, s13, -1
	s_add_i32 s26, 0, 0x10000
	v_add_u32_e32 v149, s26, v147
	ds_read_b128 v[142:145], v149
	ds_read_b128 v[150:153], v149 offset:1024
	ds_read_b128 v[154:157], v149 offset:2048
	ds_read_b128 v[158:161], v149 offset:3072
	s_cmp_eq_u32 s66, 12
	s_cselect_b32 s17, s9, s15
	s_cselect_b32 s16, s8, s14
	s_cselect_b32 s15, s5, s65
	s_cselect_b32 s14, s4, s7
	v_lshl_add_u64 v[196:197], s[12:13], 0, v[138:139]
	s_add_i32 m0, s11, 0xc000
	ds_read_b128 v[162:165], v148
	ds_read_b128 v[166:169], v148 offset:1024
	ds_read_b128 v[170:173], v148 offset:2048
	ds_read_b128 v[174:177], v148 offset:3072
	ds_read_b128 v[180:183], v148 offset:4096
	ds_read_b128 v[184:187], v148 offset:5120
	ds_read_b128 v[188:191], v148 offset:6144
	ds_read_b128 v[192:195], v148 offset:7168
	global_load_lds_dwordx4 v[196:197], off
	v_lshl_add_u64 v[196:197], s[12:13], 0, v[140:141]
	s_add_i32 m0, s11, 0xe000
	s_nop 0
	global_load_lds_dwordx4 v[196:197], off
	s_waitcnt lgkmcnt(8)
	s_barrier
	s_waitcnt lgkmcnt(0)
	v_mfma_f32_16x16x32_bf16 v[126:129], v[142:145], v[162:165], v[126:129]
	v_mfma_f32_16x16x32_bf16 v[118:121], v[154:157], v[162:165], v[118:121]
	v_mfma_f32_16x16x32_bf16 v[110:113], v[142:145], v[170:173], v[110:113]
	v_mfma_f32_16x16x32_bf16 v[102:105], v[154:157], v[170:173], v[102:105]
	v_mfma_f32_16x16x32_bf16 v[94:97], v[142:145], v[180:183], v[94:97]
	v_mfma_f32_16x16x32_bf16 v[86:89], v[154:157], v[180:183], v[86:89]
	v_mfma_f32_16x16x32_bf16 v[78:81], v[142:145], v[188:191], v[78:81]
	v_mfma_f32_16x16x32_bf16 v[70:73], v[154:157], v[188:191], v[70:73]
	v_mfma_f32_16x16x32_bf16 v[126:129], v[150:153], v[166:169], v[126:129]
	v_mfma_f32_16x16x32_bf16 v[118:121], v[158:161], v[166:169], v[118:121]
	v_mfma_f32_16x16x32_bf16 v[110:113], v[150:153], v[174:177], v[110:113]
	v_mfma_f32_16x16x32_bf16 v[102:105], v[158:161], v[174:177], v[102:105]
	v_mfma_f32_16x16x32_bf16 v[94:97], v[150:153], v[184:187], v[94:97]
	v_mfma_f32_16x16x32_bf16 v[86:89], v[158:161], v[184:187], v[86:89]
	v_mfma_f32_16x16x32_bf16 v[78:81], v[150:153], v[192:195], v[78:81]
	v_mfma_f32_16x16x32_bf16 v[70:73], v[158:161], v[192:195], v[70:73]
	s_barrier
	s_add_i32 s27, 0, 0x14000
	s_add_i32 s26, s26, s25
	v_add_u32_e32 v149, s27, v147
	v_lshl_add_u64 v[208:209], s[14:15], 0, v[134:135]
	s_mov_b32 m0, s26
	ds_read_b128 v[196:199], v149
	ds_read_b128 v[200:203], v149 offset:1024
	ds_read_b128 v[204:207], v149 offset:2048
	ds_read_b128 v[226:229], v149 offset:3072
	global_load_lds_dwordx4 v[208:209], off
	v_lshl_add_u64 v[230:231], s[14:15], 0, v[130:131]
	s_add_i32 m0, s26, 0x2000
	s_nop 0
	global_load_lds_dwordx4 v[230:231], off
	s_barrier
	s_waitcnt lgkmcnt(0)
	v_mfma_f32_16x16x32_bf16 v[122:125], v[196:199], v[162:165], v[122:125]
	v_mfma_f32_16x16x32_bf16 v[114:117], v[204:207], v[162:165], v[114:117]
	v_mfma_f32_16x16x32_bf16 v[106:109], v[196:199], v[170:173], v[106:109]
	v_mfma_f32_16x16x32_bf16 v[98:101], v[204:207], v[170:173], v[98:101]
	v_mfma_f32_16x16x32_bf16 v[90:93], v[196:199], v[180:183], v[90:93]
	v_mfma_f32_16x16x32_bf16 v[82:85], v[204:207], v[180:183], v[82:85]
	v_mfma_f32_16x16x32_bf16 v[74:77], v[196:199], v[188:191], v[74:77]
	v_mfma_f32_16x16x32_bf16 v[66:69], v[204:207], v[188:191], v[66:69]
	v_mfma_f32_16x16x32_bf16 v[122:125], v[200:203], v[166:169], v[122:125]
	v_mfma_f32_16x16x32_bf16 v[114:117], v[226:229], v[166:169], v[114:117]
	v_mfma_f32_16x16x32_bf16 v[106:109], v[200:203], v[174:177], v[106:109]
	v_mfma_f32_16x16x32_bf16 v[98:101], v[226:229], v[174:177], v[98:101]
	v_mfma_f32_16x16x32_bf16 v[90:93], v[200:203], v[184:187], v[90:93]
	v_mfma_f32_16x16x32_bf16 v[82:85], v[226:229], v[184:187], v[82:85]
	v_mfma_f32_16x16x32_bf16 v[74:77], v[200:203], v[192:195], v[74:77]
	v_mfma_f32_16x16x32_bf16 v[66:69], v[226:229], v[192:195], v[66:69]
	s_mov_b32 m0, s11
	v_lshl_add_u64 v[232:233], s[16:17], 0, v[136:137]
	s_barrier
	ds_read_b128 v[162:165], v148 offset:16384
	ds_read_b128 v[166:169], v148 offset:17408
	ds_read_b128 v[170:173], v148 offset:18432
	ds_read_b128 v[174:177], v148 offset:19456
	ds_read_b128 v[180:183], v148 offset:20480
	ds_read_b128 v[184:187], v148 offset:21504
	ds_read_b128 v[188:191], v148 offset:22528
	ds_read_b128 v[192:195], v148 offset:23552
	global_load_lds_dwordx4 v[232:233], off
	v_lshl_add_u64 v[234:235], s[16:17], 0, v[132:133]
	s_mov_b32 m0, s36
	s_nop 0
	global_load_lds_dwordx4 v[234:235], off
	s_barrier
	s_waitcnt lgkmcnt(0)
	v_mfma_f32_16x16x32_bf16 v[62:65], v[142:145], v[162:165], v[62:65]
	v_mfma_f32_16x16x32_bf16 v[54:57], v[154:157], v[162:165], v[54:57]
	v_mfma_f32_16x16x32_bf16 v[46:49], v[142:145], v[170:173], v[46:49]
	v_mfma_f32_16x16x32_bf16 v[38:41], v[154:157], v[170:173], v[38:41]
	v_mfma_f32_16x16x32_bf16 v[30:33], v[142:145], v[180:183], v[30:33]
	v_mfma_f32_16x16x32_bf16 v[22:25], v[154:157], v[180:183], v[22:25]
	v_mfma_f32_16x16x32_bf16 v[14:17], v[142:145], v[188:191], v[14:17]
	v_mfma_f32_16x16x32_bf16 v[6:9], v[154:157], v[188:191], v[6:9]
	v_mfma_f32_16x16x32_bf16 v[62:65], v[150:153], v[166:169], v[62:65]
	v_mfma_f32_16x16x32_bf16 v[54:57], v[158:161], v[166:169], v[54:57]
	v_mfma_f32_16x16x32_bf16 v[46:49], v[150:153], v[174:177], v[46:49]
	v_mfma_f32_16x16x32_bf16 v[38:41], v[158:161], v[174:177], v[38:41]
	v_mfma_f32_16x16x32_bf16 v[30:33], v[150:153], v[184:187], v[30:33]
	v_mfma_f32_16x16x32_bf16 v[22:25], v[158:161], v[184:187], v[22:25]
	v_mfma_f32_16x16x32_bf16 v[14:17], v[150:153], v[192:195], v[14:17]
	v_mfma_f32_16x16x32_bf16 v[6:9], v[158:161], v[192:195], v[6:9]
	s_barrier
; #define PG8_STAGE(bufoff, gbase, voff) do { _Pragma("unroll") for (int _i = 0; _i < 2; ++_i) \
;         __builtin_amdgcn_global_load_lds((const unsigned*)((const char*)(gbase) + (voff)[_i]), (LAS unsigned*)(lds + (bufoff) + ldsw + _i * 8192), 16, 0, 0); } while (0)
; #define PG8_LDA(dst, b, h) do { _Pragma("unroll") for (int m = 0; m < 4; ++m) _Pragma("unroll") for (int k = 0; k < 2; ++k) dst[m][k] = *(const LAS bf16x8*)(lds + PG8_SA(b, h) + aoff + m * 2048 + k * 1024); } while (0)
; #define PG8_LDB(dst, b, h) do { _Pragma("unroll") for (int n = 0; n < 2; ++n) _Pragma("unroll") for (int k = 0; k < 2; ++k) dst[n][k] = *(const LAS bf16x8*)(lds + PG8_SB(b, h) + boff + n * 2048 + k * 1024); } while (0)
; #define PG8_MMA(ai, bj, At, Bt) do { __builtin_amdgcn_s_setprio(1); _Pragma("unroll") for (int m = 0; m < 4; ++m) _Pragma("unroll") for (int n = 0; n < 2; ++n) _Pragma("unroll") for (int k = 0; k < 2; ++k) \
;         acc[ai][bj][m][n] = __builtin_amdgcn_mfma_f32_16x16x32_bf16(Bt[n][k], At[m][k], acc[ai][bj][m][n], 0, 0, 0); __builtin_amdgcn_s_setprio(0); } while (0)
; #define PG8_WAIT_V(n) asm volatile("s_waitcnt vmcnt(" #n ")" ::: "memory")
; #define PG8_WAIT_L(n) asm volatile("s_waitcnt lgkmcnt(" #n ")" ::: "memory")
; #define PG8_BAR __builtin_amdgcn_s_barrier()
; #define PG8_SCHED __builtin_amdgcn_sched_barrier(0)
; template <class Epi>
; __device__ __forceinline__ void gemm_phase(LAS unsigned char* lds, const Gemm g, const Epi& E) {
;     ...
;             PG8_STAGE(PG8_SB(0, 1), b2 + hstepB, voffB);
;             PG8_WAIT_V(6); PG8_BAR; PG8_MMA(1, 1, At, B1); PG8_BAR;
;             PG8_LDB(B0, 1, 0); PG8_SCHED; PG8_LDA(At, 1, 0); PG8_STAGE(PG8_SA(0, 1), a2 + hstepA, voffA);
;             PG8_WAIT_L(8); PG8_BAR; PG8_WAIT_L(0); PG8_MMA(0, 0, At, B0); PG8_BAR; PG8_SCHED;
;             PG8_LDB(B1, 1, 1); PG8_STAGE(PG8_SB(1, 0), b3, voffB);
;             PG8_BAR; PG8_WAIT_L(0); PG8_MMA(0, 1, At, B1); PG8_BAR;
;             PG8_LDA(At, 1, 1); PG8_STAGE(PG8_SA(1, 0), a3, voffA);
;             PG8_BAR; PG8_WAIT_L(0); PG8_MMA(1, 0, At, B0); PG8_BAR; PG8_SCHED;
	s_add_u32 s68, s14, 0x40000
	s_addc_u32 s69, s15, 0
	s_add_i32 s26, s27, s25
	v_lshl_add_u64 v[142:143], s[68:69], 0, v[134:135]
	s_mov_b32 m0, s26
	s_nop 0
	global_load_lds_dwordx4 v[142:143], off
	v_lshl_add_u64 v[142:143], s[68:69], 0, v[130:131]
	s_add_i32 m0, s26, 0x2000
	s_nop 0
	global_load_lds_dwordx4 v[142:143], off
	s_waitcnt vmcnt(6)
	s_barrier
	v_mfma_f32_16x16x32_bf16 v[58:61], v[196:199], v[162:165], v[58:61]
	v_mfma_f32_16x16x32_bf16 v[50:53], v[204:207], v[162:165], v[50:53]
	v_mfma_f32_16x16x32_bf16 v[42:45], v[196:199], v[170:173], v[42:45]
	v_mfma_f32_16x16x32_bf16 v[34:37], v[204:207], v[170:173], v[34:37]
	v_mfma_f32_16x16x32_bf16 v[26:29], v[196:199], v[180:183], v[26:29]
	v_mfma_f32_16x16x32_bf16 v[18:21], v[204:207], v[180:183], v[18:21]
	v_mfma_f32_16x16x32_bf16 v[10:13], v[196:199], v[188:191], v[10:13]
	v_mfma_f32_16x16x32_bf16 v[2:5], v[204:207], v[188:191], v[2:5]
	v_mfma_f32_16x16x32_bf16 v[58:61], v[200:203], v[166:169], v[58:61]
	v_mfma_f32_16x16x32_bf16 v[50:53], v[226:229], v[166:169], v[50:53]
	v_mfma_f32_16x16x32_bf16 v[42:45], v[200:203], v[174:177], v[42:45]
	v_mfma_f32_16x16x32_bf16 v[34:37], v[226:229], v[174:177], v[34:37]
	v_mfma_f32_16x16x32_bf16 v[26:29], v[200:203], v[184:187], v[26:29]
	v_mfma_f32_16x16x32_bf16 v[18:21], v[226:229], v[184:187], v[18:21]
	v_mfma_f32_16x16x32_bf16 v[10:13], v[200:203], v[192:195], v[10:13]
	v_mfma_f32_16x16x32_bf16 v[2:5], v[226:229], v[192:195], v[2:5]
	s_add_i32 s26, 0, 0x18000
	v_add_u32_e32 v149, s26, v147
	s_barrier
	ds_read_b128 v[142:145], v149
	ds_read_b128 v[150:153], v149 offset:1024
	ds_read_b128 v[154:157], v149 offset:2048
	ds_read_b128 v[158:161], v149 offset:3072
	s_add_u32 s16, s16, 0x40000
	s_addc_u32 s17, s17, 0
	s_mov_b32 m0, s44
	v_lshl_add_u64 v[196:197], s[16:17], 0, v[136:137]
	ds_read_b128 v[162:165], v148 offset:32768
	ds_read_b128 v[166:169], v148 offset:33792
	ds_read_b128 v[170:173], v148 offset:34816
	ds_read_b128 v[174:177], v148 offset:35840
	ds_read_b128 v[180:183], v148 offset:36864
	ds_read_b128 v[184:187], v148 offset:37888
	ds_read_b128 v[188:191], v148 offset:38912
	ds_read_b128 v[192:195], v148 offset:39936
	global_load_lds_dwordx4 v[196:197], off
	v_lshl_add_u64 v[196:197], s[16:17], 0, v[132:133]
	s_mov_b32 m0, s50
	s_nop 0
	global_load_lds_dwordx4 v[196:197], off
	s_waitcnt lgkmcnt(8)
	s_barrier
	s_waitcnt lgkmcnt(0)
	v_mfma_f32_16x16x32_bf16 v[126:129], v[142:145], v[162:165], v[126:129]
	v_mfma_f32_16x16x32_bf16 v[118:121], v[154:157], v[162:165], v[118:121]
	v_mfma_f32_16x16x32_bf16 v[110:113], v[142:145], v[170:173], v[110:113]
	v_mfma_f32_16x16x32_bf16 v[102:105], v[154:157], v[170:173], v[102:105]
	v_mfma_f32_16x16x32_bf16 v[94:97], v[142:145], v[180:183], v[94:97]
	v_mfma_f32_16x16x32_bf16 v[86:89], v[154:157], v[180:183], v[86:89]
	v_mfma_f32_16x16x32_bf16 v[78:81], v[142:145], v[188:191], v[78:81]
	v_mfma_f32_16x16x32_bf16 v[70:73], v[154:157], v[188:191], v[70:73]
	v_mfma_f32_16x16x32_bf16 v[126:129], v[150:153], v[166:169], v[126:129]
	v_mfma_f32_16x16x32_bf16 v[118:121], v[158:161], v[166:169], v[118:121]
	v_mfma_f32_16x16x32_bf16 v[110:113], v[150:153], v[174:177], v[110:113]
	v_mfma_f32_16x16x32_bf16 v[102:105], v[158:161], v[174:177], v[102:105]
	v_mfma_f32_16x16x32_bf16 v[94:97], v[150:153], v[184:187], v[94:97]
	v_mfma_f32_16x16x32_bf16 v[86:89], v[158:161], v[184:187], v[86:89]
	v_mfma_f32_16x16x32_bf16 v[78:81], v[150:153], v[192:195], v[78:81]
	v_mfma_f32_16x16x32_bf16 v[70:73], v[158:161], v[192:195], v[70:73]
	s_barrier
	s_add_i32 s16, 0, 0x1c000
	s_add_i32 s17, s26, s25
	v_add_u32_e32 v149, s16, v147
	v_lshl_add_u64 v[208:209], v[208:209], 0, s[86:87]
	s_mov_b32 m0, s17
	ds_read_b128 v[196:199], v149
	ds_read_b128 v[200:203], v149 offset:1024
	ds_read_b128 v[204:207], v149 offset:2048
	ds_read_b128 v[226:229], v149 offset:3072
	global_load_lds_dwordx4 v[208:209], off
	v_lshl_add_u64 v[208:209], v[230:231], 0, s[86:87]
	s_add_i32 m0, s17, 0x2000
	s_nop 0
	global_load_lds_dwordx4 v[208:209], off
	s_barrier
	s_waitcnt lgkmcnt(0)
	v_mfma_f32_16x16x32_bf16 v[122:125], v[196:199], v[162:165], v[122:125]
	v_mfma_f32_16x16x32_bf16 v[114:117], v[204:207], v[162:165], v[114:117]
	v_mfma_f32_16x16x32_bf16 v[106:109], v[196:199], v[170:173], v[106:109]
	v_mfma_f32_16x16x32_bf16 v[98:101], v[204:207], v[170:173], v[98:101]
	v_mfma_f32_16x16x32_bf16 v[90:93], v[196:199], v[180:183], v[90:93]
	v_mfma_f32_16x16x32_bf16 v[82:85], v[204:207], v[180:183], v[82:85]
	v_mfma_f32_16x16x32_bf16 v[74:77], v[196:199], v[188:191], v[74:77]
	v_mfma_f32_16x16x32_bf16 v[66:69], v[204:207], v[188:191], v[66:69]
	v_mfma_f32_16x16x32_bf16 v[122:125], v[200:203], v[166:169], v[122:125]
	v_mfma_f32_16x16x32_bf16 v[114:117], v[226:229], v[166:169], v[114:117]
	v_mfma_f32_16x16x32_bf16 v[106:109], v[200:203], v[174:177], v[106:109]
	v_mfma_f32_16x16x32_bf16 v[98:101], v[226:229], v[174:177], v[98:101]
	v_mfma_f32_16x16x32_bf16 v[90:93], v[200:203], v[184:187], v[90:93]
	v_mfma_f32_16x16x32_bf16 v[82:85], v[226:229], v[184:187], v[82:85]
	v_mfma_f32_16x16x32_bf16 v[74:77], v[200:203], v[192:195], v[74:77]
	v_mfma_f32_16x16x32_bf16 v[66:69], v[226:229], v[192:195], v[66:69]
	s_mov_b32 m0, s58
	v_lshl_add_u64 v[208:209], v[232:233], 0, s[86:87]
	s_barrier
	ds_read_b128 v[162:165], v148 offset:49152
	ds_read_b128 v[166:169], v148 offset:50176
	ds_read_b128 v[170:173], v148 offset:51200
	ds_read_b128 v[174:177], v148 offset:52224
	ds_read_b128 v[180:183], v148 offset:53248
	ds_read_b128 v[184:187], v148 offset:54272
	ds_read_b128 v[188:191], v148 offset:55296
	ds_read_b128 v[192:195], v148 offset:56320
	global_load_lds_dwordx4 v[208:209], off
	v_lshl_add_u64 v[208:209], v[234:235], 0, s[86:87]
	s_mov_b32 m0, s59
	s_nop 0
	global_load_lds_dwordx4 v[208:209], off
	s_barrier
; __device__ __forceinline__ unsigned cvt_pk_bf16(float lo, float hi) { unsigned r; asm("v_cvt_pk_bf16_f32 %0, %1, %2" : "=v"(r) : "v"(lo), "v"(hi)); return r; }
; #define PG8_STAGE(bufoff, gbase, voff) do { _Pragma("unroll") for (int _i = 0; _i < 2; ++_i) \
;         __builtin_amdgcn_global_load_lds((const unsigned*)((const char*)(gbase) + (voff)[_i]), (LAS unsigned*)(lds + (bufoff) + ldsw + _i * 8192), 16, 0, 0); } while (0)
; #define PG8_MMA(ai, bj, At, Bt) do { __builtin_amdgcn_s_setprio(1); _Pragma("unroll") for (int m = 0; m < 4; ++m) _Pragma("unroll") for (int n = 0; n < 2; ++n) _Pragma("unroll") for (int k = 0; k < 2; ++k) \
;         acc[ai][bj][m][n] = __builtin_amdgcn_mfma_f32_16x16x32_bf16(Bt[n][k], At[m][k], acc[ai][bj][m][n], 0, 0, 0); __builtin_amdgcn_s_setprio(0); } while (0)
; #define PG8_WAIT_V(n) asm volatile("s_waitcnt vmcnt(" #n ")" ::: "memory")
; #define PG8_BAR __builtin_amdgcn_s_barrier()
; template <class Epi>
; __device__ __forceinline__ void gemm_phase(LAS unsigned char* lds, const Gemm g, const Epi& E) {
;     ...
;             PG8_STAGE(PG8_SB(1, 1), b3 + hstepB, voffB);
;             PG8_WAIT_V(6); PG8_BAR; PG8_MMA(1, 1, At, B1); PG8_BAR;
;     __device__ __forceinline__ void operator()(const AccT& acc, const Unit& u, int wr, int wc, int fr, int fq) const {
;     ...
;             for (int m = 0; m < 4; ++m) { bf16_t* rowp = U + (size_t)(row0 + ai * 128 + m * 16) * HID + col0;
;                 const f32x4 s0 = silu4(acc[ai][0][m][0]) * acc[ai][1][m][0], s1 = silu4(acc[ai][0][m][1]) * acc[ai][1][m][1];
;                 u32x4 w; w.x = cvt_pk_bf16(s0[0], s0[1]); w.y = cvt_pk_bf16(s0[2], s0[3]); w.z = cvt_pk_bf16(s1[0], s1[1]); w.w = cvt_pk_bf16(s1[2], s1[3]);
;                 *(u32x4*)rowp = w; }
	s_waitcnt lgkmcnt(0)
	v_mfma_f32_16x16x32_bf16 v[62:65], v[142:145], v[162:165], v[62:65]
	v_mfma_f32_16x16x32_bf16 v[54:57], v[154:157], v[162:165], v[54:57]
	v_mfma_f32_16x16x32_bf16 v[46:49], v[142:145], v[170:173], v[46:49]
	v_mfma_f32_16x16x32_bf16 v[38:41], v[154:157], v[170:173], v[38:41]
	v_mfma_f32_16x16x32_bf16 v[30:33], v[142:145], v[180:183], v[30:33]
	v_mfma_f32_16x16x32_bf16 v[22:25], v[154:157], v[180:183], v[22:25]
	v_mfma_f32_16x16x32_bf16 v[14:17], v[142:145], v[188:191], v[14:17]
	v_mfma_f32_16x16x32_bf16 v[6:9], v[154:157], v[188:191], v[6:9]
	v_mfma_f32_16x16x32_bf16 v[62:65], v[150:153], v[166:169], v[62:65]
	v_mfma_f32_16x16x32_bf16 v[54:57], v[158:161], v[166:169], v[54:57]
	v_mfma_f32_16x16x32_bf16 v[46:49], v[150:153], v[174:177], v[46:49]
	v_mfma_f32_16x16x32_bf16 v[38:41], v[158:161], v[174:177], v[38:41]
	v_mfma_f32_16x16x32_bf16 v[30:33], v[150:153], v[184:187], v[30:33]
	v_mfma_f32_16x16x32_bf16 v[22:25], v[158:161], v[184:187], v[22:25]
	v_mfma_f32_16x16x32_bf16 v[14:17], v[150:153], v[192:195], v[14:17]
	v_mfma_f32_16x16x32_bf16 v[6:9], v[158:161], v[192:195], v[6:9]
	s_barrier
	s_add_u32 s14, s14, 0x40080
	s_addc_u32 s15, s15, 0
	s_add_i32 s16, s16, s25
	v_lshl_add_u64 v[142:143], s[14:15], 0, v[134:135]
	s_mov_b32 m0, s16
	s_nop 0
	global_load_lds_dwordx4 v[142:143], off
	v_lshl_add_u64 v[142:143], s[14:15], 0, v[130:131]
	s_add_i32 m0, s16, 0x2000
	s_nop 0
	global_load_lds_dwordx4 v[142:143], off
	s_waitcnt vmcnt(6)
	s_barrier
	v_mfma_f32_16x16x32_bf16 v[58:61], v[196:199], v[162:165], v[58:61]
	v_mfma_f32_16x16x32_bf16 v[50:53], v[204:207], v[162:165], v[50:53]
	v_mfma_f32_16x16x32_bf16 v[42:45], v[196:199], v[170:173], v[42:45]
	v_mfma_f32_16x16x32_bf16 v[34:37], v[204:207], v[170:173], v[34:37]
	v_mfma_f32_16x16x32_bf16 v[26:29], v[196:199], v[180:183], v[26:29]
	v_mfma_f32_16x16x32_bf16 v[18:21], v[204:207], v[180:183], v[18:21]
	v_mfma_f32_16x16x32_bf16 v[10:13], v[196:199], v[188:191], v[10:13]
	v_mfma_f32_16x16x32_bf16 v[2:5], v[204:207], v[188:191], v[2:5]
	v_mfma_f32_16x16x32_bf16 v[58:61], v[200:203], v[166:169], v[58:61]
	v_mfma_f32_16x16x32_bf16 v[50:53], v[226:229], v[166:169], v[50:53]
	v_mfma_f32_16x16x32_bf16 v[42:45], v[200:203], v[174:177], v[42:45]
	v_mfma_f32_16x16x32_bf16 v[34:37], v[226:229], v[174:177], v[34:37]
	v_mfma_f32_16x16x32_bf16 v[26:29], v[200:203], v[184:187], v[26:29]
	v_mfma_f32_16x16x32_bf16 v[18:21], v[226:229], v[184:187], v[18:21]
	v_mfma_f32_16x16x32_bf16 v[10:13], v[200:203], v[192:195], v[10:13]
	v_mfma_f32_16x16x32_bf16 v[2:5], v[226:229], v[192:195], v[2:5]
	s_add_i32 s66, s66, 2
	s_add_u32 s12, s12, 0x100
	s_addc_u32 s13, s13, 0
	s_add_u32 s7, s7, 0x100
	s_addc_u32 s65, s65, 0
	s_cmp_gt_u32 s66, 13
	s_barrier
	s_cbranch_scc0 .LBB0_525
	v_mul_f32_e32 v152, 0xbfb8aa3b, v126
	v_mul_f32_e32 v153, 0xbfb8aa3b, v127
	v_mul_f32_e32 v154, 0xbfb8aa3b, v128
	v_mul_f32_e32 v155, 0xbfb8aa3b, v129
	v_exp_f32_e32 v152, v152
	v_exp_f32_e32 v153, v153
	v_exp_f32_e32 v154, v154
	v_exp_f32_e32 v155, v155
	v_add_f32_e32 v152, 1.0, v152
	v_add_f32_e32 v153, 1.0, v153
	v_add_f32_e32 v154, 1.0, v154
	v_add_f32_e32 v155, 1.0, v155
	v_rcp_f32_e32 v152, v152
	v_rcp_f32_e32 v153, v153
	v_rcp_f32_e32 v154, v154
	v_rcp_f32_e32 v155, v155
	v_readlane_b32 s7, v255, 27
	v_pk_mul_f32 v[126:127], v[126:127], v[152:153]
	s_cmp_ge_i32 s64, s7
	v_pk_mul_f32 v[128:129], v[128:129], v[154:155]
	v_pk_mul_f32 v[122:123], v[126:127], v[122:123]
	v_pk_mul_f32 v[124:125], v[128:129], v[124:125]
	v_mul_f32_e32 v126, 0xbfb8aa3b, v118
	v_mul_f32_e32 v127, 0xbfb8aa3b, v119
	v_mul_f32_e32 v128, 0xbfb8aa3b, v120
	v_mul_f32_e32 v129, 0xbfb8aa3b, v121
	v_exp_f32_e32 v126, v126
	v_exp_f32_e32 v127, v127
	v_exp_f32_e32 v128, v128
	v_exp_f32_e32 v129, v129
	v_add_f32_e32 v126, 1.0, v126
	v_add_f32_e32 v127, 1.0, v127
	v_add_f32_e32 v128, 1.0, v128
	v_add_f32_e32 v129, 1.0, v129
	s_cselect_b32 s7, s31, 0
	v_rcp_f32_e32 v126, v126
	v_rcp_f32_e32 v127, v127
	v_rcp_f32_e32 v128, v128
	v_rcp_f32_e32 v129, v129
	s_add_i32 s7, s64, s7
	s_lshl_b32 s10, s10, 7
	v_mov_b32_e32 v142, v146
	v_mov_b32_e32 v143, v1
	s_lshl_b32 s7, s7, 8
	s_or_b32 s10, s10, s53
	s_add_i32 s7, s7, s52
	v_lshl_add_u32 v144, v143, 3, s10
	v_add_u32_e32 v149, s7, v142
	v_ashrrev_i32_e32 v145, 31, v144
	v_mov_b64_e32 v[142:143], s[34:35]
	s_movk_i32 s7, 0x1600
	v_pk_mul_f32 v[118:119], v[118:119], v[126:127]
	v_pk_mul_f32 v[120:121], v[120:121], v[128:129]
	v_mad_i64_i32 v[150:151], s[12:13], v149, s7, v[142:143]
	v_lshlrev_b64 v[144:145], 1, v[144:145]
	v_pk_mul_f32 v[120:121], v[120:121], v[116:117]
	v_pk_mul_f32 v[116:117], v[118:119], v[114:115]
	v_lshl_add_u64 v[150:151], v[150:151], 0, v[144:145]
	v_cvt_pk_bf16_f32 v116, v116, v117
	v_cvt_pk_bf16_f32 v117, v120, v121
	v_cvt_pk_bf16_f32 v114, v122, v123
	v_cvt_pk_bf16_f32 v115, v124, v125
	global_store_dwordx4 v[150:151], v[114:117], off
	v_mul_f32_e32 v118, 0xbfb8aa3b, v112
	v_mul_f32_e32 v119, 0xbfb8aa3b, v113
	v_mul_f32_e32 v116, 0xbfb8aa3b, v110
	v_mul_f32_e32 v117, 0xbfb8aa3b, v111
	v_exp_f32_e32 v116, v116
	v_exp_f32_e32 v117, v117
	v_exp_f32_e32 v118, v118
	v_exp_f32_e32 v119, v119
	v_add_f32_e32 v116, 1.0, v116
	v_add_f32_e32 v117, 1.0, v117
	v_add_f32_e32 v118, 1.0, v118
	v_add_f32_e32 v119, 1.0, v119
	v_rcp_f32_e32 v116, v116
	v_rcp_f32_e32 v117, v117
	v_rcp_f32_e32 v118, v118
	v_rcp_f32_e32 v119, v119
	v_add_u32_e32 v114, 16, v149
	v_pk_mul_f32 v[110:111], v[110:111], v[116:117]
	v_mad_i64_i32 v[114:115], s[12:13], v114, s7, v[142:143]
	v_pk_mul_f32 v[112:113], v[112:113], v[118:119]
	v_pk_mul_f32 v[106:107], v[110:111], v[106:107]
	v_pk_mul_f32 v[108:109], v[112:113], v[108:109]
; __device__ __forceinline__ unsigned cvt_pk_bf16(float lo, float hi) { unsigned r; asm("v_cvt_pk_bf16_f32 %0, %1, %2" : "=v"(r) : "v"(lo), "v"(hi)); return r; }
;     __device__ __forceinline__ void operator()(const AccT& acc, const Unit& u, int wr, int wc, int fr, int fq) const {
;     ...
;             for (int m = 0; m < 4; ++m) { bf16_t* rowp = U + (size_t)(row0 + ai * 128 + m * 16) * HID + col0;
;                 const f32x4 s0 = silu4(acc[ai][0][m][0]) * acc[ai][1][m][0], s1 = silu4(acc[ai][0][m][1]) * acc[ai][1][m][1];
;                 u32x4 w; w.x = cvt_pk_bf16(s0[0], s0[1]); w.y = cvt_pk_bf16(s0[2], s0[3]); w.z = cvt_pk_bf16(s1[0], s1[1]); w.w = cvt_pk_bf16(s1[2], s1[3]);
;                 *(u32x4*)rowp = w; }
	v_mul_f32_e32 v110, 0xbfb8aa3b, v102
	v_mul_f32_e32 v111, 0xbfb8aa3b, v103
	v_mul_f32_e32 v112, 0xbfb8aa3b, v104
	v_mul_f32_e32 v113, 0xbfb8aa3b, v105
	v_exp_f32_e32 v110, v110
	v_exp_f32_e32 v111, v111
	v_exp_f32_e32 v112, v112
	v_exp_f32_e32 v113, v113
	v_add_f32_e32 v110, 1.0, v110
	v_add_f32_e32 v111, 1.0, v111
	v_add_f32_e32 v112, 1.0, v112
	v_add_f32_e32 v113, 1.0, v113
	v_rcp_f32_e32 v110, v110
	v_rcp_f32_e32 v111, v111
	v_rcp_f32_e32 v112, v112
	v_rcp_f32_e32 v113, v113
	v_lshl_add_u64 v[114:115], v[114:115], 0, v[144:145]
	v_pk_mul_f32 v[102:103], v[102:103], v[110:111]
	s_and_b64 vcc, exec, s[2:3]
	v_pk_mul_f32 v[104:105], v[104:105], v[112:113]
	s_mov_b32 s10, s6
	v_pk_mul_f32 v[104:105], v[104:105], v[100:101]
	v_pk_mul_f32 v[100:101], v[102:103], v[98:99]
	v_cvt_pk_bf16_f32 v98, v106, v107
	v_cvt_pk_bf16_f32 v99, v108, v109
	v_mul_f32_e32 v102, 0xbfb8aa3b, v96
	v_cvt_pk_bf16_f32 v100, v100, v101
	v_cvt_pk_bf16_f32 v101, v104, v105
	global_store_dwordx4 v[114:115], v[98:101], off
	v_mul_f32_e32 v103, 0xbfb8aa3b, v97
	v_exp_f32_e32 v102, v102
	v_mul_f32_e32 v100, 0xbfb8aa3b, v94
	v_mul_f32_e32 v101, 0xbfb8aa3b, v95
	v_exp_f32_e32 v100, v100
	v_exp_f32_e32 v101, v101
	v_exp_f32_e32 v103, v103
	v_add_f32_e32 v102, 1.0, v102
	v_add_f32_e32 v100, 1.0, v100
	v_add_f32_e32 v101, 1.0, v101
	v_add_f32_e32 v103, 1.0, v103
	v_rcp_f32_e32 v100, v100
	v_rcp_f32_e32 v101, v101
	v_rcp_f32_e32 v102, v102
	v_rcp_f32_e32 v103, v103
	v_add_u32_e32 v98, 32, v149
	v_pk_mul_f32 v[94:95], v[94:95], v[100:101]
	v_mad_i64_i32 v[98:99], s[12:13], v98, s7, v[142:143]
	v_pk_mul_f32 v[96:97], v[96:97], v[102:103]
	v_pk_mul_f32 v[90:91], v[94:95], v[90:91]
	v_pk_mul_f32 v[92:93], v[96:97], v[92:93]
	v_mul_f32_e32 v94, 0xbfb8aa3b, v86
	v_mul_f32_e32 v95, 0xbfb8aa3b, v87
	v_mul_f32_e32 v96, 0xbfb8aa3b, v88
	v_mul_f32_e32 v97, 0xbfb8aa3b, v89
	v_exp_f32_e32 v94, v94
	v_exp_f32_e32 v95, v95
	v_exp_f32_e32 v96, v96
	v_exp_f32_e32 v97, v97
	v_add_f32_e32 v94, 1.0, v94
	v_add_f32_e32 v95, 1.0, v95
	v_add_f32_e32 v96, 1.0, v96
	v_add_f32_e32 v97, 1.0, v97
	v_rcp_f32_e32 v94, v94
	v_rcp_f32_e32 v95, v95
	v_rcp_f32_e32 v96, v96
	v_rcp_f32_e32 v97, v97
	v_lshl_add_u64 v[98:99], v[98:99], 0, v[144:145]
	v_pk_mul_f32 v[86:87], v[86:87], v[94:95]
	s_mov_b32 s64, s61
	v_pk_mul_f32 v[88:89], v[88:89], v[96:97]
	s_mov_b64 s[14:15], s[4:5]
	v_pk_mul_f32 v[88:89], v[88:89], v[84:85]
	v_pk_mul_f32 v[84:85], v[86:87], v[82:83]
	v_cvt_pk_bf16_f32 v82, v90, v91
	v_cvt_pk_bf16_f32 v83, v92, v93
	v_mul_f32_e32 v86, 0xbfb8aa3b, v80
	v_cvt_pk_bf16_f32 v84, v84, v85
	v_cvt_pk_bf16_f32 v85, v88, v89
	global_store_dwordx4 v[98:99], v[82:85], off
	v_mul_f32_e32 v87, 0xbfb8aa3b, v81
	v_exp_f32_e32 v86, v86
	v_mul_f32_e32 v84, 0xbfb8aa3b, v78
	v_mul_f32_e32 v85, 0xbfb8aa3b, v79
	v_exp_f32_e32 v84, v84
	v_exp_f32_e32 v85, v85
	v_exp_f32_e32 v87, v87
	v_add_f32_e32 v86, 1.0, v86
	v_add_f32_e32 v84, 1.0, v84
	v_add_f32_e32 v85, 1.0, v85
	v_add_f32_e32 v87, 1.0, v87
	v_rcp_f32_e32 v84, v84
	v_rcp_f32_e32 v85, v85
	v_rcp_f32_e32 v86, v86
	v_rcp_f32_e32 v87, v87
	v_add_u32_e32 v82, 48, v149
	v_pk_mul_f32 v[78:79], v[78:79], v[84:85]
	v_mad_i64_i32 v[82:83], s[12:13], v82, s7, v[142:143]
	v_pk_mul_f32 v[80:81], v[80:81], v[86:87]
	v_pk_mul_f32 v[74:75], v[78:79], v[74:75]
	v_pk_mul_f32 v[76:77], v[80:81], v[76:77]
	v_mul_f32_e32 v78, 0xbfb8aa3b, v70
	v_mul_f32_e32 v79, 0xbfb8aa3b, v71
	v_mul_f32_e32 v80, 0xbfb8aa3b, v72
	v_mul_f32_e32 v81, 0xbfb8aa3b, v73
	v_exp_f32_e32 v78, v78
	v_exp_f32_e32 v79, v79
	v_exp_f32_e32 v80, v80
	v_exp_f32_e32 v81, v81
	v_add_f32_e32 v78, 1.0, v78
	v_add_f32_e32 v79, 1.0, v79
	v_add_f32_e32 v80, 1.0, v80
	v_add_f32_e32 v81, 1.0, v81
	v_rcp_f32_e32 v78, v78
	v_rcp_f32_e32 v79, v79
	v_rcp_f32_e32 v80, v80
	v_rcp_f32_e32 v81, v81
	v_lshl_add_u64 v[82:83], v[82:83], 0, v[144:145]
	v_pk_mul_f32 v[70:71], v[70:71], v[78:79]
	s_mov_b64 s[68:69], 0x1000
	v_pk_mul_f32 v[72:73], v[72:73], v[80:81]
	s_nop 0
	v_pk_mul_f32 v[72:73], v[72:73], v[68:69]
	v_pk_mul_f32 v[68:69], v[70:71], v[66:67]
	v_cvt_pk_bf16_f32 v66, v74, v75
	v_cvt_pk_bf16_f32 v67, v76, v77
	v_mul_f32_e32 v70, 0xbfb8aa3b, v64
	v_cvt_pk_bf16_f32 v68, v68, v69
	v_cvt_pk_bf16_f32 v69, v72, v73
	global_store_dwordx4 v[82:83], v[66:69], off
	v_mul_f32_e32 v71, 0xbfb8aa3b, v65
	v_exp_f32_e32 v70, v70
	v_mul_f32_e32 v68, 0xbfb8aa3b, v62
	v_mul_f32_e32 v69, 0xbfb8aa3b, v63
	v_exp_f32_e32 v68, v68
	v_exp_f32_e32 v69, v69
	v_exp_f32_e32 v71, v71
	v_add_f32_e32 v70, 1.0, v70
	v_add_f32_e32 v68, 1.0, v68
	v_add_f32_e32 v69, 1.0, v69
	v_add_f32_e32 v71, 1.0, v71
	v_rcp_f32_e32 v68, v68
	v_rcp_f32_e32 v69, v69
	v_rcp_f32_e32 v70, v70
	v_rcp_f32_e32 v71, v71
	v_add_u32_e32 v66, 0x80, v149
	v_pk_mul_f32 v[62:63], v[62:63], v[68:69]
	v_mad_i64_i32 v[66:67], s[12:13], v66, s7, v[142:143]
	v_pk_mul_f32 v[64:65], v[64:65], v[70:71]
	v_pk_mul_f32 v[58:59], v[62:63], v[58:59]
	v_pk_mul_f32 v[60:61], v[64:65], v[60:61]
	v_mul_f32_e32 v62, 0xbfb8aa3b, v54
	v_mul_f32_e32 v63, 0xbfb8aa3b, v55
	v_mul_f32_e32 v64, 0xbfb8aa3b, v56
	v_mul_f32_e32 v65, 0xbfb8aa3b, v57
	v_exp_f32_e32 v62, v62
	v_exp_f32_e32 v63, v63
	v_exp_f32_e32 v64, v64
	v_exp_f32_e32 v65, v65
	v_add_f32_e32 v62, 1.0, v62
	v_add_f32_e32 v63, 1.0, v63
	v_add_f32_e32 v64, 1.0, v64
	v_add_f32_e32 v65, 1.0, v65
	v_rcp_f32_e32 v62, v62
; __device__ __forceinline__ unsigned cvt_pk_bf16(float lo, float hi) { unsigned r; asm("v_cvt_pk_bf16_f32 %0, %1, %2" : "=v"(r) : "v"(lo), "v"(hi)); return r; }
; #define PG8_WAIT_V(n) asm volatile("s_waitcnt vmcnt(" #n ")" ::: "memory")
; #define PG8_BAR __builtin_amdgcn_s_barrier()
; template <class Epi>
; __device__ __forceinline__ void gemm_phase(LAS unsigned char* lds, const Gemm g, const Epi& E) {
;     ...
;     PG8_WAIT_V(0);
;     if (wr == 0) PG8_BAR;
;     __device__ __forceinline__ void operator()(const AccT& acc, const Unit& u, int wr, int wc, int fr, int fq) const {
;     ...
;             for (int m = 0; m < 4; ++m) { bf16_t* rowp = U + (size_t)(row0 + ai * 128 + m * 16) * HID + col0;
;                 const f32x4 s0 = silu4(acc[ai][0][m][0]) * acc[ai][1][m][0], s1 = silu4(acc[ai][0][m][1]) * acc[ai][1][m][1];
;                 u32x4 w; w.x = cvt_pk_bf16(s0[0], s0[1]); w.y = cvt_pk_bf16(s0[2], s0[3]); w.z = cvt_pk_bf16(s1[0], s1[1]); w.w = cvt_pk_bf16(s1[2], s1[3]);
;                 *(u32x4*)rowp = w; }
	v_rcp_f32_e32 v63, v63
	v_rcp_f32_e32 v64, v64
	v_rcp_f32_e32 v65, v65
	v_lshl_add_u64 v[66:67], v[66:67], 0, v[144:145]
	v_pk_mul_f32 v[54:55], v[54:55], v[62:63]
	v_pk_mul_f32 v[56:57], v[56:57], v[64:65]
	s_nop 0
	v_pk_mul_f32 v[56:57], v[56:57], v[52:53]
	v_pk_mul_f32 v[52:53], v[54:55], v[50:51]
	v_cvt_pk_bf16_f32 v50, v58, v59
	v_cvt_pk_bf16_f32 v51, v60, v61
	v_mul_f32_e32 v54, 0xbfb8aa3b, v48
	v_cvt_pk_bf16_f32 v52, v52, v53
	v_cvt_pk_bf16_f32 v53, v56, v57
	global_store_dwordx4 v[66:67], v[50:53], off
	v_mul_f32_e32 v55, 0xbfb8aa3b, v49
	v_exp_f32_e32 v54, v54
	v_mul_f32_e32 v52, 0xbfb8aa3b, v46
	v_mul_f32_e32 v53, 0xbfb8aa3b, v47
	v_exp_f32_e32 v52, v52
	v_exp_f32_e32 v53, v53
	v_exp_f32_e32 v55, v55
	v_add_f32_e32 v54, 1.0, v54
	v_add_f32_e32 v52, 1.0, v52
	v_add_f32_e32 v53, 1.0, v53
	v_add_f32_e32 v55, 1.0, v55
	v_rcp_f32_e32 v52, v52
	v_rcp_f32_e32 v53, v53
	v_rcp_f32_e32 v54, v54
	v_rcp_f32_e32 v55, v55
	v_add_u32_e32 v50, 0x90, v149
	v_pk_mul_f32 v[46:47], v[46:47], v[52:53]
	v_mad_i64_i32 v[50:51], s[12:13], v50, s7, v[142:143]
	v_pk_mul_f32 v[48:49], v[48:49], v[54:55]
	v_pk_mul_f32 v[42:43], v[46:47], v[42:43]
	v_pk_mul_f32 v[44:45], v[48:49], v[44:45]
	v_mul_f32_e32 v46, 0xbfb8aa3b, v38
	v_mul_f32_e32 v47, 0xbfb8aa3b, v39
	v_mul_f32_e32 v48, 0xbfb8aa3b, v40
	v_mul_f32_e32 v49, 0xbfb8aa3b, v41
	v_exp_f32_e32 v46, v46
	v_exp_f32_e32 v47, v47
	v_exp_f32_e32 v48, v48
	v_exp_f32_e32 v49, v49
	v_add_f32_e32 v46, 1.0, v46
	v_add_f32_e32 v47, 1.0, v47
	v_add_f32_e32 v48, 1.0, v48
	v_add_f32_e32 v49, 1.0, v49
	v_rcp_f32_e32 v46, v46
	v_rcp_f32_e32 v47, v47
	v_rcp_f32_e32 v48, v48
	v_rcp_f32_e32 v49, v49
	v_lshl_add_u64 v[50:51], v[50:51], 0, v[144:145]
	v_pk_mul_f32 v[38:39], v[38:39], v[46:47]
	v_pk_mul_f32 v[40:41], v[40:41], v[48:49]
	s_nop 0
	v_pk_mul_f32 v[40:41], v[40:41], v[36:37]
	v_pk_mul_f32 v[36:37], v[38:39], v[34:35]
	v_cvt_pk_bf16_f32 v34, v42, v43
	v_cvt_pk_bf16_f32 v35, v44, v45
	v_mul_f32_e32 v38, 0xbfb8aa3b, v32
	v_cvt_pk_bf16_f32 v36, v36, v37
	v_cvt_pk_bf16_f32 v37, v40, v41
	global_store_dwordx4 v[50:51], v[34:37], off
	v_mul_f32_e32 v39, 0xbfb8aa3b, v33
	v_exp_f32_e32 v38, v38
	v_mul_f32_e32 v36, 0xbfb8aa3b, v30
	v_mul_f32_e32 v37, 0xbfb8aa3b, v31
	v_exp_f32_e32 v36, v36
	v_exp_f32_e32 v37, v37
	v_exp_f32_e32 v39, v39
	v_add_f32_e32 v38, 1.0, v38
	v_add_f32_e32 v36, 1.0, v36
	v_add_f32_e32 v37, 1.0, v37
	v_add_f32_e32 v39, 1.0, v39
	v_rcp_f32_e32 v36, v36
	v_rcp_f32_e32 v37, v37
	v_rcp_f32_e32 v38, v38
	v_rcp_f32_e32 v39, v39
	v_add_u32_e32 v34, 0xa0, v149
	v_pk_mul_f32 v[30:31], v[30:31], v[36:37]
	v_mad_i64_i32 v[34:35], s[12:13], v34, s7, v[142:143]
	v_pk_mul_f32 v[32:33], v[32:33], v[38:39]
	v_pk_mul_f32 v[26:27], v[30:31], v[26:27]
	v_pk_mul_f32 v[28:29], v[32:33], v[28:29]
	v_mul_f32_e32 v30, 0xbfb8aa3b, v22
	v_mul_f32_e32 v31, 0xbfb8aa3b, v23
	v_mul_f32_e32 v32, 0xbfb8aa3b, v24
	v_mul_f32_e32 v33, 0xbfb8aa3b, v25
	v_exp_f32_e32 v30, v30
	v_exp_f32_e32 v31, v31
	v_exp_f32_e32 v32, v32
	v_exp_f32_e32 v33, v33
	v_add_f32_e32 v30, 1.0, v30
	v_add_f32_e32 v31, 1.0, v31
	v_add_f32_e32 v32, 1.0, v32
	v_add_f32_e32 v33, 1.0, v33
	v_rcp_f32_e32 v30, v30
	v_rcp_f32_e32 v31, v31
	v_rcp_f32_e32 v32, v32
	v_rcp_f32_e32 v33, v33
	v_lshl_add_u64 v[34:35], v[34:35], 0, v[144:145]
	v_pk_mul_f32 v[22:23], v[22:23], v[30:31]
	v_pk_mul_f32 v[24:25], v[24:25], v[32:33]
	s_nop 0
	v_pk_mul_f32 v[24:25], v[24:25], v[20:21]
	v_pk_mul_f32 v[20:21], v[22:23], v[18:19]
	v_cvt_pk_bf16_f32 v18, v26, v27
	v_cvt_pk_bf16_f32 v19, v28, v29
	v_mul_f32_e32 v22, 0xbfb8aa3b, v16
	v_cvt_pk_bf16_f32 v20, v20, v21
	v_cvt_pk_bf16_f32 v21, v24, v25
	global_store_dwordx4 v[34:35], v[18:21], off
	v_mul_f32_e32 v23, 0xbfb8aa3b, v17
	v_exp_f32_e32 v22, v22
	v_mul_f32_e32 v20, 0xbfb8aa3b, v14
	v_mul_f32_e32 v21, 0xbfb8aa3b, v15
	v_exp_f32_e32 v20, v20
	v_exp_f32_e32 v21, v21
	v_exp_f32_e32 v23, v23
	v_add_f32_e32 v22, 1.0, v22
	v_add_f32_e32 v20, 1.0, v20
	v_add_f32_e32 v21, 1.0, v21
	v_add_f32_e32 v23, 1.0, v23
	v_rcp_f32_e32 v20, v20
	v_rcp_f32_e32 v21, v21
	v_rcp_f32_e32 v22, v22
	v_rcp_f32_e32 v23, v23
	v_add_u32_e32 v18, 0xb0, v149
	v_pk_mul_f32 v[14:15], v[14:15], v[20:21]
	v_mad_i64_i32 v[18:19], s[12:13], v18, s7, v[142:143]
	v_pk_mul_f32 v[16:17], v[16:17], v[22:23]
	v_pk_mul_f32 v[10:11], v[14:15], v[10:11]
	v_pk_mul_f32 v[12:13], v[16:17], v[12:13]
	v_mul_f32_e32 v14, 0xbfb8aa3b, v6
	v_mul_f32_e32 v15, 0xbfb8aa3b, v7
	v_mul_f32_e32 v16, 0xbfb8aa3b, v8
	v_mul_f32_e32 v17, 0xbfb8aa3b, v9
	v_exp_f32_e32 v14, v14
	v_exp_f32_e32 v15, v15
	v_exp_f32_e32 v16, v16
	v_exp_f32_e32 v17, v17
	v_add_f32_e32 v14, 1.0, v14
	v_add_f32_e32 v15, 1.0, v15
	v_add_f32_e32 v16, 1.0, v16
	v_add_f32_e32 v17, 1.0, v17
	v_rcp_f32_e32 v14, v14
	v_rcp_f32_e32 v15, v15
	v_rcp_f32_e32 v16, v16
	v_rcp_f32_e32 v17, v17
	v_lshl_add_u64 v[18:19], v[18:19], 0, v[144:145]
	v_pk_mul_f32 v[6:7], v[6:7], v[14:15]
	s_mov_b64 s[12:13], s[8:9]
	v_pk_mul_f32 v[8:9], v[8:9], v[16:17]
	s_nop 0
	v_pk_mul_f32 v[8:9], v[8:9], v[4:5]
	v_pk_mul_f32 v[4:5], v[6:7], v[2:3]
	v_cvt_pk_bf16_f32 v2, v10, v11
	v_cvt_pk_bf16_f32 v3, v12, v13
	s_nop 0
	v_cvt_pk_bf16_f32 v4, v4, v5
	v_cvt_pk_bf16_f32 v5, v8, v9
	global_store_dwordx4 v[18:19], v[2:5], off
	s_cbranch_vccz .LBB0_520
	s_waitcnt vmcnt(0)
	s_cmpk_gt_u32 s1, 0xff
	s_cbranch_scc1 .LBB0_529
	s_barrier

; #define PG8_STAGE(bufoff, gbase, voff) do { _Pragma("unroll") for (int _i = 0; _i < 2; ++_i) \
;         __builtin_amdgcn_global_load_lds((const unsigned*)((const char*)(gbase) + (voff)[_i]), (LAS unsigned*)(lds + (bufoff) + ldsw + _i * 8192), 16, 0, 0); } while (0)
; #define PG8_LDA(dst, b, h) do { _Pragma("unroll") for (int m = 0; m < 4; ++m) _Pragma("unroll") for (int k = 0; k < 2; ++k) dst[m][k] = *(const LAS bf16x8*)(lds + PG8_SA(b, h) + aoff + m * 2048 + k * 1024); } while (0)
; #define PG8_LDB(dst, b, h) do { _Pragma("unroll") for (int n = 0; n < 2; ++n) _Pragma("unroll") for (int k = 0; k < 2; ++k) dst[n][k] = *(const LAS bf16x8*)(lds + PG8_SB(b, h) + boff + n * 2048 + k * 1024); } while (0)
; #define PG8_MMA(ai, bj, At, Bt) do { __builtin_amdgcn_s_setprio(1); _Pragma("unroll") for (int m = 0; m < 4; ++m) _Pragma("unroll") for (int n = 0; n < 2; ++n) _Pragma("unroll") for (int k = 0; k < 2; ++k) \
;         acc[ai][bj][m][n] = __builtin_amdgcn_mfma_f32_16x16x32_bf16(Bt[n][k], At[m][k], acc[ai][bj][m][n], 0, 0, 0); __builtin_amdgcn_s_setprio(0); } while (0)
; #define PG8_WAIT_L(n) asm volatile("s_waitcnt lgkmcnt(" #n ")" ::: "memory")
; #define PG8_BAR __builtin_amdgcn_s_barrier()
; #define PG8_SCHED __builtin_amdgcn_sched_barrier(0)
; template <class Epi>
; __device__ __forceinline__ void gemm_phase(LAS unsigned char* lds, const Gemm g, const Epi& E) {
;     ...
;             PG8_LDB(B0, 0, 0); PG8_SCHED; PG8_LDA(At, 0, 0); PG8_STAGE(PG8_SA(1, 1), a1 + hstepA, voffA);
;             PG8_WAIT_L(8); PG8_BAR; PG8_WAIT_L(0); PG8_MMA(0, 0, At, B0); PG8_BAR; PG8_SCHED;
;             PG8_LDB(B1, 0, 1); PG8_STAGE(PG8_SB(0, 0), b2, voffB);
;             PG8_BAR; PG8_WAIT_L(0); PG8_MMA(0, 1, At, B1); PG8_BAR;
;             PG8_LDA(At, 0, 1); PG8_STAGE(PG8_SA(0, 0), a2, voffA);
;             PG8_BAR; PG8_WAIT_L(0); PG8_MMA(1, 0, At, B0); PG8_BAR; PG8_SCHED;
.LBB0_547:
	s_add_u32 s10, s8, 0x100
	s_addc_u32 s11, s9, 0
	s_add_i32 s26, 0, 0x10000
	v_add_u32_e32 v142, s26, v157
	ds_read_b128 v[130:133], v142
	ds_read_b128 v[134:137], v142 offset:1024
	ds_read_b128 v[138:141], v142 offset:2048
	ds_read_b128 v[142:145], v142 offset:3072
	s_cmp_eq_u32 s67, 40
	s_cselect_b32 s15, s5, s11
	s_cselect_b32 s14, s4, s10
	s_cselect_b32 s13, s7, s66
	s_cselect_b32 s12, s6, s65
	v_lshl_add_u64 v[154:155], s[8:9], 0, v[150:151]
	s_add_i32 m0, s29, 0xc000
	ds_read_b128 v[160:163], v158
	ds_read_b128 v[164:167], v158 offset:1024
	ds_read_b128 v[168:171], v158 offset:2048
	ds_read_b128 v[172:175], v158 offset:3072
	ds_read_b128 v[180:183], v158 offset:4096
	ds_read_b128 v[184:187], v158 offset:5120
	ds_read_b128 v[188:191], v158 offset:6144
	ds_read_b128 v[192:195], v158 offset:7168
	global_load_lds_dwordx4 v[154:155], off
	v_lshl_add_u64 v[154:155], s[8:9], 0, v[152:153]
	s_add_i32 m0, s29, 0xe000
	s_nop 0
	global_load_lds_dwordx4 v[154:155], off
	s_waitcnt lgkmcnt(8)
	s_barrier
	s_waitcnt lgkmcnt(0)
	v_mfma_f32_16x16x32_bf16 v[126:129], v[130:133], v[160:163], v[126:129]
	v_mfma_f32_16x16x32_bf16 v[122:125], v[138:141], v[160:163], v[122:125]
	v_mfma_f32_16x16x32_bf16 v[118:121], v[130:133], v[168:171], v[118:121]
	v_mfma_f32_16x16x32_bf16 v[110:113], v[138:141], v[168:171], v[110:113]
	v_mfma_f32_16x16x32_bf16 v[102:105], v[130:133], v[180:183], v[102:105]
	v_mfma_f32_16x16x32_bf16 v[94:97], v[138:141], v[180:183], v[94:97]
	v_mfma_f32_16x16x32_bf16 v[86:89], v[130:133], v[188:191], v[86:89]
	v_mfma_f32_16x16x32_bf16 v[78:81], v[138:141], v[188:191], v[78:81]
	v_mfma_f32_16x16x32_bf16 v[126:129], v[134:137], v[164:167], v[126:129]
	v_mfma_f32_16x16x32_bf16 v[122:125], v[142:145], v[164:167], v[122:125]
	v_mfma_f32_16x16x32_bf16 v[118:121], v[134:137], v[172:175], v[118:121]
	v_mfma_f32_16x16x32_bf16 v[110:113], v[142:145], v[172:175], v[110:113]
	v_mfma_f32_16x16x32_bf16 v[102:105], v[134:137], v[184:187], v[102:105]
	v_mfma_f32_16x16x32_bf16 v[94:97], v[142:145], v[184:187], v[94:97]
	v_mfma_f32_16x16x32_bf16 v[86:89], v[134:137], v[192:195], v[86:89]
	v_mfma_f32_16x16x32_bf16 v[78:81], v[142:145], v[192:195], v[78:81]
	s_barrier
	s_add_i32 s27, 0, 0x14000
	v_add_u32_e32 v154, s27, v157
	s_add_i32 s8, s26, s18
	ds_read_b128 v[196:199], v154
	ds_read_b128 v[200:203], v154 offset:1024
	ds_read_b128 v[204:207], v154 offset:2048
	ds_read_b128 v[226:229], v154 offset:3072
	v_lshl_add_u64 v[154:155], s[12:13], 0, v[148:149]
	s_mov_b32 m0, s8
	v_lshl_add_u64 v[176:177], s[12:13], 0, v[146:147]
	global_load_lds_dwordx4 v[154:155], off
	s_add_i32 m0, s8, 0x2000
	s_nop 0
	global_load_lds_dwordx4 v[176:177], off
	s_barrier
	s_waitcnt lgkmcnt(0)
	v_mfma_f32_16x16x32_bf16 v[114:117], v[196:199], v[160:163], v[114:117]
	v_mfma_f32_16x16x32_bf16 v[106:109], v[204:207], v[160:163], v[106:109]
	v_mfma_f32_16x16x32_bf16 v[98:101], v[196:199], v[168:171], v[98:101]
	v_mfma_f32_16x16x32_bf16 v[90:93], v[204:207], v[168:171], v[90:93]
	v_mfma_f32_16x16x32_bf16 v[82:85], v[196:199], v[180:183], v[82:85]
	v_mfma_f32_16x16x32_bf16 v[74:77], v[204:207], v[180:183], v[74:77]
	v_mfma_f32_16x16x32_bf16 v[70:73], v[196:199], v[188:191], v[70:73]
	v_mfma_f32_16x16x32_bf16 v[66:69], v[204:207], v[188:191], v[66:69]
	v_mfma_f32_16x16x32_bf16 v[114:117], v[200:203], v[164:167], v[114:117]
	v_mfma_f32_16x16x32_bf16 v[106:109], v[226:229], v[164:167], v[106:109]
	v_mfma_f32_16x16x32_bf16 v[98:101], v[200:203], v[172:175], v[98:101]
	v_mfma_f32_16x16x32_bf16 v[90:93], v[226:229], v[172:175], v[90:93]
	v_mfma_f32_16x16x32_bf16 v[82:85], v[200:203], v[184:187], v[82:85]
	v_mfma_f32_16x16x32_bf16 v[74:77], v[226:229], v[184:187], v[74:77]
	v_mfma_f32_16x16x32_bf16 v[70:73], v[200:203], v[192:195], v[70:73]
	v_mfma_f32_16x16x32_bf16 v[66:69], v[226:229], v[192:195], v[66:69]
	s_mov_b32 m0, s29
	v_lshl_add_u64 v[208:209], s[14:15], 0, v[148:149]
	s_barrier
	ds_read_b128 v[160:163], v158 offset:16384
	ds_read_b128 v[164:167], v158 offset:17408
	ds_read_b128 v[168:171], v158 offset:18432
	ds_read_b128 v[172:175], v158 offset:19456
	ds_read_b128 v[180:183], v158 offset:20480
	ds_read_b128 v[184:187], v158 offset:21504
	ds_read_b128 v[188:191], v158 offset:22528
	ds_read_b128 v[192:195], v158 offset:23552
	global_load_lds_dwordx4 v[208:209], off
	v_lshl_add_u64 v[230:231], s[14:15], 0, v[146:147]
	s_mov_b32 m0, s30
	s_nop 0
	global_load_lds_dwordx4 v[230:231], off
	s_barrier
	s_waitcnt lgkmcnt(0)
	v_mfma_f32_16x16x32_bf16 v[62:65], v[130:133], v[160:163], v[62:65]
	v_mfma_f32_16x16x32_bf16 v[58:61], v[138:141], v[160:163], v[58:61]
	v_mfma_f32_16x16x32_bf16 v[54:57], v[130:133], v[168:171], v[54:57]
	v_mfma_f32_16x16x32_bf16 v[46:49], v[138:141], v[168:171], v[46:49]
	v_mfma_f32_16x16x32_bf16 v[38:41], v[130:133], v[180:183], v[38:41]
	v_mfma_f32_16x16x32_bf16 v[30:33], v[138:141], v[180:183], v[30:33]
	v_mfma_f32_16x16x32_bf16 v[22:25], v[130:133], v[188:191], v[22:25]
	v_mfma_f32_16x16x32_bf16 v[14:17], v[138:141], v[188:191], v[14:17]
	v_mfma_f32_16x16x32_bf16 v[62:65], v[134:137], v[164:167], v[62:65]
	v_mfma_f32_16x16x32_bf16 v[58:61], v[142:145], v[164:167], v[58:61]
	v_mfma_f32_16x16x32_bf16 v[54:57], v[134:137], v[172:175], v[54:57]
	v_mfma_f32_16x16x32_bf16 v[46:49], v[142:145], v[172:175], v[46:49]
	v_mfma_f32_16x16x32_bf16 v[38:41], v[134:137], v[184:187], v[38:41]
	v_mfma_f32_16x16x32_bf16 v[30:33], v[142:145], v[184:187], v[30:33]
	v_mfma_f32_16x16x32_bf16 v[22:25], v[134:137], v[192:195], v[22:25]
	v_mfma_f32_16x16x32_bf16 v[14:17], v[142:145], v[192:195], v[14:17]
	s_barrier
; #define PG8_STAGE(bufoff, gbase, voff) do { _Pragma("unroll") for (int _i = 0; _i < 2; ++_i) \
;         __builtin_amdgcn_global_load_lds((const unsigned*)((const char*)(gbase) + (voff)[_i]), (LAS unsigned*)(lds + (bufoff) + ldsw + _i * 8192), 16, 0, 0); } while (0)
; #define PG8_LDA(dst, b, h) do { _Pragma("unroll") for (int m = 0; m < 4; ++m) _Pragma("unroll") for (int k = 0; k < 2; ++k) dst[m][k] = *(const LAS bf16x8*)(lds + PG8_SA(b, h) + aoff + m * 2048 + k * 1024); } while (0)
; #define PG8_LDB(dst, b, h) do { _Pragma("unroll") for (int n = 0; n < 2; ++n) _Pragma("unroll") for (int k = 0; k < 2; ++k) dst[n][k] = *(const LAS bf16x8*)(lds + PG8_SB(b, h) + boff + n * 2048 + k * 1024); } while (0)
; #define PG8_MMA(ai, bj, At, Bt) do { __builtin_amdgcn_s_setprio(1); _Pragma("unroll") for (int m = 0; m < 4; ++m) _Pragma("unroll") for (int n = 0; n < 2; ++n) _Pragma("unroll") for (int k = 0; k < 2; ++k) \
;         acc[ai][bj][m][n] = __builtin_amdgcn_mfma_f32_16x16x32_bf16(Bt[n][k], At[m][k], acc[ai][bj][m][n], 0, 0, 0); __builtin_amdgcn_s_setprio(0); } while (0)
; #define PG8_WAIT_V(n) asm volatile("s_waitcnt vmcnt(" #n ")" ::: "memory")
; #define PG8_WAIT_L(n) asm volatile("s_waitcnt lgkmcnt(" #n ")" ::: "memory")
; #define PG8_BAR __builtin_amdgcn_s_barrier()
; #define PG8_SCHED __builtin_amdgcn_sched_barrier(0)
; template <class Epi>
; __device__ __forceinline__ void gemm_phase(LAS unsigned char* lds, const Gemm g, const Epi& E) {
;     ...
;             PG8_STAGE(PG8_SB(0, 1), b2 + hstepB, voffB);
;             PG8_WAIT_V(6); PG8_BAR; PG8_MMA(1, 1, At, B1); PG8_BAR;
;             PG8_LDB(B0, 1, 0); PG8_SCHED; PG8_LDA(At, 1, 0); PG8_STAGE(PG8_SA(0, 1), a2 + hstepA, voffA);
;             PG8_WAIT_L(8); PG8_BAR; PG8_WAIT_L(0); PG8_MMA(0, 0, At, B0); PG8_BAR; PG8_SCHED;
;             PG8_LDB(B1, 1, 1); PG8_STAGE(PG8_SB(1, 0), b3, voffB);
;             PG8_BAR; PG8_WAIT_L(0); PG8_MMA(0, 1, At, B1); PG8_BAR;
;             PG8_LDA(At, 1, 1); PG8_STAGE(PG8_SA(1, 0), a3, voffA);
;             PG8_BAR; PG8_WAIT_L(0); PG8_MMA(1, 0, At, B0); PG8_BAR; PG8_SCHED;
	s_add_u32 s8, s12, 0xb0000
	s_addc_u32 s9, s13, 0
	s_add_i32 s26, s27, s18
	v_lshl_add_u64 v[130:131], s[8:9], 0, v[148:149]
	s_mov_b32 m0, s26
	s_nop 0
	global_load_lds_dwordx4 v[130:131], off
	v_lshl_add_u64 v[130:131], s[8:9], 0, v[146:147]
	s_add_i32 m0, s26, 0x2000
	s_nop 0
	global_load_lds_dwordx4 v[130:131], off
	s_waitcnt vmcnt(6)
	s_barrier
	v_mfma_f32_16x16x32_bf16 v[50:53], v[196:199], v[160:163], v[50:53]
	v_mfma_f32_16x16x32_bf16 v[42:45], v[204:207], v[160:163], v[42:45]
	v_mfma_f32_16x16x32_bf16 v[34:37], v[196:199], v[168:171], v[34:37]
	v_mfma_f32_16x16x32_bf16 v[26:29], v[204:207], v[168:171], v[26:29]
	v_mfma_f32_16x16x32_bf16 v[18:21], v[196:199], v[180:183], v[18:21]
	v_mfma_f32_16x16x32_bf16 v[10:13], v[204:207], v[180:183], v[10:13]
	v_mfma_f32_16x16x32_bf16 v[6:9], v[196:199], v[188:191], v[6:9]
	v_mfma_f32_16x16x32_bf16 v[2:5], v[204:207], v[188:191], v[2:5]
	v_mfma_f32_16x16x32_bf16 v[50:53], v[200:203], v[164:167], v[50:53]
	v_mfma_f32_16x16x32_bf16 v[42:45], v[226:229], v[164:167], v[42:45]
	v_mfma_f32_16x16x32_bf16 v[34:37], v[200:203], v[172:175], v[34:37]
	v_mfma_f32_16x16x32_bf16 v[26:29], v[226:229], v[172:175], v[26:29]
	v_mfma_f32_16x16x32_bf16 v[18:21], v[200:203], v[184:187], v[18:21]
	v_mfma_f32_16x16x32_bf16 v[10:13], v[226:229], v[184:187], v[10:13]
	v_mfma_f32_16x16x32_bf16 v[6:9], v[200:203], v[192:195], v[6:9]
	v_mfma_f32_16x16x32_bf16 v[2:5], v[226:229], v[192:195], v[2:5]
	s_add_i32 s26, 0, 0x18000
	v_add_u32_e32 v142, s26, v157
	s_barrier
	ds_read_b128 v[130:133], v142
	ds_read_b128 v[134:137], v142 offset:1024
	ds_read_b128 v[138:141], v142 offset:2048
	ds_read_b128 v[142:145], v142 offset:3072
	s_add_u32 s8, s14, 0xb0000
	s_addc_u32 s9, s15, 0
	s_mov_b32 m0, s31
	v_lshl_add_u64 v[196:197], s[8:9], 0, v[148:149]
	ds_read_b128 v[160:163], v158 offset:32768
	ds_read_b128 v[164:167], v158 offset:33792
	ds_read_b128 v[168:171], v158 offset:34816
	ds_read_b128 v[172:175], v158 offset:35840
	ds_read_b128 v[180:183], v158 offset:36864
	ds_read_b128 v[184:187], v158 offset:37888
	ds_read_b128 v[188:191], v158 offset:38912
	ds_read_b128 v[192:195], v158 offset:39936
	global_load_lds_dwordx4 v[196:197], off
	v_lshl_add_u64 v[196:197], s[8:9], 0, v[146:147]
	s_mov_b32 m0, s36
	s_nop 0
	global_load_lds_dwordx4 v[196:197], off
	s_waitcnt lgkmcnt(8)
	s_barrier
	s_waitcnt lgkmcnt(0)
	v_mfma_f32_16x16x32_bf16 v[126:129], v[130:133], v[160:163], v[126:129]
	v_mfma_f32_16x16x32_bf16 v[122:125], v[138:141], v[160:163], v[122:125]
	v_mfma_f32_16x16x32_bf16 v[118:121], v[130:133], v[168:171], v[118:121]
	v_mfma_f32_16x16x32_bf16 v[110:113], v[138:141], v[168:171], v[110:113]
	v_mfma_f32_16x16x32_bf16 v[102:105], v[130:133], v[180:183], v[102:105]
	v_mfma_f32_16x16x32_bf16 v[94:97], v[138:141], v[180:183], v[94:97]
	v_mfma_f32_16x16x32_bf16 v[86:89], v[130:133], v[188:191], v[86:89]
	v_mfma_f32_16x16x32_bf16 v[78:81], v[138:141], v[188:191], v[78:81]
	v_mfma_f32_16x16x32_bf16 v[126:129], v[134:137], v[164:167], v[126:129]
	v_mfma_f32_16x16x32_bf16 v[122:125], v[142:145], v[164:167], v[122:125]
	v_mfma_f32_16x16x32_bf16 v[118:121], v[134:137], v[172:175], v[118:121]
	v_mfma_f32_16x16x32_bf16 v[110:113], v[142:145], v[172:175], v[110:113]
	v_mfma_f32_16x16x32_bf16 v[102:105], v[134:137], v[184:187], v[102:105]
	v_mfma_f32_16x16x32_bf16 v[94:97], v[142:145], v[184:187], v[94:97]
	v_mfma_f32_16x16x32_bf16 v[86:89], v[134:137], v[192:195], v[86:89]
	v_mfma_f32_16x16x32_bf16 v[78:81], v[142:145], v[192:195], v[78:81]
	s_barrier
	s_add_i32 s14, 0, 0x1c000
	s_add_i32 s8, s26, s18
	v_add_u32_e32 v159, s14, v157
	v_lshl_add_u64 v[154:155], v[154:155], 0, s[86:87]
	s_mov_b32 m0, s8
	ds_read_b128 v[196:199], v159
	ds_read_b128 v[200:203], v159 offset:1024
	ds_read_b128 v[204:207], v159 offset:2048
	ds_read_b128 v[226:229], v159 offset:3072
	global_load_lds_dwordx4 v[154:155], off
	v_lshl_add_u64 v[154:155], v[176:177], 0, s[86:87]
	s_add_i32 m0, s8, 0x2000
	s_nop 0
	global_load_lds_dwordx4 v[154:155], off
	s_barrier
	s_waitcnt lgkmcnt(0)
	v_mfma_f32_16x16x32_bf16 v[114:117], v[196:199], v[160:163], v[114:117]
	v_mfma_f32_16x16x32_bf16 v[106:109], v[204:207], v[160:163], v[106:109]
	v_mfma_f32_16x16x32_bf16 v[98:101], v[196:199], v[168:171], v[98:101]
	v_mfma_f32_16x16x32_bf16 v[90:93], v[204:207], v[168:171], v[90:93]
	v_mfma_f32_16x16x32_bf16 v[82:85], v[196:199], v[180:183], v[82:85]
	v_mfma_f32_16x16x32_bf16 v[74:77], v[204:207], v[180:183], v[74:77]
	v_mfma_f32_16x16x32_bf16 v[70:73], v[196:199], v[188:191], v[70:73]
	v_mfma_f32_16x16x32_bf16 v[66:69], v[204:207], v[188:191], v[66:69]
	v_mfma_f32_16x16x32_bf16 v[114:117], v[200:203], v[164:167], v[114:117]
	v_mfma_f32_16x16x32_bf16 v[106:109], v[226:229], v[164:167], v[106:109]
	v_mfma_f32_16x16x32_bf16 v[98:101], v[200:203], v[172:175], v[98:101]
	v_mfma_f32_16x16x32_bf16 v[90:93], v[226:229], v[172:175], v[90:93]
	v_mfma_f32_16x16x32_bf16 v[82:85], v[200:203], v[184:187], v[82:85]
	v_mfma_f32_16x16x32_bf16 v[74:77], v[226:229], v[184:187], v[74:77]
	v_mfma_f32_16x16x32_bf16 v[70:73], v[200:203], v[192:195], v[70:73]
	v_mfma_f32_16x16x32_bf16 v[66:69], v[226:229], v[192:195], v[66:69]
	s_mov_b32 m0, s52
	v_lshl_add_u64 v[154:155], v[208:209], 0, s[86:87]
	s_barrier
	ds_read_b128 v[160:163], v158 offset:49152
	ds_read_b128 v[164:167], v158 offset:50176
	ds_read_b128 v[168:171], v158 offset:51200
	ds_read_b128 v[172:175], v158 offset:52224
	ds_read_b128 v[180:183], v158 offset:53248
	ds_read_b128 v[184:187], v158 offset:54272
	ds_read_b128 v[188:191], v158 offset:55296
	ds_read_b128 v[192:195], v158 offset:56320
	global_load_lds_dwordx4 v[154:155], off
	v_lshl_add_u64 v[154:155], v[230:231], 0, s[86:87]
	s_mov_b32 m0, s53
	s_nop 0
	global_load_lds_dwordx4 v[154:155], off
	s_barrier
; #define PG8_STAGE(bufoff, gbase, voff) do { _Pragma("unroll") for (int _i = 0; _i < 2; ++_i) \
;         __builtin_amdgcn_global_load_lds((const unsigned*)((const char*)(gbase) + (voff)[_i]), (LAS unsigned*)(lds + (bufoff) + ldsw + _i * 8192), 16, 0, 0); } while (0)
; #define PG8_MMA(ai, bj, At, Bt) do { __builtin_amdgcn_s_setprio(1); _Pragma("unroll") for (int m = 0; m < 4; ++m) _Pragma("unroll") for (int n = 0; n < 2; ++n) _Pragma("unroll") for (int k = 0; k < 2; ++k) \
;         acc[ai][bj][m][n] = __builtin_amdgcn_mfma_f32_16x16x32_bf16(Bt[n][k], At[m][k], acc[ai][bj][m][n], 0, 0, 0); __builtin_amdgcn_s_setprio(0); } while (0)
; #define PG8_WAIT_V(n) asm volatile("s_waitcnt vmcnt(" #n ")" ::: "memory")
; #define PG8_BAR __builtin_amdgcn_s_barrier()
; template <class Epi>
; __device__ __forceinline__ void gemm_phase(LAS unsigned char* lds, const Gemm g, const Epi& E) {
;     ...
;             PG8_STAGE(PG8_SB(1, 1), b3 + hstepB, voffB);
;             PG8_WAIT_V(6); PG8_BAR; PG8_MMA(1, 1, At, B1); PG8_BAR;
;     __device__ __forceinline__ void operator()(const AccT& acc, const Unit& u, int wr, int wc, int fr, int fq) const {
;     ...
;         const int gpm = mapA.src(u.pm);
;         const int mb = gpm < 32 ? 32 : (gpm - 32) >> 3;
;         const int row0 = gpm * 256 + wr * 64 + fr, col0 = u.pn * 256 + wc * 32 + 4 * fq;
;         const float* gp = modl + ((size_t)mb * 6 + gi) * 1024;
;         f32x4 gv[2][2];
; #pragma unroll
;         for (int bj = 0; bj < 2; ++bj)
; #pragma unroll
;             for (int n = 0; n < 2; ++n) { gv[bj][n] = *(const f32x4*)(gp + col0 + bj * 128 + n * 16); if (scale) gv[bj][n] = gv[bj][n] * *(const f32x4*)(scale + col0 + bj * 128 + n * 16); }
;         const float* sbase = (gpm < 32 ? Xc : Xl) + (size_t)row0 * 1024 + col0;
; #pragma unroll
;         for (int ai = 0; ai < 2; ++ai) {
;             f32x4 xo[4][2][2];
; #pragma unroll
;             for (int m = 0; m < 4; ++m)
; #pragma unroll
;                 for (int bj = 0; bj < 2; ++bj)
; #pragma unroll
;                     for (int n = 0; n < 2; ++n) xo[m][bj][n] = *(const f32x4*)(sbase + (size_t)(ai * 128 + m * 16) * 1024 + bj * 128 + n * 16);
	s_waitcnt lgkmcnt(0)
	v_mfma_f32_16x16x32_bf16 v[62:65], v[130:133], v[160:163], v[62:65]
	v_mfma_f32_16x16x32_bf16 v[58:61], v[138:141], v[160:163], v[58:61]
	v_mfma_f32_16x16x32_bf16 v[54:57], v[130:133], v[168:171], v[54:57]
	v_mfma_f32_16x16x32_bf16 v[46:49], v[138:141], v[168:171], v[46:49]
	v_mfma_f32_16x16x32_bf16 v[38:41], v[130:133], v[180:183], v[38:41]
	v_mfma_f32_16x16x32_bf16 v[30:33], v[138:141], v[180:183], v[30:33]
	v_mfma_f32_16x16x32_bf16 v[22:25], v[130:133], v[188:191], v[22:25]
	v_mfma_f32_16x16x32_bf16 v[14:17], v[138:141], v[188:191], v[14:17]
	v_mfma_f32_16x16x32_bf16 v[62:65], v[134:137], v[164:167], v[62:65]
	v_mfma_f32_16x16x32_bf16 v[58:61], v[142:145], v[164:167], v[58:61]
	v_mfma_f32_16x16x32_bf16 v[54:57], v[134:137], v[172:175], v[54:57]
	v_mfma_f32_16x16x32_bf16 v[46:49], v[142:145], v[172:175], v[46:49]
	v_mfma_f32_16x16x32_bf16 v[38:41], v[134:137], v[184:187], v[38:41]
	v_mfma_f32_16x16x32_bf16 v[30:33], v[142:145], v[184:187], v[30:33]
	v_mfma_f32_16x16x32_bf16 v[22:25], v[134:137], v[192:195], v[22:25]
	v_mfma_f32_16x16x32_bf16 v[14:17], v[142:145], v[192:195], v[14:17]
	s_barrier
	s_add_u32 s8, s12, 0xb0080
	s_addc_u32 s9, s13, 0
	s_add_i32 s12, s14, s18
	v_lshl_add_u64 v[130:131], s[8:9], 0, v[148:149]
	s_mov_b32 m0, s12
	s_nop 0
	global_load_lds_dwordx4 v[130:131], off
	v_lshl_add_u64 v[130:131], s[8:9], 0, v[146:147]
	s_add_i32 m0, s12, 0x2000
	s_nop 0
	global_load_lds_dwordx4 v[130:131], off
	s_waitcnt vmcnt(6)
	s_barrier
	v_mfma_f32_16x16x32_bf16 v[50:53], v[196:199], v[160:163], v[50:53]
	v_mfma_f32_16x16x32_bf16 v[42:45], v[204:207], v[160:163], v[42:45]
	v_mfma_f32_16x16x32_bf16 v[34:37], v[196:199], v[168:171], v[34:37]
	v_mfma_f32_16x16x32_bf16 v[26:29], v[204:207], v[168:171], v[26:29]
	v_mfma_f32_16x16x32_bf16 v[18:21], v[196:199], v[180:183], v[18:21]
	v_mfma_f32_16x16x32_bf16 v[10:13], v[204:207], v[180:183], v[10:13]
	v_mfma_f32_16x16x32_bf16 v[6:9], v[196:199], v[188:191], v[6:9]
	v_mfma_f32_16x16x32_bf16 v[2:5], v[204:207], v[188:191], v[2:5]
	v_mfma_f32_16x16x32_bf16 v[50:53], v[200:203], v[164:167], v[50:53]
	v_mfma_f32_16x16x32_bf16 v[42:45], v[226:229], v[164:167], v[42:45]
	v_mfma_f32_16x16x32_bf16 v[34:37], v[200:203], v[172:175], v[34:37]
	v_mfma_f32_16x16x32_bf16 v[26:29], v[226:229], v[172:175], v[26:29]
	v_mfma_f32_16x16x32_bf16 v[18:21], v[200:203], v[184:187], v[18:21]
	v_mfma_f32_16x16x32_bf16 v[10:13], v[226:229], v[184:187], v[10:13]
	v_mfma_f32_16x16x32_bf16 v[6:9], v[200:203], v[192:195], v[6:9]
	v_mfma_f32_16x16x32_bf16 v[2:5], v[226:229], v[192:195], v[2:5]
	s_add_i32 s67, s67, 2
	s_add_u32 s65, s65, 0x100
	s_addc_u32 s66, s66, 0
	s_cmp_gt_u32 s67, 41
	s_mov_b64 s[8:9], s[10:11]
	s_barrier
	s_cbranch_scc0 .LBB0_547
	v_readlane_b32 s8, v255, 27
	s_cmp_ge_i32 s64, s8
	s_cselect_b32 s8, s25, 0
	s_add_i32 s10, s64, s8
	s_sub_i32 s8, s10, 32
	s_lshl_b32 s9, s61, 8
	s_ashr_i32 s8, s8, 3
	s_or_b32 s9, s9, s50
	v_mov_b32_e32 v130, v1
	v_mov_b32_e32 v159, v156
	s_mul_i32 s8, s8, 6
	s_cmp_gt_i32 s10, 31
	s_cselect_b32 s8, s8, 0xc0
	v_lshl_add_u32 v130, v130, 2, s9
	s_ashr_i32 s9, s8, 31
	s_lshl_b64 s[8:9], s[8:9], 12
	v_readlane_b32 s12, v255, 14
	v_readlane_b32 s13, v255, 15
	s_add_u32 s8, s12, s8
	v_ashrrev_i32_e32 v131, 31, v130
	s_addc_u32 s9, s13, s9
	v_lshlrev_b64 v[154:155], 2, v[130:131]
	v_lshl_add_u64 v[130:131], s[8:9], 0, v[154:155]
	s_mov_b64 s[8:9], 0x5000
	v_lshl_add_u64 v[132:133], v[130:131], 0, s[8:9]
	s_movk_i32 s8, 0x5000
	v_add_co_u32_e32 v130, vcc, s8, v130
	s_lshl_b32 s8, s10, 8
	s_add_i32 s8, s8, s44
	v_add_u32_e32 v160, s8, v159
	v_ashrrev_i32_e32 v161, 31, v160
	v_readlane_b32 s8, v254, 0
	v_lshlrev_b64 v[160:161], 12, v[160:161]
	v_readlane_b32 s9, v254, 1
	v_addc_co_u32_e32 v131, vcc, 0, v131, vcc
	s_nop 0
	v_lshl_add_u64 v[160:161], s[8:9], 0, v[160:161]
	v_lshl_add_u64 v[154:155], v[160:161], 0, v[154:155]
	v_add_co_u32_e32 v176, vcc, s45, v154
	global_load_dwordx4 v[138:141], v[132:133], off offset:64
	global_load_dwordx4 v[134:137], v[132:133], off offset:512
	global_load_dwordx4 v[142:145], v[130:131], off
	s_nop 0
	global_load_dwordx4 v[130:133], v[132:133], off offset:576
	v_addc_co_u32_e32 v177, vcc, 0, v155, vcc
	v_add_co_u32_e32 v208, vcc, s19, v154
	global_load_dwordx4 v[160:163], v[154:155], off
	global_load_dwordx4 v[164:167], v[154:155], off offset:64
	global_load_dwordx4 v[168:171], v[154:155], off offset:512
	global_load_dwordx4 v[172:175], v[154:155], off offset:576
	v_addc_co_u32_e32 v209, vcc, 0, v155, vcc
	v_add_co_u32_e32 v246, vcc, s88, v154
	global_load_dwordx4 v[180:183], v[176:177], off
	global_load_dwordx4 v[184:187], v[176:177], off offset:64
	global_load_dwordx4 v[188:191], v[176:177], off offset:512
	global_load_dwordx4 v[192:195], v[176:177], off offset:576
	v_addc_co_u32_e32 v247, vcc, 0, v155, vcc
	global_load_dwordx4 v[196:199], v[208:209], off
	global_load_dwordx4 v[200:203], v[208:209], off offset:64
	global_load_dwordx4 v[204:207], v[208:209], off offset:512
	global_load_dwordx4 v[226:229], v[208:209], off offset:576
	global_load_dwordx4 v[230:233], v[246:247], off
	global_load_dwordx4 v[234:237], v[246:247], off offset:64
	global_load_dwordx4 v[238:241], v[246:247], off offset:512
	global_load_dwordx4 v[242:245], v[246:247], off offset:576
	s_mov_b64 s[8:9], 0x30000
	v_lshl_add_u64 v[248:249], v[154:155], 0, s[84:85]
	v_lshl_add_u64 v[250:251], v[154:155], 0, s[82:83]
	v_lshl_add_u64 v[252:253], v[154:155], 0, s[8:9]
	s_waitcnt vmcnt(0)
;     __device__ __forceinline__ void operator()(const AccT& acc, const Unit& u, int wr, int wc, int fr, int fq) const {
;     ...
;             for (int m = 0; m < 4; ++m) { float* rowp = X + (size_t)(row0 + ai * 128 + m * 16) * 1024 + col0;
; #pragma unroll
;                 for (int bj = 0; bj < 2; ++bj)
; #pragma unroll
;                     for (int n = 0; n < 2; ++n) *(f32x4*)(rowp + bj * 128 + n * 16) = xo[m][bj][n] + gv[bj][n] * acc[ai][bj][m][n]; }
	v_pk_fma_f32 v[108:109], v[108:109], v[132:133], v[174:175]
	v_pk_fma_f32 v[106:107], v[106:107], v[130:131], v[172:173]
	v_pk_fma_f32 v[92:93], v[92:93], v[132:133], v[194:195]
	v_pk_fma_f32 v[90:91], v[90:91], v[130:131], v[192:193]
	v_pk_fma_f32 v[76:77], v[76:77], v[132:133], v[228:229]
	v_pk_fma_f32 v[74:75], v[74:75], v[130:131], v[226:227]
	global_store_dwordx4 v[154:155], v[106:109], off offset:576
	global_store_dwordx4 v[248:249], v[90:93], off offset:576
	global_store_dwordx4 v[250:251], v[74:77], off offset:576
	v_pk_fma_f32 v[108:109], v[120:121], v[144:145], v[182:183]
	v_pk_fma_f32 v[106:107], v[118:119], v[142:143], v[180:181]
	v_pk_fma_f32 v[92:93], v[104:105], v[144:145], v[198:199]
	v_pk_fma_f32 v[90:91], v[102:103], v[142:143], v[196:197]
	v_pk_fma_f32 v[76:77], v[88:89], v[144:145], v[232:233]
	v_pk_fma_f32 v[74:75], v[86:87], v[142:143], v[230:231]
	v_pk_fma_f32 v[128:129], v[128:129], v[144:145], v[162:163]
	v_pk_fma_f32 v[126:127], v[126:127], v[142:143], v[160:161]
	v_pk_fma_f32 v[124:125], v[124:125], v[140:141], v[166:167]
	v_pk_fma_f32 v[122:123], v[122:123], v[138:139], v[164:165]
	v_pk_fma_f32 v[116:117], v[116:117], v[136:137], v[170:171]
	v_pk_fma_f32 v[114:115], v[114:115], v[134:135], v[168:169]
	global_store_dwordx4 v[176:177], v[106:109], off
	v_pk_fma_f32 v[100:101], v[100:101], v[136:137], v[190:191]
	v_pk_fma_f32 v[98:99], v[98:99], v[134:135], v[188:189]
	v_pk_fma_f32 v[108:109], v[112:113], v[140:141], v[186:187]
	v_pk_fma_f32 v[106:107], v[110:111], v[138:139], v[184:185]
	global_store_dwordx4 v[208:209], v[90:93], off
	v_pk_fma_f32 v[84:85], v[84:85], v[136:137], v[206:207]
	v_pk_fma_f32 v[82:83], v[82:83], v[134:135], v[204:205]
	v_pk_fma_f32 v[92:93], v[96:97], v[140:141], v[202:203]
	v_pk_fma_f32 v[90:91], v[94:95], v[138:139], v[200:201]
	global_store_dwordx4 v[246:247], v[74:77], off
	v_pk_fma_f32 v[72:73], v[72:73], v[136:137], v[240:241]
	v_pk_fma_f32 v[70:71], v[70:71], v[134:135], v[238:239]
	v_pk_fma_f32 v[76:77], v[80:81], v[140:141], v[236:237]
	v_pk_fma_f32 v[74:75], v[78:79], v[138:139], v[234:235]
	v_pk_fma_f32 v[68:69], v[68:69], v[132:133], v[244:245]
	v_pk_fma_f32 v[66:67], v[66:67], v[130:131], v[242:243]
	global_store_dwordx4 v[154:155], v[126:129], off
	global_store_dwordx4 v[154:155], v[122:125], off offset:64
	global_store_dwordx4 v[154:155], v[114:117], off offset:512
	global_store_dwordx4 v[248:249], v[106:109], off offset:64
	global_store_dwordx4 v[248:249], v[98:101], off offset:512
	global_store_dwordx4 v[250:251], v[90:93], off offset:64
	global_store_dwordx4 v[250:251], v[82:85], off offset:512
	global_store_dwordx4 v[252:253], v[74:77], off offset:64
	global_store_dwordx4 v[252:253], v[70:73], off offset:512
	global_store_dwordx4 v[252:253], v[66:69], off offset:576
	s_mov_b64 s[8:9], 0x80000
	v_lshl_add_u64 v[160:161], v[154:155], 0, s[8:9]
	s_mov_b32 s8, 0x80000
	v_add_co_u32_e32 v162, vcc, s8, v154
	s_mov_b64 s[8:9], 0x90000
	s_nop 0
	v_addc_co_u32_e32 v163, vcc, 0, v155, vcc
	v_lshl_add_u64 v[164:165], v[154:155], 0, s[8:9]
	s_mov_b32 s8, 0x90000
	v_add_co_u32_e32 v166, vcc, s8, v154
	s_mov_b64 s[8:9], 0xa0000
	s_nop 0
	v_addc_co_u32_e32 v167, vcc, 0, v155, vcc
	v_lshl_add_u64 v[168:169], v[154:155], 0, s[8:9]
	s_mov_b32 s8, 0xa0000
	v_add_co_u32_e32 v170, vcc, s8, v154
	s_mov_b64 s[8:9], 0xb0000
	s_nop 0
	v_addc_co_u32_e32 v171, vcc, 0, v155, vcc
	v_lshl_add_u64 v[172:173], v[154:155], 0, s[8:9]
	s_mov_b32 s8, 0xb0000
	v_add_co_u32_e32 v154, vcc, s8, v154
	global_load_dwordx4 v[66:69], v[162:163], off
	global_load_dwordx4 v[70:73], v[162:163], off offset:64
	global_load_dwordx4 v[74:77], v[162:163], off offset:512
	global_load_dwordx4 v[78:81], v[162:163], off offset:576
	v_addc_co_u32_e32 v155, vcc, 0, v155, vcc
	global_load_dwordx4 v[82:85], v[166:167], off
	global_load_dwordx4 v[86:89], v[166:167], off offset:64
	global_load_dwordx4 v[90:93], v[166:167], off offset:512
	global_load_dwordx4 v[94:97], v[166:167], off offset:576
	global_load_dwordx4 v[98:101], v[170:171], off
	global_load_dwordx4 v[102:105], v[170:171], off offset:64
	global_load_dwordx4 v[106:109], v[170:171], off offset:512
	global_load_dwordx4 v[110:113], v[170:171], off offset:576
	global_load_dwordx4 v[114:117], v[154:155], off
	global_load_dwordx4 v[118:121], v[154:155], off offset:64
	global_load_dwordx4 v[122:125], v[154:155], off offset:512
	global_load_dwordx4 v[126:129], v[154:155], off offset:576
	s_waitcnt vmcnt(0)
; #define PG8_WAIT_V(n) asm volatile("s_waitcnt vmcnt(" #n ")" ::: "memory")
; #define PG8_BAR __builtin_amdgcn_s_barrier()
; template <class Epi>
; __device__ __forceinline__ void gemm_phase(LAS unsigned char* lds, const Gemm g, const Epi& E) {
;     ...
;         cur = nxt; cA = nA; cB = nB; ++ui;
;     }
;     PG8_WAIT_V(0);
;     if (wr == 0) PG8_BAR;
;     __device__ __forceinline__ void operator()(const AccT& acc, const Unit& u, int wr, int wc, int fr, int fq) const {
;     ...
;             for (int m = 0; m < 4; ++m) { float* rowp = X + (size_t)(row0 + ai * 128 + m * 16) * 1024 + col0;
; #pragma unroll
;                 for (int bj = 0; bj < 2; ++bj)
; #pragma unroll
;                     for (int n = 0; n < 2; ++n) *(f32x4*)(rowp + bj * 128 + n * 16) = xo[m][bj][n] + gv[bj][n] * acc[ai][bj][m][n]; }
	v_pk_fma_f32 v[44:45], v[44:45], v[132:133], v[80:81]
	v_pk_fma_f32 v[42:43], v[42:43], v[130:131], v[78:79]
	v_pk_fma_f32 v[28:29], v[28:29], v[132:133], v[96:97]
	v_pk_fma_f32 v[26:27], v[26:27], v[130:131], v[94:95]
	v_pk_fma_f32 v[12:13], v[12:13], v[132:133], v[112:113]
	v_pk_fma_f32 v[10:11], v[10:11], v[130:131], v[110:111]
	global_store_dwordx4 v[160:161], v[42:45], off offset:576
	global_store_dwordx4 v[164:165], v[26:29], off offset:576
	global_store_dwordx4 v[168:169], v[10:13], off offset:576
	v_pk_fma_f32 v[44:45], v[56:57], v[144:145], v[84:85]
	v_pk_fma_f32 v[42:43], v[54:55], v[142:143], v[82:83]
	v_pk_fma_f32 v[28:29], v[40:41], v[144:145], v[100:101]
	v_pk_fma_f32 v[26:27], v[38:39], v[142:143], v[98:99]
	v_pk_fma_f32 v[12:13], v[24:25], v[144:145], v[116:117]
	v_pk_fma_f32 v[10:11], v[22:23], v[142:143], v[114:115]
	v_pk_fma_f32 v[64:65], v[64:65], v[144:145], v[68:69]
	v_pk_fma_f32 v[62:63], v[62:63], v[142:143], v[66:67]
	v_pk_fma_f32 v[60:61], v[60:61], v[140:141], v[72:73]
	v_pk_fma_f32 v[58:59], v[58:59], v[138:139], v[70:71]
	v_pk_fma_f32 v[52:53], v[52:53], v[136:137], v[76:77]
	v_pk_fma_f32 v[50:51], v[50:51], v[134:135], v[74:75]
	global_store_dwordx4 v[166:167], v[42:45], off
	v_pk_fma_f32 v[36:37], v[36:37], v[136:137], v[92:93]
	v_pk_fma_f32 v[34:35], v[34:35], v[134:135], v[90:91]
	v_pk_fma_f32 v[44:45], v[48:49], v[140:141], v[88:89]
	v_pk_fma_f32 v[42:43], v[46:47], v[138:139], v[86:87]
	global_store_dwordx4 v[170:171], v[26:29], off
	v_pk_fma_f32 v[20:21], v[20:21], v[136:137], v[108:109]
	v_pk_fma_f32 v[18:19], v[18:19], v[134:135], v[106:107]
	v_pk_fma_f32 v[28:29], v[32:33], v[140:141], v[104:105]
	v_pk_fma_f32 v[26:27], v[30:31], v[138:139], v[102:103]
	global_store_dwordx4 v[154:155], v[10:13], off
	v_pk_fma_f32 v[8:9], v[8:9], v[136:137], v[124:125]
	v_pk_fma_f32 v[6:7], v[6:7], v[134:135], v[122:123]
	v_pk_fma_f32 v[12:13], v[16:17], v[140:141], v[120:121]
	v_pk_fma_f32 v[10:11], v[14:15], v[138:139], v[118:119]
	v_pk_fma_f32 v[4:5], v[4:5], v[132:133], v[128:129]
	v_pk_fma_f32 v[2:3], v[2:3], v[130:131], v[126:127]
	global_store_dwordx4 v[162:163], v[62:65], off
	global_store_dwordx4 v[160:161], v[58:61], off offset:64
	global_store_dwordx4 v[160:161], v[50:53], off offset:512
	global_store_dwordx4 v[164:165], v[42:45], off offset:64
	global_store_dwordx4 v[164:165], v[34:37], off offset:512
	global_store_dwordx4 v[168:169], v[26:29], off offset:64
	global_store_dwordx4 v[168:169], v[18:21], off offset:512
	global_store_dwordx4 v[172:173], v[10:13], off offset:64
	global_store_dwordx4 v[172:173], v[6:9], off offset:512
	global_store_dwordx4 v[172:173], v[2:5], off offset:576
	s_and_b64 vcc, exec, s[2:3]
	s_mov_b32 s61, s59
	s_mov_b32 s64, s60
	s_mov_b64 s[10:11], s[6:7]
	s_mov_b64 s[8:9], s[4:5]
	s_cbranch_vccz .LBB0_540
	s_waitcnt vmcnt(0)
	s_cmpk_gt_u32 s1, 0xff
	s_movk_i32 s36, 0xf000
	s_cbranch_scc1 .LBB0_551
	s_barrier
